# v30 + loop-top fragment ds_reads issued before the scalar address block in 9 GEMM K loops
# baseline (speedup 1.0000x reference)
; #define PG8_STAGEA(bufoff, gbase, voff) PG8_STAGE_X(bufoff, gbase, voff, PG8_AUX_A)
; #define PG8_STAGEB(bufoff, gbase, voff) PG8_STAGE_X(bufoff, gbase, voff, PG8_AUX_B)
; #define PG8_LDA(dst, b, h) do { _Pragma("unroll") for (int m = 0; m < 4; ++m) _Pragma("unroll") for (int k = 0; k < 2; ++k) dst[m][k] = *(const PG8_LAS bf16x8*)(lds + PG8_SA(b, h) + aoff + m * 2048 + k * 1024); } while (0)
; #define PG8_LDB(dst, b, h) do { _Pragma("unroll") for (int n = 0; n < 2; ++n) _Pragma("unroll") for (int k = 0; k < 2; ++k) dst[n][k] = *(const PG8_LAS bf16x8*)(lds + PG8_SB(b, h) + boff + n * 2048 + k * 1024); } while (0)
; #define PG8_MMA(ai, bj, At, Bt) do { __builtin_amdgcn_s_setprio(1); _Pragma("unroll") for (int m = 0; m < 4; ++m) _Pragma("unroll") for (int n = 0; n < 2; ++n) _Pragma("unroll") for (int k = 0; k < 2; ++k) \
;         acc[ai][bj][m][n] = __builtin_amdgcn_mfma_f32_16x16x32_bf16(Bt[n][k], At[m][k], acc[ai][bj][m][n], 0, 0, 0); __builtin_amdgcn_s_setprio(0); } while (0)
; template <class Epi, class Sched, bool ALIGN_EPI = false, bool SP2 = false>
; __device__ __forceinline__ void gemm_phase(PG8_LAS unsigned char* lds, const Gemm g, const Sched& S, const Epi& E) {
;     ...
;         for (int t = 0; t < nt; t += 2) {
;             const bool last = (t == nt - 2);
;             if constexpr (HasMid<Epi>::value) { if (t == ns) E.mid(acc, cur, wr, wc, fr, fq); }
;             const char* sA1 = (t + 1 >= ns) ? cA2 : cA; const char* sA2 = (t + 2 >= ns) ? cA2 : cA; const char* sB2 = (t + 2 >= ns) ? cB2 : cB;
;             const char* a1 = sA1 + (size_t)(t + 1) * kstep;
;             const char* a2 = last ? nA : sA2 + (size_t)(t + 2) * kstep; const char* b2 = last ? nB : sB2 + (size_t)(t + 2) * kstep;
;             const char* a3 = a2 + kstep; const char* b3 = b2 + kstep;
;             if (last && has_next) S.a_ready(nxt);
;             if constexpr (SP2) {
;             PG8_LDB(B0, 0, 0); PG8_LDB(B1, 0, 1); PG8_SCHED; PG8_LDA(At, 0, 0); PG8_STAGEA(PG8_SA(1, 1), a1 + hstep, voffA);
;             PG8_WAIT_V(8); PG8_WAIT_L(0); PG8_BAR; PG8_MMA(0, 0, At, B0); PG8_MMA(0, 1, At, B1); PG8_BAR; PG8_SCHED;
;             PG8_LDA(At, 0, 1); PG8_STAGEB(PG8_SB(0, 0), b2, voffB); PG8_STAGEB(PG8_SB(0, 1), b2 + hstep, voffB); PG8_STAGEA(PG8_SA(0, 0), a2, voffA);
;             PG8_WAIT_V(8); PG8_WAIT_L(0); PG8_BAR; PG8_MMA(1, 0, At, B0); PG8_MMA(1, 1, At, B1); PG8_BAR; PG8_SCHED;
.LBB0_94:
	ds_read_b128 v[134:137], v184
	ds_read_b128 v[138:141], v184 offset:1024
	ds_read_b128 v[142:145], v184 offset:2048
	ds_read_b128 v[170:173], v184 offset:3072
	ds_read_b128 v[174:177], v185
	ds_read_b128 v[178:181], v185 offset:1024
	ds_read_b128 v[190:193], v185 offset:2048
	ds_read_b128 v[194:197], v185 offset:3072
	ds_read_b128 v[198:201], v186
	ds_read_b128 v[202:205], v186 offset:1024
	ds_read_b128 v[206:209], v186 offset:2048
	ds_read_b128 v[210:213], v186 offset:3072
	ds_read_b128 v[214:217], v186 offset:4096
	ds_read_b128 v[218:221], v186 offset:5120
	ds_read_b128 v[222:225], v186 offset:6144
	ds_read_b128 v[226:229], v186 offset:7168
	s_add_i32 s71, s73, 2
	s_cmp_gt_u32 s71, 29
	s_cselect_b64 s[34:35], -1, 0
	s_and_b64 vcc, s[34:35], exec
	s_cselect_b32 s83, s60, s78
	s_cselect_b32 s34, s59, s9
	s_cselect_b32 s35, s58, s8
	s_cselect_b32 s82, s61, s79
	s_add_u32 s83, s83, s80
	s_addc_u32 s82, s82, s81
	s_add_u32 s83, s83, 0xfff80080
	s_addc_u32 s82, s82, -1
	s_add_u32 s35, s35, s80
	s_addc_u32 s34, s34, s81
	s_add_u32 s35, s35, 0xfff80080
	s_addc_u32 s34, s34, -1
	s_cmp_eq_u32 s73, 28
	s_cselect_b32 s85, s7, s82
	s_cselect_b32 s84, s26, s83
	s_cselect_b32 s83, s27, s34
	s_cselect_b32 s82, s57, s35
	v_lshl_add_u64 v[230:231], v[130:131], 0, s[80:81]
	s_add_i32 m0, s90, 0xc000
	global_load_lds_dwordx4 v[230:231], off
	v_lshl_add_u64 v[230:231], v[132:133], 0, s[80:81]
	s_add_i32 m0, s90, 0xe000
	s_nop 0
	global_load_lds_dwordx4 v[230:231], off
	s_waitcnt vmcnt(8)
	s_waitcnt lgkmcnt(0)
	s_barrier
	s_setprio 1
	s_waitcnt lgkmcnt(0)
	v_mfma_f32_16x16x32_bf16 v[126:129], v[134:137], v[198:201], v[126:129]
	v_mfma_f32_16x16x32_bf16 v[94:97], v[142:145], v[198:201], v[94:97]
	v_mfma_f32_16x16x32_bf16 v[122:125], v[134:137], v[206:209], v[122:125]
	v_mfma_f32_16x16x32_bf16 v[90:93], v[142:145], v[206:209], v[90:93]
	v_mfma_f32_16x16x32_bf16 v[118:121], v[134:137], v[214:217], v[118:121]
	v_mfma_f32_16x16x32_bf16 v[86:89], v[142:145], v[214:217], v[86:89]
	v_mfma_f32_16x16x32_bf16 v[114:117], v[134:137], v[222:225], v[114:117]
	v_mfma_f32_16x16x32_bf16 v[82:85], v[142:145], v[222:225], v[82:85]
	v_mfma_f32_16x16x32_bf16 v[126:129], v[138:141], v[202:205], v[126:129]
	v_mfma_f32_16x16x32_bf16 v[94:97], v[170:173], v[202:205], v[94:97]
	v_mfma_f32_16x16x32_bf16 v[122:125], v[138:141], v[210:213], v[122:125]
	v_mfma_f32_16x16x32_bf16 v[90:93], v[170:173], v[210:213], v[90:93]
	v_mfma_f32_16x16x32_bf16 v[118:121], v[138:141], v[218:221], v[118:121]
	v_mfma_f32_16x16x32_bf16 v[86:89], v[170:173], v[218:221], v[86:89]
	v_mfma_f32_16x16x32_bf16 v[114:117], v[138:141], v[226:229], v[114:117]
	v_mfma_f32_16x16x32_bf16 v[82:85], v[170:173], v[226:229], v[82:85]
	s_setprio 0
	s_setprio 1
	v_mfma_f32_16x16x32_bf16 v[62:65], v[174:177], v[198:201], v[62:65]
	v_mfma_f32_16x16x32_bf16 v[30:33], v[190:193], v[198:201], v[30:33]
	v_mfma_f32_16x16x32_bf16 v[58:61], v[174:177], v[206:209], v[58:61]
	v_mfma_f32_16x16x32_bf16 v[26:29], v[190:193], v[206:209], v[26:29]
	v_mfma_f32_16x16x32_bf16 v[54:57], v[174:177], v[214:217], v[54:57]
	v_mfma_f32_16x16x32_bf16 v[22:25], v[190:193], v[214:217], v[22:25]
	v_mfma_f32_16x16x32_bf16 v[50:53], v[174:177], v[222:225], v[50:53]
	v_mfma_f32_16x16x32_bf16 v[18:21], v[190:193], v[222:225], v[18:21]
	v_mfma_f32_16x16x32_bf16 v[62:65], v[178:181], v[202:205], v[62:65]
	v_mfma_f32_16x16x32_bf16 v[30:33], v[194:197], v[202:205], v[30:33]
	v_mfma_f32_16x16x32_bf16 v[58:61], v[178:181], v[210:213], v[58:61]
	v_mfma_f32_16x16x32_bf16 v[26:29], v[194:197], v[210:213], v[26:29]
	v_mfma_f32_16x16x32_bf16 v[54:57], v[178:181], v[218:221], v[54:57]
	v_mfma_f32_16x16x32_bf16 v[22:25], v[194:197], v[218:221], v[22:25]
	v_mfma_f32_16x16x32_bf16 v[50:53], v[178:181], v[226:229], v[50:53]
	v_mfma_f32_16x16x32_bf16 v[18:21], v[194:197], v[226:229], v[18:21]
	s_setprio 0
	s_barrier
	s_add_i32 s34, s97, s87
	v_lshl_add_u64 v[230:231], s[82:83], 0, v[148:149]
	s_mov_b32 m0, s34
	ds_read_b128 v[198:201], v186 offset:16384
	ds_read_b128 v[202:205], v186 offset:17408
	ds_read_b128 v[206:209], v186 offset:18432
	ds_read_b128 v[210:213], v186 offset:19456
	ds_read_b128 v[214:217], v186 offset:20480
	ds_read_b128 v[218:221], v186 offset:21504
	ds_read_b128 v[222:225], v186 offset:22528
	ds_read_b128 v[226:229], v186 offset:23552
	global_load_lds_dwordx4 v[230:231], off
	s_add_i32 m0, s34, 0x2000
	s_add_u32 s34, s82, 0x80000
	v_lshl_add_u64 v[232:233], s[82:83], 0, v[152:153]
	s_addc_u32 s35, s83, 0
	s_add_i32 s73, s11, s87
	global_load_lds_dwordx4 v[232:233], off
	v_lshl_add_u64 v[234:235], s[34:35], 0, v[148:149]
	s_mov_b32 m0, s73
	v_lshl_add_u64 v[236:237], s[84:85], 0, v[150:151]
	global_load_lds_dwordx4 v[234:235], off
	v_lshl_add_u64 v[234:235], s[34:35], 0, v[152:153]
	s_add_i32 m0, s73, 0x2000
	s_nop 0
	global_load_lds_dwordx4 v[234:235], off
	v_lshl_add_u64 v[234:235], s[84:85], 0, v[146:147]
	s_mov_b32 m0, s90
	s_nop 0
	global_load_lds_dwordx4 v[234:235], off
	s_mov_b32 m0, s91
	s_nop 0
	global_load_lds_dwordx4 v[236:237], off
	s_waitcnt vmcnt(8)
	s_waitcnt lgkmcnt(0)
	s_barrier
; #define PG8_STAGEA(bufoff, gbase, voff) PG8_STAGE_X(bufoff, gbase, voff, PG8_AUX_A)
; #define PG8_STAGEB(bufoff, gbase, voff) PG8_STAGE_X(bufoff, gbase, voff, PG8_AUX_B)
; #define PG8_LDA(dst, b, h) do { _Pragma("unroll") for (int m = 0; m < 4; ++m) _Pragma("unroll") for (int k = 0; k < 2; ++k) dst[m][k] = *(const PG8_LAS bf16x8*)(lds + PG8_SA(b, h) + aoff + m * 2048 + k * 1024); } while (0)
; #define PG8_LDB(dst, b, h) do { _Pragma("unroll") for (int n = 0; n < 2; ++n) _Pragma("unroll") for (int k = 0; k < 2; ++k) dst[n][k] = *(const PG8_LAS bf16x8*)(lds + PG8_SB(b, h) + boff + n * 2048 + k * 1024); } while (0)
; #define PG8_MMA(ai, bj, At, Bt) do { __builtin_amdgcn_s_setprio(1); _Pragma("unroll") for (int m = 0; m < 4; ++m) _Pragma("unroll") for (int n = 0; n < 2; ++n) _Pragma("unroll") for (int k = 0; k < 2; ++k) \
;         acc[ai][bj][m][n] = __builtin_amdgcn_mfma_f32_16x16x32_bf16(Bt[n][k], At[m][k], acc[ai][bj][m][n], 0, 0, 0); __builtin_amdgcn_s_setprio(0); } while (0)
; #define PG8_WAIT_V(n) asm volatile("s_waitcnt vmcnt(" #n ")" ::: "memory")
; #define PG8_WAIT_L(n) asm volatile("s_waitcnt lgkmcnt(" #n ")" ::: "memory")
; #define PG8_BAR __builtin_amdgcn_s_barrier()
; #define PG8_SCHED __builtin_amdgcn_sched_barrier(0)
; template <class Epi, class Sched, bool ALIGN_EPI = false, bool SP2 = false>
; __device__ __forceinline__ void gemm_phase(PG8_LAS unsigned char* lds, const Gemm g, const Sched& S, const Epi& E) {
;     ...
;             PG8_WAIT_V(8); PG8_WAIT_L(0); PG8_BAR; PG8_MMA(0, 0, At, B0); PG8_MMA(0, 1, At, B1); PG8_BAR; PG8_SCHED;
;             PG8_LDA(At, 0, 1); PG8_STAGEB(PG8_SB(0, 0), b2, voffB); PG8_STAGEB(PG8_SB(0, 1), b2 + hstep, voffB); PG8_STAGEA(PG8_SA(0, 0), a2, voffA);
;             PG8_WAIT_V(8); PG8_WAIT_L(0); PG8_BAR; PG8_MMA(1, 0, At, B0); PG8_MMA(1, 1, At, B1); PG8_BAR; PG8_SCHED;
;             PG8_LDB(B0, 1, 0); PG8_LDB(B1, 1, 1); PG8_SCHED; PG8_LDA(At, 1, 0); PG8_STAGEA(PG8_SA(0, 1), a2 + hstep, voffA);
;             PG8_WAIT_V(8); PG8_WAIT_L(0); PG8_BAR; PG8_MMA(0, 0, At, B0); PG8_MMA(0, 1, At, B1); PG8_BAR; PG8_SCHED;
	s_setprio 1
	s_waitcnt lgkmcnt(0)
	v_mfma_f32_16x16x32_bf16 v[110:113], v[134:137], v[198:201], v[110:113]
	v_mfma_f32_16x16x32_bf16 v[78:81], v[142:145], v[198:201], v[78:81]
	v_mfma_f32_16x16x32_bf16 v[106:109], v[134:137], v[206:209], v[106:109]
	v_mfma_f32_16x16x32_bf16 v[74:77], v[142:145], v[206:209], v[74:77]
	v_mfma_f32_16x16x32_bf16 v[102:105], v[134:137], v[214:217], v[102:105]
	v_mfma_f32_16x16x32_bf16 v[70:73], v[142:145], v[214:217], v[70:73]
	v_mfma_f32_16x16x32_bf16 v[98:101], v[134:137], v[222:225], v[98:101]
	v_mfma_f32_16x16x32_bf16 v[66:69], v[142:145], v[222:225], v[66:69]
	v_mfma_f32_16x16x32_bf16 v[110:113], v[138:141], v[202:205], v[110:113]
	v_mfma_f32_16x16x32_bf16 v[78:81], v[170:173], v[202:205], v[78:81]
	v_mfma_f32_16x16x32_bf16 v[106:109], v[138:141], v[210:213], v[106:109]
	v_mfma_f32_16x16x32_bf16 v[74:77], v[170:173], v[210:213], v[74:77]
	v_mfma_f32_16x16x32_bf16 v[102:105], v[138:141], v[218:221], v[102:105]
	v_mfma_f32_16x16x32_bf16 v[70:73], v[170:173], v[218:221], v[70:73]
	v_mfma_f32_16x16x32_bf16 v[98:101], v[138:141], v[226:229], v[98:101]
	v_mfma_f32_16x16x32_bf16 v[66:69], v[170:173], v[226:229], v[66:69]
	s_setprio 0
	s_setprio 1
	v_mfma_f32_16x16x32_bf16 v[46:49], v[174:177], v[198:201], v[46:49]
	v_mfma_f32_16x16x32_bf16 v[14:17], v[190:193], v[198:201], v[14:17]
	v_mfma_f32_16x16x32_bf16 v[42:45], v[174:177], v[206:209], v[42:45]
	v_mfma_f32_16x16x32_bf16 v[10:13], v[190:193], v[206:209], v[10:13]
	v_mfma_f32_16x16x32_bf16 v[38:41], v[174:177], v[214:217], v[38:41]
	v_mfma_f32_16x16x32_bf16 v[6:9], v[190:193], v[214:217], v[6:9]
	v_mfma_f32_16x16x32_bf16 v[34:37], v[174:177], v[222:225], v[34:37]
	v_mfma_f32_16x16x32_bf16 v[2:5], v[190:193], v[222:225], v[2:5]
	v_mfma_f32_16x16x32_bf16 v[46:49], v[178:181], v[202:205], v[46:49]
	v_mfma_f32_16x16x32_bf16 v[14:17], v[194:197], v[202:205], v[14:17]
	v_mfma_f32_16x16x32_bf16 v[42:45], v[178:181], v[210:213], v[42:45]
	v_mfma_f32_16x16x32_bf16 v[10:13], v[194:197], v[210:213], v[10:13]
	v_mfma_f32_16x16x32_bf16 v[38:41], v[178:181], v[218:221], v[38:41]
	v_mfma_f32_16x16x32_bf16 v[6:9], v[194:197], v[218:221], v[6:9]
	v_mfma_f32_16x16x32_bf16 v[34:37], v[178:181], v[226:229], v[34:37]
	v_mfma_f32_16x16x32_bf16 v[2:5], v[194:197], v[226:229], v[2:5]
	s_setprio 0
	s_barrier
	s_add_i32 s73, 0, 0x18000
	v_add_u32_e32 v154, s73, v182
	s_add_i32 s54, 0, 0x1c000
	ds_read_b128 v[134:137], v154
	ds_read_b128 v[138:141], v154 offset:1024
	ds_read_b128 v[142:145], v154 offset:2048
	ds_read_b128 v[170:173], v154 offset:3072
	v_add_u32_e32 v154, s54, v182
	ds_read_b128 v[174:177], v154
	ds_read_b128 v[178:181], v154 offset:1024
	ds_read_b128 v[190:193], v154 offset:2048
	ds_read_b128 v[194:197], v154 offset:3072
	s_add_u32 s34, s84, 0x80000
	s_addc_u32 s35, s85, 0
	s_mov_b32 m0, s92
	v_lshl_add_u64 v[238:239], s[34:35], 0, v[146:147]
	ds_read_b128 v[198:201], v186 offset:32768
	ds_read_b128 v[202:205], v186 offset:33792
	ds_read_b128 v[206:209], v186 offset:34816
	ds_read_b128 v[210:213], v186 offset:35840
	ds_read_b128 v[214:217], v186 offset:36864
	ds_read_b128 v[218:221], v186 offset:37888
	ds_read_b128 v[222:225], v186 offset:38912
	ds_read_b128 v[226:229], v186 offset:39936
	global_load_lds_dwordx4 v[238:239], off
	v_lshl_add_u64 v[238:239], s[34:35], 0, v[150:151]
	s_mov_b32 m0, s93
	s_nop 0
	global_load_lds_dwordx4 v[238:239], off
	s_waitcnt vmcnt(8)
	s_waitcnt lgkmcnt(0)
	s_barrier
	s_setprio 1
	s_waitcnt lgkmcnt(0)
	v_mfma_f32_16x16x32_bf16 v[126:129], v[134:137], v[198:201], v[126:129]
	v_mfma_f32_16x16x32_bf16 v[94:97], v[142:145], v[198:201], v[94:97]
	v_mfma_f32_16x16x32_bf16 v[122:125], v[134:137], v[206:209], v[122:125]
	v_mfma_f32_16x16x32_bf16 v[90:93], v[142:145], v[206:209], v[90:93]
	v_mfma_f32_16x16x32_bf16 v[118:121], v[134:137], v[214:217], v[118:121]
	v_mfma_f32_16x16x32_bf16 v[86:89], v[142:145], v[214:217], v[86:89]
	v_mfma_f32_16x16x32_bf16 v[114:117], v[134:137], v[222:225], v[114:117]
	v_mfma_f32_16x16x32_bf16 v[82:85], v[142:145], v[222:225], v[82:85]
	v_mfma_f32_16x16x32_bf16 v[126:129], v[138:141], v[202:205], v[126:129]
	v_mfma_f32_16x16x32_bf16 v[94:97], v[170:173], v[202:205], v[94:97]
	v_mfma_f32_16x16x32_bf16 v[122:125], v[138:141], v[210:213], v[122:125]
	v_mfma_f32_16x16x32_bf16 v[90:93], v[170:173], v[210:213], v[90:93]
	v_mfma_f32_16x16x32_bf16 v[118:121], v[138:141], v[218:221], v[118:121]
	v_mfma_f32_16x16x32_bf16 v[86:89], v[170:173], v[218:221], v[86:89]
	v_mfma_f32_16x16x32_bf16 v[114:117], v[138:141], v[226:229], v[114:117]
	v_mfma_f32_16x16x32_bf16 v[82:85], v[170:173], v[226:229], v[82:85]
	s_setprio 0
	s_setprio 1
	v_mfma_f32_16x16x32_bf16 v[62:65], v[174:177], v[198:201], v[62:65]
	v_mfma_f32_16x16x32_bf16 v[30:33], v[190:193], v[198:201], v[30:33]
	v_mfma_f32_16x16x32_bf16 v[58:61], v[174:177], v[206:209], v[58:61]
	v_mfma_f32_16x16x32_bf16 v[26:29], v[190:193], v[206:209], v[26:29]
	v_mfma_f32_16x16x32_bf16 v[54:57], v[174:177], v[214:217], v[54:57]
	v_mfma_f32_16x16x32_bf16 v[22:25], v[190:193], v[214:217], v[22:25]
	v_mfma_f32_16x16x32_bf16 v[50:53], v[174:177], v[222:225], v[50:53]
	v_mfma_f32_16x16x32_bf16 v[18:21], v[190:193], v[222:225], v[18:21]
	v_mfma_f32_16x16x32_bf16 v[62:65], v[178:181], v[202:205], v[62:65]
	v_mfma_f32_16x16x32_bf16 v[30:33], v[194:197], v[202:205], v[30:33]
	v_mfma_f32_16x16x32_bf16 v[58:61], v[178:181], v[210:213], v[58:61]
	v_mfma_f32_16x16x32_bf16 v[26:29], v[194:197], v[210:213], v[26:29]
	v_mfma_f32_16x16x32_bf16 v[54:57], v[178:181], v[218:221], v[54:57]
	v_mfma_f32_16x16x32_bf16 v[22:25], v[194:197], v[218:221], v[22:25]
	v_mfma_f32_16x16x32_bf16 v[50:53], v[178:181], v[226:229], v[50:53]
	v_mfma_f32_16x16x32_bf16 v[18:21], v[194:197], v[226:229], v[18:21]
	s_setprio 0
	s_barrier
; #define PG8_STAGEA(bufoff, gbase, voff) PG8_STAGE_X(bufoff, gbase, voff, PG8_AUX_A)
; #define PG8_STAGEB(bufoff, gbase, voff) PG8_STAGE_X(bufoff, gbase, voff, PG8_AUX_B)
; #define PG8_LDA(dst, b, h) do { _Pragma("unroll") for (int m = 0; m < 4; ++m) _Pragma("unroll") for (int k = 0; k < 2; ++k) dst[m][k] = *(const PG8_LAS bf16x8*)(lds + PG8_SA(b, h) + aoff + m * 2048 + k * 1024); } while (0)
; #define PG8_MMA(ai, bj, At, Bt) do { __builtin_amdgcn_s_setprio(1); _Pragma("unroll") for (int m = 0; m < 4; ++m) _Pragma("unroll") for (int n = 0; n < 2; ++n) _Pragma("unroll") for (int k = 0; k < 2; ++k) \
;         acc[ai][bj][m][n] = __builtin_amdgcn_mfma_f32_16x16x32_bf16(Bt[n][k], At[m][k], acc[ai][bj][m][n], 0, 0, 0); __builtin_amdgcn_s_setprio(0); } while (0)
; #define PG8_WAIT_V(n) asm volatile("s_waitcnt vmcnt(" #n ")" ::: "memory")
; #define PG8_WAIT_L(n) asm volatile("s_waitcnt lgkmcnt(" #n ")" ::: "memory")
; #define PG8_BAR __builtin_amdgcn_s_barrier()
; #define PG8_SCHED __builtin_amdgcn_sched_barrier(0)
; template <class Epi, class Sched, bool ALIGN_EPI = false, bool SP2 = false>
; __device__ __forceinline__ void gemm_phase(PG8_LAS unsigned char* lds, const Gemm g, const Sched& S, const Epi& E) {
;     ...
;             PG8_WAIT_V(8); PG8_WAIT_L(0); PG8_BAR; PG8_MMA(0, 0, At, B0); PG8_MMA(0, 1, At, B1); PG8_BAR; PG8_SCHED;
;             PG8_LDA(At, 1, 1); PG8_STAGEB(PG8_SB(1, 0), b3, voffB); PG8_STAGEB(PG8_SB(1, 1), b3 + hstep, voffB); PG8_STAGEA(PG8_SA(1, 0), a3, voffA);
;             PG8_WAIT_V(8); PG8_WAIT_L(0); PG8_BAR; PG8_MMA(1, 0, At, B0); PG8_MMA(1, 1, At, B1); PG8_BAR; PG8_SCHED;
	s_add_i32 s34, s73, s87
	v_lshl_add_u64 v[230:231], v[230:231], 0, s[64:65]
	s_mov_b32 m0, s34
	ds_read_b128 v[198:201], v186 offset:49152
	ds_read_b128 v[202:205], v186 offset:50176
	ds_read_b128 v[206:209], v186 offset:51200
	ds_read_b128 v[210:213], v186 offset:52224
	ds_read_b128 v[214:217], v186 offset:53248
	ds_read_b128 v[218:221], v186 offset:54272
	ds_read_b128 v[222:225], v186 offset:55296
	ds_read_b128 v[226:229], v186 offset:56320
	global_load_lds_dwordx4 v[230:231], off
	s_add_i32 m0, s34, 0x2000
	s_add_u32 s34, s82, 0x80080
	v_lshl_add_u64 v[230:231], v[232:233], 0, s[64:65]
	s_addc_u32 s35, s83, 0
	s_add_i32 s54, s54, s87
	global_load_lds_dwordx4 v[230:231], off
	v_lshl_add_u64 v[230:231], s[34:35], 0, v[148:149]
	s_mov_b32 m0, s54
	s_nop 0
	global_load_lds_dwordx4 v[230:231], off
	v_lshl_add_u64 v[230:231], s[34:35], 0, v[152:153]
	s_add_i32 m0, s54, 0x2000
	s_nop 0
	global_load_lds_dwordx4 v[230:231], off
	v_lshl_add_u64 v[230:231], v[234:235], 0, s[64:65]
	s_mov_b32 m0, s95
	s_nop 0
	global_load_lds_dwordx4 v[230:231], off
	v_lshl_add_u64 v[230:231], v[236:237], 0, s[64:65]
	s_mov_b32 m0, s96
	s_nop 0
	global_load_lds_dwordx4 v[230:231], off
	s_waitcnt vmcnt(8)
	s_waitcnt lgkmcnt(0)
	s_barrier
	s_setprio 1
	s_waitcnt lgkmcnt(0)
	v_mfma_f32_16x16x32_bf16 v[110:113], v[134:137], v[198:201], v[110:113]
	v_mfma_f32_16x16x32_bf16 v[78:81], v[142:145], v[198:201], v[78:81]
	v_mfma_f32_16x16x32_bf16 v[106:109], v[134:137], v[206:209], v[106:109]
	v_mfma_f32_16x16x32_bf16 v[74:77], v[142:145], v[206:209], v[74:77]
	v_mfma_f32_16x16x32_bf16 v[102:105], v[134:137], v[214:217], v[102:105]
	v_mfma_f32_16x16x32_bf16 v[70:73], v[142:145], v[214:217], v[70:73]
	v_mfma_f32_16x16x32_bf16 v[98:101], v[134:137], v[222:225], v[98:101]
	v_mfma_f32_16x16x32_bf16 v[66:69], v[142:145], v[222:225], v[66:69]
	v_mfma_f32_16x16x32_bf16 v[110:113], v[138:141], v[202:205], v[110:113]
	v_mfma_f32_16x16x32_bf16 v[78:81], v[170:173], v[202:205], v[78:81]
	v_mfma_f32_16x16x32_bf16 v[106:109], v[138:141], v[210:213], v[106:109]
	v_mfma_f32_16x16x32_bf16 v[74:77], v[170:173], v[210:213], v[74:77]
	v_mfma_f32_16x16x32_bf16 v[102:105], v[138:141], v[218:221], v[102:105]
	v_mfma_f32_16x16x32_bf16 v[70:73], v[170:173], v[218:221], v[70:73]
	v_mfma_f32_16x16x32_bf16 v[98:101], v[138:141], v[226:229], v[98:101]
	v_mfma_f32_16x16x32_bf16 v[66:69], v[170:173], v[226:229], v[66:69]
	s_setprio 0
	s_setprio 1
	v_mfma_f32_16x16x32_bf16 v[46:49], v[174:177], v[198:201], v[46:49]
	v_mfma_f32_16x16x32_bf16 v[14:17], v[190:193], v[198:201], v[14:17]
	v_mfma_f32_16x16x32_bf16 v[42:45], v[174:177], v[206:209], v[42:45]
	v_mfma_f32_16x16x32_bf16 v[10:13], v[190:193], v[206:209], v[10:13]
	v_mfma_f32_16x16x32_bf16 v[38:41], v[174:177], v[214:217], v[38:41]
	v_mfma_f32_16x16x32_bf16 v[6:9], v[190:193], v[214:217], v[6:9]
	v_mfma_f32_16x16x32_bf16 v[34:37], v[174:177], v[222:225], v[34:37]
	v_mfma_f32_16x16x32_bf16 v[2:5], v[190:193], v[222:225], v[2:5]
	v_mfma_f32_16x16x32_bf16 v[46:49], v[178:181], v[202:205], v[46:49]
	v_mfma_f32_16x16x32_bf16 v[14:17], v[194:197], v[202:205], v[14:17]
	v_mfma_f32_16x16x32_bf16 v[42:45], v[178:181], v[210:213], v[42:45]
	v_mfma_f32_16x16x32_bf16 v[10:13], v[194:197], v[210:213], v[10:13]
	v_mfma_f32_16x16x32_bf16 v[38:41], v[178:181], v[218:221], v[38:41]
	v_mfma_f32_16x16x32_bf16 v[6:9], v[194:197], v[218:221], v[6:9]
	v_mfma_f32_16x16x32_bf16 v[34:37], v[178:181], v[226:229], v[34:37]
	v_mfma_f32_16x16x32_bf16 v[2:5], v[194:197], v[226:229], v[2:5]
	s_setprio 0
	s_barrier
	s_add_u32 s80, s80, 0x100
	s_addc_u32 s81, s81, 0
	s_mov_b32 s73, s71
	s_cbranch_vccz .LBB0_94
	s_and_b64 vcc, exec, s[66:67]
	s_cbranch_vccz .LBB0_97
	s_barrier

; #define PG8_STAGEA(bufoff, gbase, voff) PG8_STAGE_X(bufoff, gbase, voff, PG8_AUX_A)
; #define PG8_STAGEB(bufoff, gbase, voff) PG8_STAGE_X(bufoff, gbase, voff, PG8_AUX_B)
; #define PG8_LDA(dst, b, h) do { _Pragma("unroll") for (int m = 0; m < 4; ++m) _Pragma("unroll") for (int k = 0; k < 2; ++k) dst[m][k] = *(const PG8_LAS bf16x8*)(lds + PG8_SA(b, h) + aoff + m * 2048 + k * 1024); } while (0)
; #define PG8_LDB(dst, b, h) do { _Pragma("unroll") for (int n = 0; n < 2; ++n) _Pragma("unroll") for (int k = 0; k < 2; ++k) dst[n][k] = *(const PG8_LAS bf16x8*)(lds + PG8_SB(b, h) + boff + n * 2048 + k * 1024); } while (0)
; #define PG8_MMA(ai, bj, At, Bt) do { __builtin_amdgcn_s_setprio(1); _Pragma("unroll") for (int m = 0; m < 4; ++m) _Pragma("unroll") for (int n = 0; n < 2; ++n) _Pragma("unroll") for (int k = 0; k < 2; ++k) \
;         acc[ai][bj][m][n] = __builtin_amdgcn_mfma_f32_16x16x32_bf16(Bt[n][k], At[m][k], acc[ai][bj][m][n], 0, 0, 0); __builtin_amdgcn_s_setprio(0); } while (0)
; template <class Epi, class Sched, bool ALIGN_EPI = false, bool SP2 = false>
; __device__ __forceinline__ void gemm_phase(PG8_LAS unsigned char* lds, const Gemm g, const Sched& S, const Epi& E) {
;     ...
;         for (int t = 0; t < nt; t += 2) {
;             const bool last = (t == nt - 2);
;             if constexpr (HasMid<Epi>::value) { if (t == ns) E.mid(acc, cur, wr, wc, fr, fq); }
;             const char* sA1 = (t + 1 >= ns) ? cA2 : cA; const char* sA2 = (t + 2 >= ns) ? cA2 : cA; const char* sB2 = (t + 2 >= ns) ? cB2 : cB;
;             const char* a1 = sA1 + (size_t)(t + 1) * kstep;
;             const char* a2 = last ? nA : sA2 + (size_t)(t + 2) * kstep; const char* b2 = last ? nB : sB2 + (size_t)(t + 2) * kstep;
;             const char* a3 = a2 + kstep; const char* b3 = b2 + kstep;
;             if (last && has_next) S.a_ready(nxt);
;             if constexpr (SP2) {
;             PG8_LDB(B0, 0, 0); PG8_LDB(B1, 0, 1); PG8_SCHED; PG8_LDA(At, 0, 0); PG8_STAGEA(PG8_SA(1, 1), a1 + hstep, voffA);
;             PG8_WAIT_V(8); PG8_WAIT_L(0); PG8_BAR; PG8_MMA(0, 0, At, B0); PG8_MMA(0, 1, At, B1); PG8_BAR; PG8_SCHED;
;             PG8_LDA(At, 0, 1); PG8_STAGEB(PG8_SB(0, 0), b2, voffB); PG8_STAGEB(PG8_SB(0, 1), b2 + hstep, voffB); PG8_STAGEA(PG8_SA(0, 0), a2, voffA);
;             PG8_WAIT_V(8); PG8_WAIT_L(0); PG8_BAR; PG8_MMA(1, 0, At, B0); PG8_MMA(1, 1, At, B1); PG8_BAR; PG8_SCHED;
.LBB0_295:
	ds_read_b128 v[156:159], v152
	ds_read_b128 v[160:163], v152 offset:1024
	ds_read_b128 v[164:167], v152 offset:2048
	ds_read_b128 v[168:171], v152 offset:3072
	ds_read_b128 v[172:175], v153
	ds_read_b128 v[176:179], v153 offset:1024
	ds_read_b128 v[180:183], v153 offset:2048
	ds_read_b128 v[184:187], v153 offset:3072
	ds_read_b128 v[188:191], v154
	ds_read_b128 v[192:195], v154 offset:1024
	ds_read_b128 v[196:199], v154 offset:2048
	ds_read_b128 v[200:203], v154 offset:3072
	ds_read_b128 v[204:207], v154 offset:4096
	ds_read_b128 v[208:211], v154 offset:5120
	ds_read_b128 v[212:215], v154 offset:6144
	ds_read_b128 v[216:219], v154 offset:7168
	s_add_i32 s92, s74, 2
	s_cmp_gt_u32 s92, 29
	s_cselect_b64 s[34:35], -1, 0
	s_and_b64 vcc, s[34:35], exec
	s_cselect_b32 s76, s6, s70
	s_cselect_b32 s34, s5, s69
	s_cselect_b32 s35, s4, s68
	s_cselect_b32 s75, s7, s71
	s_add_u32 s76, s76, s72
	s_addc_u32 s75, s75, s73
	s_add_u32 s76, s76, 0xfff80080
	s_addc_u32 s75, s75, -1
	s_add_u32 s35, s35, s72
	s_addc_u32 s34, s34, s73
	s_add_u32 s35, s35, 0xfff80080
	s_addc_u32 s34, s34, -1
	s_cmp_eq_u32 s74, 28
	s_cselect_b32 s74, s91, s35
	s_cselect_b32 s77, s61, s75
	s_cselect_b32 s76, s90, s76
	s_cselect_b32 s75, s59, s34
	v_lshl_add_u64 v[220:221], v[146:147], 0, s[72:73]
	s_add_i32 m0, s67, 0xc000
	global_load_lds_dwordx4 v[220:221], off
	v_lshl_add_u64 v[220:221], v[148:149], 0, s[72:73]
	s_add_i32 m0, s67, 0xe000
	s_nop 0
	global_load_lds_dwordx4 v[220:221], off
	s_waitcnt vmcnt(8)
	s_waitcnt lgkmcnt(0)
	s_barrier
	s_setprio 1
	s_waitcnt lgkmcnt(0)
	v_mfma_f32_16x16x32_bf16 v[126:129], v[156:159], v[188:191], v[126:129]
	v_mfma_f32_16x16x32_bf16 v[122:125], v[164:167], v[188:191], v[122:125]
	v_mfma_f32_16x16x32_bf16 v[118:121], v[156:159], v[196:199], v[118:121]
	v_mfma_f32_16x16x32_bf16 v[110:113], v[164:167], v[196:199], v[110:113]
	v_mfma_f32_16x16x32_bf16 v[102:105], v[156:159], v[204:207], v[102:105]
	v_mfma_f32_16x16x32_bf16 v[94:97], v[164:167], v[204:207], v[94:97]
	v_mfma_f32_16x16x32_bf16 v[86:89], v[156:159], v[212:215], v[86:89]
	v_mfma_f32_16x16x32_bf16 v[78:81], v[164:167], v[212:215], v[78:81]
	v_mfma_f32_16x16x32_bf16 v[126:129], v[160:163], v[192:195], v[126:129]
	v_mfma_f32_16x16x32_bf16 v[122:125], v[168:171], v[192:195], v[122:125]
	v_mfma_f32_16x16x32_bf16 v[118:121], v[160:163], v[200:203], v[118:121]
	v_mfma_f32_16x16x32_bf16 v[110:113], v[168:171], v[200:203], v[110:113]
	v_mfma_f32_16x16x32_bf16 v[102:105], v[160:163], v[208:211], v[102:105]
	v_mfma_f32_16x16x32_bf16 v[94:97], v[168:171], v[208:211], v[94:97]
	v_mfma_f32_16x16x32_bf16 v[86:89], v[160:163], v[216:219], v[86:89]
	v_mfma_f32_16x16x32_bf16 v[78:81], v[168:171], v[216:219], v[78:81]
	s_setprio 0
	s_setprio 1
	v_mfma_f32_16x16x32_bf16 v[114:117], v[172:175], v[188:191], v[114:117]
	v_mfma_f32_16x16x32_bf16 v[106:109], v[180:183], v[188:191], v[106:109]
	v_mfma_f32_16x16x32_bf16 v[98:101], v[172:175], v[196:199], v[98:101]
	v_mfma_f32_16x16x32_bf16 v[90:93], v[180:183], v[196:199], v[90:93]
	v_mfma_f32_16x16x32_bf16 v[82:85], v[172:175], v[204:207], v[82:85]
	v_mfma_f32_16x16x32_bf16 v[74:77], v[180:183], v[204:207], v[74:77]
	v_mfma_f32_16x16x32_bf16 v[70:73], v[172:175], v[212:215], v[70:73]
	v_mfma_f32_16x16x32_bf16 v[66:69], v[180:183], v[212:215], v[66:69]
	v_mfma_f32_16x16x32_bf16 v[114:117], v[176:179], v[192:195], v[114:117]
	v_mfma_f32_16x16x32_bf16 v[106:109], v[184:187], v[192:195], v[106:109]
	v_mfma_f32_16x16x32_bf16 v[98:101], v[176:179], v[200:203], v[98:101]
	v_mfma_f32_16x16x32_bf16 v[90:93], v[184:187], v[200:203], v[90:93]
	v_mfma_f32_16x16x32_bf16 v[82:85], v[176:179], v[208:211], v[82:85]
	v_mfma_f32_16x16x32_bf16 v[74:77], v[184:187], v[208:211], v[74:77]
	v_mfma_f32_16x16x32_bf16 v[70:73], v[176:179], v[216:219], v[70:73]
	v_mfma_f32_16x16x32_bf16 v[66:69], v[184:187], v[216:219], v[66:69]
	s_setprio 0
	s_barrier
	s_add_i32 s34, s84, s11
	v_lshl_add_u64 v[220:221], s[74:75], 0, v[134:135]
	s_mov_b32 m0, s34
	ds_read_b128 v[188:191], v154 offset:16384
	ds_read_b128 v[192:195], v154 offset:17408
	ds_read_b128 v[196:199], v154 offset:18432
	ds_read_b128 v[200:203], v154 offset:19456
	ds_read_b128 v[204:207], v154 offset:20480
	ds_read_b128 v[208:211], v154 offset:21504
	ds_read_b128 v[212:215], v154 offset:22528
	ds_read_b128 v[216:219], v154 offset:23552
	global_load_lds_dwordx4 v[220:221], off
	s_add_i32 m0, s34, 0x2000
	s_add_u32 s34, s74, 0x80000
	v_lshl_add_u64 v[222:223], s[74:75], 0, v[130:131]
	s_addc_u32 s35, s75, 0
	s_add_i32 s93, s85, s11
	global_load_lds_dwordx4 v[222:223], off
	v_lshl_add_u64 v[224:225], s[34:35], 0, v[134:135]
	s_mov_b32 m0, s93
	v_lshl_add_u64 v[226:227], s[76:77], 0, v[132:133]
	global_load_lds_dwordx4 v[224:225], off
	v_lshl_add_u64 v[224:225], s[34:35], 0, v[130:131]
	s_add_i32 m0, s93, 0x2000
	s_nop 0
	global_load_lds_dwordx4 v[224:225], off
	v_lshl_add_u64 v[224:225], s[76:77], 0, v[136:137]
	s_mov_b32 m0, s67
	s_nop 0
	global_load_lds_dwordx4 v[224:225], off
	s_mov_b32 m0, s78
	s_nop 0
	global_load_lds_dwordx4 v[226:227], off
	s_waitcnt vmcnt(8)
	s_waitcnt lgkmcnt(0)
	s_barrier
; #define PG8_STAGEA(bufoff, gbase, voff) PG8_STAGE_X(bufoff, gbase, voff, PG8_AUX_A)
; #define PG8_STAGEB(bufoff, gbase, voff) PG8_STAGE_X(bufoff, gbase, voff, PG8_AUX_B)
; #define PG8_LDA(dst, b, h) do { _Pragma("unroll") for (int m = 0; m < 4; ++m) _Pragma("unroll") for (int k = 0; k < 2; ++k) dst[m][k] = *(const PG8_LAS bf16x8*)(lds + PG8_SA(b, h) + aoff + m * 2048 + k * 1024); } while (0)
; #define PG8_LDB(dst, b, h) do { _Pragma("unroll") for (int n = 0; n < 2; ++n) _Pragma("unroll") for (int k = 0; k < 2; ++k) dst[n][k] = *(const PG8_LAS bf16x8*)(lds + PG8_SB(b, h) + boff + n * 2048 + k * 1024); } while (0)
; #define PG8_MMA(ai, bj, At, Bt) do { __builtin_amdgcn_s_setprio(1); _Pragma("unroll") for (int m = 0; m < 4; ++m) _Pragma("unroll") for (int n = 0; n < 2; ++n) _Pragma("unroll") for (int k = 0; k < 2; ++k) \
;         acc[ai][bj][m][n] = __builtin_amdgcn_mfma_f32_16x16x32_bf16(Bt[n][k], At[m][k], acc[ai][bj][m][n], 0, 0, 0); __builtin_amdgcn_s_setprio(0); } while (0)
; #define PG8_WAIT_V(n) asm volatile("s_waitcnt vmcnt(" #n ")" ::: "memory")
; #define PG8_WAIT_L(n) asm volatile("s_waitcnt lgkmcnt(" #n ")" ::: "memory")
; #define PG8_BAR __builtin_amdgcn_s_barrier()
; #define PG8_SCHED __builtin_amdgcn_sched_barrier(0)
; template <class Epi, class Sched, bool ALIGN_EPI = false, bool SP2 = false>
; __device__ __forceinline__ void gemm_phase(PG8_LAS unsigned char* lds, const Gemm g, const Sched& S, const Epi& E) {
;     ...
;             PG8_WAIT_V(8); PG8_WAIT_L(0); PG8_BAR; PG8_MMA(0, 0, At, B0); PG8_MMA(0, 1, At, B1); PG8_BAR; PG8_SCHED;
;             PG8_LDA(At, 0, 1); PG8_STAGEB(PG8_SB(0, 0), b2, voffB); PG8_STAGEB(PG8_SB(0, 1), b2 + hstep, voffB); PG8_STAGEA(PG8_SA(0, 0), a2, voffA);
;             PG8_WAIT_V(8); PG8_WAIT_L(0); PG8_BAR; PG8_MMA(1, 0, At, B0); PG8_MMA(1, 1, At, B1); PG8_BAR; PG8_SCHED;
;             PG8_LDB(B0, 1, 0); PG8_LDB(B1, 1, 1); PG8_SCHED; PG8_LDA(At, 1, 0); PG8_STAGEA(PG8_SA(0, 1), a2 + hstep, voffA);
;             PG8_WAIT_V(8); PG8_WAIT_L(0); PG8_BAR; PG8_MMA(0, 0, At, B0); PG8_MMA(0, 1, At, B1); PG8_BAR; PG8_SCHED;
	s_setprio 1
	s_waitcnt lgkmcnt(0)
	v_mfma_f32_16x16x32_bf16 v[62:65], v[156:159], v[188:191], v[62:65]
	v_mfma_f32_16x16x32_bf16 v[58:61], v[164:167], v[188:191], v[58:61]
	v_mfma_f32_16x16x32_bf16 v[54:57], v[156:159], v[196:199], v[54:57]
	v_mfma_f32_16x16x32_bf16 v[46:49], v[164:167], v[196:199], v[46:49]
	v_mfma_f32_16x16x32_bf16 v[38:41], v[156:159], v[204:207], v[38:41]
	v_mfma_f32_16x16x32_bf16 v[30:33], v[164:167], v[204:207], v[30:33]
	v_mfma_f32_16x16x32_bf16 v[22:25], v[156:159], v[212:215], v[22:25]
	v_mfma_f32_16x16x32_bf16 v[14:17], v[164:167], v[212:215], v[14:17]
	v_mfma_f32_16x16x32_bf16 v[62:65], v[160:163], v[192:195], v[62:65]
	v_mfma_f32_16x16x32_bf16 v[58:61], v[168:171], v[192:195], v[58:61]
	v_mfma_f32_16x16x32_bf16 v[54:57], v[160:163], v[200:203], v[54:57]
	v_mfma_f32_16x16x32_bf16 v[46:49], v[168:171], v[200:203], v[46:49]
	v_mfma_f32_16x16x32_bf16 v[38:41], v[160:163], v[208:211], v[38:41]
	v_mfma_f32_16x16x32_bf16 v[30:33], v[168:171], v[208:211], v[30:33]
	v_mfma_f32_16x16x32_bf16 v[22:25], v[160:163], v[216:219], v[22:25]
	v_mfma_f32_16x16x32_bf16 v[14:17], v[168:171], v[216:219], v[14:17]
	s_setprio 0
	s_setprio 1
	v_mfma_f32_16x16x32_bf16 v[50:53], v[172:175], v[188:191], v[50:53]
	v_mfma_f32_16x16x32_bf16 v[42:45], v[180:183], v[188:191], v[42:45]
	v_mfma_f32_16x16x32_bf16 v[34:37], v[172:175], v[196:199], v[34:37]
	v_mfma_f32_16x16x32_bf16 v[26:29], v[180:183], v[196:199], v[26:29]
	v_mfma_f32_16x16x32_bf16 v[18:21], v[172:175], v[204:207], v[18:21]
	v_mfma_f32_16x16x32_bf16 v[10:13], v[180:183], v[204:207], v[10:13]
	v_mfma_f32_16x16x32_bf16 v[6:9], v[172:175], v[212:215], v[6:9]
	v_mfma_f32_16x16x32_bf16 v[2:5], v[180:183], v[212:215], v[2:5]
	v_mfma_f32_16x16x32_bf16 v[50:53], v[176:179], v[192:195], v[50:53]
	v_mfma_f32_16x16x32_bf16 v[42:45], v[184:187], v[192:195], v[42:45]
	v_mfma_f32_16x16x32_bf16 v[34:37], v[176:179], v[200:203], v[34:37]
	v_mfma_f32_16x16x32_bf16 v[26:29], v[184:187], v[200:203], v[26:29]
	v_mfma_f32_16x16x32_bf16 v[18:21], v[176:179], v[208:211], v[18:21]
	v_mfma_f32_16x16x32_bf16 v[10:13], v[184:187], v[208:211], v[10:13]
	v_mfma_f32_16x16x32_bf16 v[6:9], v[176:179], v[216:219], v[6:9]
	v_mfma_f32_16x16x32_bf16 v[2:5], v[184:187], v[216:219], v[2:5]
	s_setprio 0
	s_barrier
	s_add_i32 s93, 0, 0x18000
	v_add_u32_e32 v155, s93, v150
	s_add_i32 s94, 0, 0x1c000
	ds_read_b128 v[156:159], v155
	ds_read_b128 v[160:163], v155 offset:1024
	ds_read_b128 v[164:167], v155 offset:2048
	ds_read_b128 v[168:171], v155 offset:3072
	v_add_u32_e32 v155, s94, v150
	ds_read_b128 v[172:175], v155
	ds_read_b128 v[176:179], v155 offset:1024
	ds_read_b128 v[180:183], v155 offset:2048
	ds_read_b128 v[184:187], v155 offset:3072
	s_add_u32 s34, s76, 0x80000
	s_addc_u32 s35, s77, 0
	s_mov_b32 m0, s79
	v_lshl_add_u64 v[228:229], s[34:35], 0, v[136:137]
	ds_read_b128 v[188:191], v154 offset:32768
	ds_read_b128 v[192:195], v154 offset:33792
	ds_read_b128 v[196:199], v154 offset:34816
	ds_read_b128 v[200:203], v154 offset:35840
	ds_read_b128 v[204:207], v154 offset:36864
	ds_read_b128 v[208:211], v154 offset:37888
	ds_read_b128 v[212:215], v154 offset:38912
	ds_read_b128 v[216:219], v154 offset:39936
	global_load_lds_dwordx4 v[228:229], off
	v_lshl_add_u64 v[228:229], s[34:35], 0, v[132:133]
	s_mov_b32 m0, s80
	s_nop 0
	global_load_lds_dwordx4 v[228:229], off
	s_waitcnt vmcnt(8)
	s_waitcnt lgkmcnt(0)
	s_barrier
	s_setprio 1
	s_waitcnt lgkmcnt(0)
	v_mfma_f32_16x16x32_bf16 v[126:129], v[156:159], v[188:191], v[126:129]
	v_mfma_f32_16x16x32_bf16 v[122:125], v[164:167], v[188:191], v[122:125]
	v_mfma_f32_16x16x32_bf16 v[118:121], v[156:159], v[196:199], v[118:121]
	v_mfma_f32_16x16x32_bf16 v[110:113], v[164:167], v[196:199], v[110:113]
	v_mfma_f32_16x16x32_bf16 v[102:105], v[156:159], v[204:207], v[102:105]
	v_mfma_f32_16x16x32_bf16 v[94:97], v[164:167], v[204:207], v[94:97]
	v_mfma_f32_16x16x32_bf16 v[86:89], v[156:159], v[212:215], v[86:89]
	v_mfma_f32_16x16x32_bf16 v[78:81], v[164:167], v[212:215], v[78:81]
	v_mfma_f32_16x16x32_bf16 v[126:129], v[160:163], v[192:195], v[126:129]
	v_mfma_f32_16x16x32_bf16 v[122:125], v[168:171], v[192:195], v[122:125]
	v_mfma_f32_16x16x32_bf16 v[118:121], v[160:163], v[200:203], v[118:121]
	v_mfma_f32_16x16x32_bf16 v[110:113], v[168:171], v[200:203], v[110:113]
	v_mfma_f32_16x16x32_bf16 v[102:105], v[160:163], v[208:211], v[102:105]
	v_mfma_f32_16x16x32_bf16 v[94:97], v[168:171], v[208:211], v[94:97]
	v_mfma_f32_16x16x32_bf16 v[86:89], v[160:163], v[216:219], v[86:89]
	v_mfma_f32_16x16x32_bf16 v[78:81], v[168:171], v[216:219], v[78:81]
	s_setprio 0
	s_setprio 1
	v_mfma_f32_16x16x32_bf16 v[114:117], v[172:175], v[188:191], v[114:117]
	v_mfma_f32_16x16x32_bf16 v[106:109], v[180:183], v[188:191], v[106:109]
	v_mfma_f32_16x16x32_bf16 v[98:101], v[172:175], v[196:199], v[98:101]
	v_mfma_f32_16x16x32_bf16 v[90:93], v[180:183], v[196:199], v[90:93]
	v_mfma_f32_16x16x32_bf16 v[82:85], v[172:175], v[204:207], v[82:85]
	v_mfma_f32_16x16x32_bf16 v[74:77], v[180:183], v[204:207], v[74:77]
	v_mfma_f32_16x16x32_bf16 v[70:73], v[172:175], v[212:215], v[70:73]
	v_mfma_f32_16x16x32_bf16 v[66:69], v[180:183], v[212:215], v[66:69]
	v_mfma_f32_16x16x32_bf16 v[114:117], v[176:179], v[192:195], v[114:117]
	v_mfma_f32_16x16x32_bf16 v[106:109], v[184:187], v[192:195], v[106:109]
	v_mfma_f32_16x16x32_bf16 v[98:101], v[176:179], v[200:203], v[98:101]
	v_mfma_f32_16x16x32_bf16 v[90:93], v[184:187], v[200:203], v[90:93]
	v_mfma_f32_16x16x32_bf16 v[82:85], v[176:179], v[208:211], v[82:85]
	v_mfma_f32_16x16x32_bf16 v[74:77], v[184:187], v[208:211], v[74:77]
	v_mfma_f32_16x16x32_bf16 v[70:73], v[176:179], v[216:219], v[70:73]
	v_mfma_f32_16x16x32_bf16 v[66:69], v[184:187], v[216:219], v[66:69]
	s_setprio 0
	s_barrier
; #define PG8_STAGEA(bufoff, gbase, voff) PG8_STAGE_X(bufoff, gbase, voff, PG8_AUX_A)
; #define PG8_STAGEB(bufoff, gbase, voff) PG8_STAGE_X(bufoff, gbase, voff, PG8_AUX_B)
; #define PG8_LDA(dst, b, h) do { _Pragma("unroll") for (int m = 0; m < 4; ++m) _Pragma("unroll") for (int k = 0; k < 2; ++k) dst[m][k] = *(const PG8_LAS bf16x8*)(lds + PG8_SA(b, h) + aoff + m * 2048 + k * 1024); } while (0)
; #define PG8_MMA(ai, bj, At, Bt) do { __builtin_amdgcn_s_setprio(1); _Pragma("unroll") for (int m = 0; m < 4; ++m) _Pragma("unroll") for (int n = 0; n < 2; ++n) _Pragma("unroll") for (int k = 0; k < 2; ++k) \
;         acc[ai][bj][m][n] = __builtin_amdgcn_mfma_f32_16x16x32_bf16(Bt[n][k], At[m][k], acc[ai][bj][m][n], 0, 0, 0); __builtin_amdgcn_s_setprio(0); } while (0)
; #define PG8_WAIT_V(n) asm volatile("s_waitcnt vmcnt(" #n ")" ::: "memory")
; #define PG8_WAIT_L(n) asm volatile("s_waitcnt lgkmcnt(" #n ")" ::: "memory")
; #define PG8_BAR __builtin_amdgcn_s_barrier()
; #define PG8_SCHED __builtin_amdgcn_sched_barrier(0)
; template <class Epi, class Sched, bool ALIGN_EPI = false, bool SP2 = false>
; __device__ __forceinline__ void gemm_phase(PG8_LAS unsigned char* lds, const Gemm g, const Sched& S, const Epi& E) {
;     ...
;             PG8_WAIT_V(8); PG8_WAIT_L(0); PG8_BAR; PG8_MMA(0, 0, At, B0); PG8_MMA(0, 1, At, B1); PG8_BAR; PG8_SCHED;
;             PG8_LDA(At, 1, 1); PG8_STAGEB(PG8_SB(1, 0), b3, voffB); PG8_STAGEB(PG8_SB(1, 1), b3 + hstep, voffB); PG8_STAGEA(PG8_SA(1, 0), a3, voffA);
;             PG8_WAIT_V(8); PG8_WAIT_L(0); PG8_BAR; PG8_MMA(1, 0, At, B0); PG8_MMA(1, 1, At, B1); PG8_BAR; PG8_SCHED;
	s_add_i32 s34, s93, s11
	v_lshl_add_u64 v[220:221], v[220:221], 0, s[54:55]
	s_mov_b32 m0, s34
	ds_read_b128 v[188:191], v154 offset:49152
	ds_read_b128 v[192:195], v154 offset:50176
	ds_read_b128 v[196:199], v154 offset:51200
	ds_read_b128 v[200:203], v154 offset:52224
	ds_read_b128 v[204:207], v154 offset:53248
	ds_read_b128 v[208:211], v154 offset:54272
	ds_read_b128 v[212:215], v154 offset:55296
	ds_read_b128 v[216:219], v154 offset:56320
	global_load_lds_dwordx4 v[220:221], off
	s_add_i32 m0, s34, 0x2000
	s_add_u32 s34, s74, 0x80080
	v_lshl_add_u64 v[220:221], v[222:223], 0, s[54:55]
	s_addc_u32 s35, s75, 0
	s_add_i32 s74, s94, s11
	global_load_lds_dwordx4 v[220:221], off
	v_lshl_add_u64 v[220:221], s[34:35], 0, v[134:135]
	s_mov_b32 m0, s74
	s_nop 0
	global_load_lds_dwordx4 v[220:221], off
	v_lshl_add_u64 v[220:221], s[34:35], 0, v[130:131]
	s_add_i32 m0, s74, 0x2000
	s_nop 0
	global_load_lds_dwordx4 v[220:221], off
	v_lshl_add_u64 v[220:221], v[224:225], 0, s[54:55]
	s_mov_b32 m0, s82
	s_nop 0
	global_load_lds_dwordx4 v[220:221], off
	v_lshl_add_u64 v[220:221], v[226:227], 0, s[54:55]
	s_mov_b32 m0, s83
	s_nop 0
	global_load_lds_dwordx4 v[220:221], off
	s_waitcnt vmcnt(8)
	s_waitcnt lgkmcnt(0)
	s_barrier
	s_setprio 1
	s_waitcnt lgkmcnt(0)
	v_mfma_f32_16x16x32_bf16 v[62:65], v[156:159], v[188:191], v[62:65]
	v_mfma_f32_16x16x32_bf16 v[58:61], v[164:167], v[188:191], v[58:61]
	v_mfma_f32_16x16x32_bf16 v[54:57], v[156:159], v[196:199], v[54:57]
	v_mfma_f32_16x16x32_bf16 v[46:49], v[164:167], v[196:199], v[46:49]
	v_mfma_f32_16x16x32_bf16 v[38:41], v[156:159], v[204:207], v[38:41]
	v_mfma_f32_16x16x32_bf16 v[30:33], v[164:167], v[204:207], v[30:33]
	v_mfma_f32_16x16x32_bf16 v[22:25], v[156:159], v[212:215], v[22:25]
	v_mfma_f32_16x16x32_bf16 v[14:17], v[164:167], v[212:215], v[14:17]
	v_mfma_f32_16x16x32_bf16 v[62:65], v[160:163], v[192:195], v[62:65]
	v_mfma_f32_16x16x32_bf16 v[58:61], v[168:171], v[192:195], v[58:61]
	v_mfma_f32_16x16x32_bf16 v[54:57], v[160:163], v[200:203], v[54:57]
	v_mfma_f32_16x16x32_bf16 v[46:49], v[168:171], v[200:203], v[46:49]
	v_mfma_f32_16x16x32_bf16 v[38:41], v[160:163], v[208:211], v[38:41]
	v_mfma_f32_16x16x32_bf16 v[30:33], v[168:171], v[208:211], v[30:33]
	v_mfma_f32_16x16x32_bf16 v[22:25], v[160:163], v[216:219], v[22:25]
	v_mfma_f32_16x16x32_bf16 v[14:17], v[168:171], v[216:219], v[14:17]
	s_setprio 0
	s_setprio 1
	v_mfma_f32_16x16x32_bf16 v[50:53], v[172:175], v[188:191], v[50:53]
	v_mfma_f32_16x16x32_bf16 v[42:45], v[180:183], v[188:191], v[42:45]
	v_mfma_f32_16x16x32_bf16 v[34:37], v[172:175], v[196:199], v[34:37]
	v_mfma_f32_16x16x32_bf16 v[26:29], v[180:183], v[196:199], v[26:29]
	v_mfma_f32_16x16x32_bf16 v[18:21], v[172:175], v[204:207], v[18:21]
	v_mfma_f32_16x16x32_bf16 v[10:13], v[180:183], v[204:207], v[10:13]
	v_mfma_f32_16x16x32_bf16 v[6:9], v[172:175], v[212:215], v[6:9]
	v_mfma_f32_16x16x32_bf16 v[2:5], v[180:183], v[212:215], v[2:5]
	v_mfma_f32_16x16x32_bf16 v[50:53], v[176:179], v[192:195], v[50:53]
	v_mfma_f32_16x16x32_bf16 v[42:45], v[184:187], v[192:195], v[42:45]
	v_mfma_f32_16x16x32_bf16 v[34:37], v[176:179], v[200:203], v[34:37]
	v_mfma_f32_16x16x32_bf16 v[26:29], v[184:187], v[200:203], v[26:29]
	v_mfma_f32_16x16x32_bf16 v[18:21], v[176:179], v[208:211], v[18:21]
	v_mfma_f32_16x16x32_bf16 v[10:13], v[184:187], v[208:211], v[10:13]
	v_mfma_f32_16x16x32_bf16 v[6:9], v[176:179], v[216:219], v[6:9]
	v_mfma_f32_16x16x32_bf16 v[2:5], v[184:187], v[216:219], v[2:5]
	s_setprio 0
	s_barrier
	s_add_u32 s72, s72, 0x100
	s_addc_u32 s73, s73, 0
	s_mov_b32 s74, s92
	s_cbranch_vccz .LBB0_295
	s_and_b64 vcc, exec, s[56:57]
	s_cbranch_vccz .LBB0_298
	s_barrier

; #define PG8_STAGEA(bufoff, gbase, voff) PG8_STAGE_X(bufoff, gbase, voff, PG8_AUX_A)
; #define PG8_STAGEB(bufoff, gbase, voff) PG8_STAGE_X(bufoff, gbase, voff, PG8_AUX_B)
; #define PG8_LDA(dst, b, h) do { _Pragma("unroll") for (int m = 0; m < 4; ++m) _Pragma("unroll") for (int k = 0; k < 2; ++k) dst[m][k] = *(const PG8_LAS bf16x8*)(lds + PG8_SA(b, h) + aoff + m * 2048 + k * 1024); } while (0)
; #define PG8_LDB(dst, b, h) do { _Pragma("unroll") for (int n = 0; n < 2; ++n) _Pragma("unroll") for (int k = 0; k < 2; ++k) dst[n][k] = *(const PG8_LAS bf16x8*)(lds + PG8_SB(b, h) + boff + n * 2048 + k * 1024); } while (0)
; #define PG8_MMA(ai, bj, At, Bt) do { __builtin_amdgcn_s_setprio(1); _Pragma("unroll") for (int m = 0; m < 4; ++m) _Pragma("unroll") for (int n = 0; n < 2; ++n) _Pragma("unroll") for (int k = 0; k < 2; ++k) \
;         acc[ai][bj][m][n] = __builtin_amdgcn_mfma_f32_16x16x32_bf16(Bt[n][k], At[m][k], acc[ai][bj][m][n], 0, 0, 0); __builtin_amdgcn_s_setprio(0); } while (0)
; template <class Epi, class Sched, bool ALIGN_EPI = false, bool SP2 = false>
; __device__ __forceinline__ void gemm_phase(PG8_LAS unsigned char* lds, const Gemm g, const Sched& S, const Epi& E) {
;     ...
;         for (int t = 0; t < nt; t += 2) {
;             const bool last = (t == nt - 2);
;             if constexpr (HasMid<Epi>::value) { if (t == ns) E.mid(acc, cur, wr, wc, fr, fq); }
;             const char* sA1 = (t + 1 >= ns) ? cA2 : cA; const char* sA2 = (t + 2 >= ns) ? cA2 : cA; const char* sB2 = (t + 2 >= ns) ? cB2 : cB;
;             const char* a1 = sA1 + (size_t)(t + 1) * kstep;
;             const char* a2 = last ? nA : sA2 + (size_t)(t + 2) * kstep; const char* b2 = last ? nB : sB2 + (size_t)(t + 2) * kstep;
;             const char* a3 = a2 + kstep; const char* b3 = b2 + kstep;
;             if (last && has_next) S.a_ready(nxt);
;             if constexpr (SP2) {
;             PG8_LDB(B0, 0, 0); PG8_LDB(B1, 0, 1); PG8_SCHED; PG8_LDA(At, 0, 0); PG8_STAGEA(PG8_SA(1, 1), a1 + hstep, voffA);
;             PG8_WAIT_V(8); PG8_WAIT_L(0); PG8_BAR; PG8_MMA(0, 0, At, B0); PG8_MMA(0, 1, At, B1); PG8_BAR; PG8_SCHED;
;             PG8_LDA(At, 0, 1); PG8_STAGEB(PG8_SB(0, 0), b2, voffB); PG8_STAGEB(PG8_SB(0, 1), b2 + hstep, voffB); PG8_STAGEA(PG8_SA(0, 0), a2, voffA);
;             PG8_WAIT_V(8); PG8_WAIT_L(0); PG8_BAR; PG8_MMA(1, 0, At, B0); PG8_MMA(1, 1, At, B1); PG8_BAR; PG8_SCHED;
.LBB0_643:
	ds_read_b128 v[82:85], v166
	ds_read_b128 v[90:93], v166 offset:1024
	ds_read_b128 v[94:97], v166 offset:2048
	ds_read_b128 v[158:161], v166 offset:3072
	ds_read_b128 v[170:173], v167
	ds_read_b128 v[174:177], v167 offset:1024
	ds_read_b128 v[178:181], v167 offset:2048
	ds_read_b128 v[182:185], v167 offset:3072
	ds_read_b128 v[186:189], v168
	ds_read_b128 v[190:193], v168 offset:1024
	ds_read_b128 v[194:197], v168 offset:2048
	ds_read_b128 v[198:201], v168 offset:3072
	ds_read_b128 v[202:205], v168 offset:4096
	ds_read_b128 v[206:209], v168 offset:5120
	ds_read_b128 v[210:213], v168 offset:6144
	ds_read_b128 v[214:217], v168 offset:7168
	s_add_i32 s97, s96, 2
	s_cmp_lt_u32 s96, 30
	s_cselect_b32 s37, s72, s50
	s_cselect_b32 s34, s71, s47
	s_cselect_b32 s35, s70, s46
	s_cselect_b32 s36, s73, s51
	s_add_u32 s37, s37, s74
	s_addc_u32 s36, s36, s75
	s_add_u32 s37, s37, 0xfff80080
	s_addc_u32 s36, s36, -1
	s_add_u32 s35, s35, s74
	s_addc_u32 s34, s34, s75
	s_add_u32 s35, s35, 0xfff80080
	s_addc_u32 s34, s34, -1
	s_cmp_eq_u32 s96, 30
	s_cselect_b32 s83, s61, s36
	s_cselect_b32 s82, s67, s37
	s_cselect_b32 s85, s59, s34
	s_cselect_b32 s84, s95, s35
	s_add_i32 s37, s93, s8
	s_add_i32 m0, s9, 0xc000
	s_add_i32 s36, s9, 0xe000
	s_add_i32 s38, s37, 0x2000
	s_add_u32 s86, s84, 0x80000
	s_addc_u32 s87, s85, 0
	s_add_i32 s39, s94, s8
	s_add_i32 s24, s39, 0x2000
	s_add_i32 s25, 0, 0x18000
	s_add_i32 vcc_hi, 0, 0x1c000
	s_add_u32 s80, s82, 0x80000
	s_addc_u32 s81, s83, 0
	s_add_i32 vcc_lo, s25, s8
	s_add_i32 s34, vcc_lo, 0x2000
	s_add_u32 s78, s84, 0x80080
	s_addc_u32 s79, s85, 0
	s_add_i32 s35, vcc_hi, s8
	s_add_i32 s28, s35, 0x2000
	s_add_u32 s76, s74, 0x100
	s_addc_u32 s77, s75, 0
	s_cmp_gt_u32 s96, 29
	v_lshl_add_u64 v[162:163], v[74:75], 0, s[74:75]
	global_load_lds_dwordx4 v[162:163], off
	v_lshl_add_u64 v[162:163], v[76:77], 0, s[74:75]
	s_mov_b32 m0, s36
	s_nop 0
	global_load_lds_dwordx4 v[162:163], off
	s_waitcnt vmcnt(8)
	s_waitcnt lgkmcnt(0)
	s_barrier
	s_setprio 1
	s_waitcnt lgkmcnt(0)
	v_mfma_f32_16x16x32_bf16 v[142:145], v[82:85], v[186:189], v[142:145]
	v_mfma_f32_16x16x32_bf16 v[138:141], v[94:97], v[186:189], v[138:141]
	v_mfma_f32_16x16x32_bf16 v[126:129], v[82:85], v[194:197], v[126:129]
	v_mfma_f32_16x16x32_bf16 v[122:125], v[94:97], v[194:197], v[122:125]
	v_mfma_f32_16x16x32_bf16 v[110:113], v[82:85], v[202:205], v[110:113]
	v_mfma_f32_16x16x32_bf16 v[106:109], v[94:97], v[202:205], v[106:109]
	v_mfma_f32_16x16x32_bf16 v[86:89], v[82:85], v[210:213], v[86:89]
	v_mfma_f32_16x16x32_bf16 v[78:81], v[94:97], v[210:213], v[78:81]
	v_mfma_f32_16x16x32_bf16 v[142:145], v[90:93], v[190:193], v[142:145]
	v_mfma_f32_16x16x32_bf16 v[138:141], v[158:161], v[190:193], v[138:141]
	v_mfma_f32_16x16x32_bf16 v[126:129], v[90:93], v[198:201], v[126:129]
	v_mfma_f32_16x16x32_bf16 v[122:125], v[158:161], v[198:201], v[122:125]
	v_mfma_f32_16x16x32_bf16 v[110:113], v[90:93], v[206:209], v[110:113]
	v_mfma_f32_16x16x32_bf16 v[106:109], v[158:161], v[206:209], v[106:109]
	v_mfma_f32_16x16x32_bf16 v[86:89], v[90:93], v[214:217], v[86:89]
	v_mfma_f32_16x16x32_bf16 v[78:81], v[158:161], v[214:217], v[78:81]
	s_setprio 0
	s_setprio 1
	v_mfma_f32_16x16x32_bf16 v[134:137], v[170:173], v[186:189], v[134:137]
	v_mfma_f32_16x16x32_bf16 v[130:133], v[178:181], v[186:189], v[130:133]
	v_mfma_f32_16x16x32_bf16 v[118:121], v[170:173], v[194:197], v[118:121]
	v_mfma_f32_16x16x32_bf16 v[114:117], v[178:181], v[194:197], v[114:117]
	v_mfma_f32_16x16x32_bf16 v[102:105], v[170:173], v[202:205], v[102:105]
	v_mfma_f32_16x16x32_bf16 v[98:101], v[178:181], v[202:205], v[98:101]
	v_mfma_f32_16x16x32_bf16 v[70:73], v[170:173], v[210:213], v[70:73]
	v_mfma_f32_16x16x32_bf16 v[66:69], v[178:181], v[210:213], v[66:69]
	v_mfma_f32_16x16x32_bf16 v[134:137], v[174:177], v[190:193], v[134:137]
	v_mfma_f32_16x16x32_bf16 v[130:133], v[182:185], v[190:193], v[130:133]
	v_mfma_f32_16x16x32_bf16 v[118:121], v[174:177], v[198:201], v[118:121]
	v_mfma_f32_16x16x32_bf16 v[114:117], v[182:185], v[198:201], v[114:117]
	v_mfma_f32_16x16x32_bf16 v[102:105], v[174:177], v[206:209], v[102:105]
	v_mfma_f32_16x16x32_bf16 v[98:101], v[182:185], v[206:209], v[98:101]
	v_mfma_f32_16x16x32_bf16 v[70:73], v[174:177], v[214:217], v[70:73]
	v_mfma_f32_16x16x32_bf16 v[66:69], v[182:185], v[214:217], v[66:69]
	s_setprio 0
	s_barrier
	s_mov_b32 m0, s37
	v_lshl_add_u64 v[162:163], s[84:85], 0, v[146:147]
	ds_read_b128 v[186:189], v168 offset:16384
	ds_read_b128 v[190:193], v168 offset:17408
	ds_read_b128 v[194:197], v168 offset:18432
	ds_read_b128 v[198:201], v168 offset:19456
	ds_read_b128 v[202:205], v168 offset:20480
	ds_read_b128 v[206:209], v168 offset:21504
	ds_read_b128 v[210:213], v168 offset:22528
	ds_read_b128 v[214:217], v168 offset:23552
	global_load_lds_dwordx4 v[162:163], off
	v_lshl_add_u64 v[218:219], s[84:85], 0, v[148:149]
	s_mov_b32 m0, s38
	v_lshl_add_u64 v[220:221], s[86:87], 0, v[146:147]
	global_load_lds_dwordx4 v[218:219], off
	s_mov_b32 m0, s39
	v_lshl_add_u64 v[222:223], s[82:83], 0, v[148:149]
	global_load_lds_dwordx4 v[220:221], off
	v_lshl_add_u64 v[220:221], s[86:87], 0, v[148:149]
	s_mov_b32 m0, s24
	s_nop 0
	global_load_lds_dwordx4 v[220:221], off
	v_lshl_add_u64 v[220:221], s[82:83], 0, v[146:147]
	s_mov_b32 m0, s9
	s_nop 0
	global_load_lds_dwordx4 v[220:221], off
	s_mov_b32 m0, s11
	s_nop 0
	global_load_lds_dwordx4 v[222:223], off
	s_waitcnt vmcnt(8)
	s_waitcnt lgkmcnt(0)
	s_barrier
; #define PG8_STAGEA(bufoff, gbase, voff) PG8_STAGE_X(bufoff, gbase, voff, PG8_AUX_A)
; #define PG8_STAGEB(bufoff, gbase, voff) PG8_STAGE_X(bufoff, gbase, voff, PG8_AUX_B)
; #define PG8_LDA(dst, b, h) do { _Pragma("unroll") for (int m = 0; m < 4; ++m) _Pragma("unroll") for (int k = 0; k < 2; ++k) dst[m][k] = *(const PG8_LAS bf16x8*)(lds + PG8_SA(b, h) + aoff + m * 2048 + k * 1024); } while (0)
; #define PG8_LDB(dst, b, h) do { _Pragma("unroll") for (int n = 0; n < 2; ++n) _Pragma("unroll") for (int k = 0; k < 2; ++k) dst[n][k] = *(const PG8_LAS bf16x8*)(lds + PG8_SB(b, h) + boff + n * 2048 + k * 1024); } while (0)
; #define PG8_MMA(ai, bj, At, Bt) do { __builtin_amdgcn_s_setprio(1); _Pragma("unroll") for (int m = 0; m < 4; ++m) _Pragma("unroll") for (int n = 0; n < 2; ++n) _Pragma("unroll") for (int k = 0; k < 2; ++k) \
;         acc[ai][bj][m][n] = __builtin_amdgcn_mfma_f32_16x16x32_bf16(Bt[n][k], At[m][k], acc[ai][bj][m][n], 0, 0, 0); __builtin_amdgcn_s_setprio(0); } while (0)
; #define PG8_WAIT_V(n) asm volatile("s_waitcnt vmcnt(" #n ")" ::: "memory")
; #define PG8_WAIT_L(n) asm volatile("s_waitcnt lgkmcnt(" #n ")" ::: "memory")
; #define PG8_BAR __builtin_amdgcn_s_barrier()
; #define PG8_SCHED __builtin_amdgcn_sched_barrier(0)
; template <class Epi, class Sched, bool ALIGN_EPI = false, bool SP2 = false>
; __device__ __forceinline__ void gemm_phase(PG8_LAS unsigned char* lds, const Gemm g, const Sched& S, const Epi& E) {
;     ...
;             PG8_WAIT_V(8); PG8_WAIT_L(0); PG8_BAR; PG8_MMA(0, 0, At, B0); PG8_MMA(0, 1, At, B1); PG8_BAR; PG8_SCHED;
;             PG8_LDA(At, 0, 1); PG8_STAGEB(PG8_SB(0, 0), b2, voffB); PG8_STAGEB(PG8_SB(0, 1), b2 + hstep, voffB); PG8_STAGEA(PG8_SA(0, 0), a2, voffA);
;             PG8_WAIT_V(8); PG8_WAIT_L(0); PG8_BAR; PG8_MMA(1, 0, At, B0); PG8_MMA(1, 1, At, B1); PG8_BAR; PG8_SCHED;
;             PG8_LDB(B0, 1, 0); PG8_LDB(B1, 1, 1); PG8_SCHED; PG8_LDA(At, 1, 0); PG8_STAGEA(PG8_SA(0, 1), a2 + hstep, voffA);
;             PG8_WAIT_V(8); PG8_WAIT_L(0); PG8_BAR; PG8_MMA(0, 0, At, B0); PG8_MMA(0, 1, At, B1); PG8_BAR; PG8_SCHED;
	s_setprio 1
	s_waitcnt lgkmcnt(0)
	v_mfma_f32_16x16x32_bf16 v[62:65], v[82:85], v[186:189], v[62:65]
	v_mfma_f32_16x16x32_bf16 v[58:61], v[94:97], v[186:189], v[58:61]
	v_mfma_f32_16x16x32_bf16 v[46:49], v[82:85], v[194:197], v[46:49]
	v_mfma_f32_16x16x32_bf16 v[42:45], v[94:97], v[194:197], v[42:45]
	v_mfma_f32_16x16x32_bf16 v[30:33], v[82:85], v[202:205], v[30:33]
	v_mfma_f32_16x16x32_bf16 v[26:29], v[94:97], v[202:205], v[26:29]
	v_mfma_f32_16x16x32_bf16 v[14:17], v[82:85], v[210:213], v[14:17]
	v_mfma_f32_16x16x32_bf16 v[10:13], v[94:97], v[210:213], v[10:13]
	v_mfma_f32_16x16x32_bf16 v[62:65], v[90:93], v[190:193], v[62:65]
	v_mfma_f32_16x16x32_bf16 v[58:61], v[158:161], v[190:193], v[58:61]
	v_mfma_f32_16x16x32_bf16 v[46:49], v[90:93], v[198:201], v[46:49]
	v_mfma_f32_16x16x32_bf16 v[42:45], v[158:161], v[198:201], v[42:45]
	v_mfma_f32_16x16x32_bf16 v[30:33], v[90:93], v[206:209], v[30:33]
	v_mfma_f32_16x16x32_bf16 v[26:29], v[158:161], v[206:209], v[26:29]
	v_mfma_f32_16x16x32_bf16 v[14:17], v[90:93], v[214:217], v[14:17]
	v_mfma_f32_16x16x32_bf16 v[10:13], v[158:161], v[214:217], v[10:13]
	s_setprio 0
	s_setprio 1
	v_mfma_f32_16x16x32_bf16 v[54:57], v[170:173], v[186:189], v[54:57]
	v_mfma_f32_16x16x32_bf16 v[50:53], v[178:181], v[186:189], v[50:53]
	v_mfma_f32_16x16x32_bf16 v[38:41], v[170:173], v[194:197], v[38:41]
	v_mfma_f32_16x16x32_bf16 v[34:37], v[178:181], v[194:197], v[34:37]
	v_mfma_f32_16x16x32_bf16 v[22:25], v[170:173], v[202:205], v[22:25]
	v_mfma_f32_16x16x32_bf16 v[18:21], v[178:181], v[202:205], v[18:21]
	v_mfma_f32_16x16x32_bf16 v[6:9], v[170:173], v[210:213], v[6:9]
	v_mfma_f32_16x16x32_bf16 v[2:5], v[178:181], v[210:213], v[2:5]
	v_mfma_f32_16x16x32_bf16 v[54:57], v[174:177], v[190:193], v[54:57]
	v_mfma_f32_16x16x32_bf16 v[50:53], v[182:185], v[190:193], v[50:53]
	v_mfma_f32_16x16x32_bf16 v[38:41], v[174:177], v[198:201], v[38:41]
	v_mfma_f32_16x16x32_bf16 v[34:37], v[182:185], v[198:201], v[34:37]
	v_mfma_f32_16x16x32_bf16 v[22:25], v[174:177], v[206:209], v[22:25]
	v_mfma_f32_16x16x32_bf16 v[18:21], v[182:185], v[206:209], v[18:21]
	v_mfma_f32_16x16x32_bf16 v[6:9], v[174:177], v[214:217], v[6:9]
	v_mfma_f32_16x16x32_bf16 v[2:5], v[182:185], v[214:217], v[2:5]
	s_setprio 0
	s_barrier
	v_add_u32_e32 v158, s25, v164
	v_add_u32_e32 v182, vcc_hi, v164
	ds_read_b128 v[82:85], v158
	ds_read_b128 v[90:93], v158 offset:1024
	ds_read_b128 v[94:97], v158 offset:2048
	ds_read_b128 v[158:161], v158 offset:3072
	ds_read_b128 v[170:173], v182
	ds_read_b128 v[174:177], v182 offset:1024
	ds_read_b128 v[178:181], v182 offset:2048
	ds_read_b128 v[182:185], v182 offset:3072
	s_mov_b32 m0, s21
	v_lshl_add_u64 v[224:225], s[80:81], 0, v[146:147]
	ds_read_b128 v[186:189], v168 offset:32768
	ds_read_b128 v[190:193], v168 offset:33792
	ds_read_b128 v[194:197], v168 offset:34816
	ds_read_b128 v[198:201], v168 offset:35840
	ds_read_b128 v[202:205], v168 offset:36864
	ds_read_b128 v[206:209], v168 offset:37888
	ds_read_b128 v[210:213], v168 offset:38912
	ds_read_b128 v[214:217], v168 offset:39936
	global_load_lds_dwordx4 v[224:225], off
	v_lshl_add_u64 v[224:225], s[80:81], 0, v[148:149]
	s_mov_b32 m0, s23
	s_nop 0
	global_load_lds_dwordx4 v[224:225], off
	s_waitcnt vmcnt(8)
	s_waitcnt lgkmcnt(0)
	s_barrier
	s_setprio 1
	s_waitcnt lgkmcnt(0)
	v_mfma_f32_16x16x32_bf16 v[142:145], v[82:85], v[186:189], v[142:145]
	v_mfma_f32_16x16x32_bf16 v[138:141], v[94:97], v[186:189], v[138:141]
	v_mfma_f32_16x16x32_bf16 v[126:129], v[82:85], v[194:197], v[126:129]
	v_mfma_f32_16x16x32_bf16 v[122:125], v[94:97], v[194:197], v[122:125]
	v_mfma_f32_16x16x32_bf16 v[110:113], v[82:85], v[202:205], v[110:113]
	v_mfma_f32_16x16x32_bf16 v[106:109], v[94:97], v[202:205], v[106:109]
	v_mfma_f32_16x16x32_bf16 v[86:89], v[82:85], v[210:213], v[86:89]
	v_mfma_f32_16x16x32_bf16 v[78:81], v[94:97], v[210:213], v[78:81]
	v_mfma_f32_16x16x32_bf16 v[142:145], v[90:93], v[190:193], v[142:145]
	v_mfma_f32_16x16x32_bf16 v[138:141], v[158:161], v[190:193], v[138:141]
	v_mfma_f32_16x16x32_bf16 v[126:129], v[90:93], v[198:201], v[126:129]
	v_mfma_f32_16x16x32_bf16 v[122:125], v[158:161], v[198:201], v[122:125]
	v_mfma_f32_16x16x32_bf16 v[110:113], v[90:93], v[206:209], v[110:113]
	v_mfma_f32_16x16x32_bf16 v[106:109], v[158:161], v[206:209], v[106:109]
	v_mfma_f32_16x16x32_bf16 v[86:89], v[90:93], v[214:217], v[86:89]
	v_mfma_f32_16x16x32_bf16 v[78:81], v[158:161], v[214:217], v[78:81]
	s_setprio 0
	s_setprio 1
	v_mfma_f32_16x16x32_bf16 v[134:137], v[170:173], v[186:189], v[134:137]
	v_mfma_f32_16x16x32_bf16 v[130:133], v[178:181], v[186:189], v[130:133]
	v_mfma_f32_16x16x32_bf16 v[118:121], v[170:173], v[194:197], v[118:121]
	v_mfma_f32_16x16x32_bf16 v[114:117], v[178:181], v[194:197], v[114:117]
	v_mfma_f32_16x16x32_bf16 v[102:105], v[170:173], v[202:205], v[102:105]
	v_mfma_f32_16x16x32_bf16 v[98:101], v[178:181], v[202:205], v[98:101]
	v_mfma_f32_16x16x32_bf16 v[70:73], v[170:173], v[210:213], v[70:73]
	v_mfma_f32_16x16x32_bf16 v[66:69], v[178:181], v[210:213], v[66:69]
	v_mfma_f32_16x16x32_bf16 v[134:137], v[174:177], v[190:193], v[134:137]
	v_mfma_f32_16x16x32_bf16 v[130:133], v[182:185], v[190:193], v[130:133]
	v_mfma_f32_16x16x32_bf16 v[118:121], v[174:177], v[198:201], v[118:121]
	v_mfma_f32_16x16x32_bf16 v[114:117], v[182:185], v[198:201], v[114:117]
	v_mfma_f32_16x16x32_bf16 v[102:105], v[174:177], v[206:209], v[102:105]
	v_mfma_f32_16x16x32_bf16 v[98:101], v[182:185], v[206:209], v[98:101]
	v_mfma_f32_16x16x32_bf16 v[70:73], v[174:177], v[214:217], v[70:73]
	v_mfma_f32_16x16x32_bf16 v[66:69], v[182:185], v[214:217], v[66:69]
	s_setprio 0
	s_barrier
; #define PG8_STAGEA(bufoff, gbase, voff) PG8_STAGE_X(bufoff, gbase, voff, PG8_AUX_A)
; #define PG8_STAGEB(bufoff, gbase, voff) PG8_STAGE_X(bufoff, gbase, voff, PG8_AUX_B)
; #define PG8_LDA(dst, b, h) do { _Pragma("unroll") for (int m = 0; m < 4; ++m) _Pragma("unroll") for (int k = 0; k < 2; ++k) dst[m][k] = *(const PG8_LAS bf16x8*)(lds + PG8_SA(b, h) + aoff + m * 2048 + k * 1024); } while (0)
; #define PG8_MMA(ai, bj, At, Bt) do { __builtin_amdgcn_s_setprio(1); _Pragma("unroll") for (int m = 0; m < 4; ++m) _Pragma("unroll") for (int n = 0; n < 2; ++n) _Pragma("unroll") for (int k = 0; k < 2; ++k) \
;         acc[ai][bj][m][n] = __builtin_amdgcn_mfma_f32_16x16x32_bf16(Bt[n][k], At[m][k], acc[ai][bj][m][n], 0, 0, 0); __builtin_amdgcn_s_setprio(0); } while (0)
; #define PG8_WAIT_V(n) asm volatile("s_waitcnt vmcnt(" #n ")" ::: "memory")
; #define PG8_WAIT_L(n) asm volatile("s_waitcnt lgkmcnt(" #n ")" ::: "memory")
; #define PG8_BAR __builtin_amdgcn_s_barrier()
; #define PG8_SCHED __builtin_amdgcn_sched_barrier(0)
; template <class Epi, class Sched, bool ALIGN_EPI = false, bool SP2 = false>
; __device__ __forceinline__ void gemm_phase(PG8_LAS unsigned char* lds, const Gemm g, const Sched& S, const Epi& E) {
;     ...
;             PG8_WAIT_V(8); PG8_WAIT_L(0); PG8_BAR; PG8_MMA(0, 0, At, B0); PG8_MMA(0, 1, At, B1); PG8_BAR; PG8_SCHED;
;             PG8_LDA(At, 1, 1); PG8_STAGEB(PG8_SB(1, 0), b3, voffB); PG8_STAGEB(PG8_SB(1, 1), b3 + hstep, voffB); PG8_STAGEA(PG8_SA(1, 0), a3, voffA);
;             PG8_WAIT_V(8); PG8_WAIT_L(0); PG8_BAR; PG8_MMA(1, 0, At, B0); PG8_MMA(1, 1, At, B1); PG8_BAR; PG8_SCHED;
	s_mov_b32 m0, vcc_lo
	v_lshl_add_u64 v[162:163], v[162:163], 0, s[54:55]
	ds_read_b128 v[186:189], v168 offset:49152
	ds_read_b128 v[190:193], v168 offset:50176
	ds_read_b128 v[194:197], v168 offset:51200
	ds_read_b128 v[198:201], v168 offset:52224
	ds_read_b128 v[202:205], v168 offset:53248
	ds_read_b128 v[206:209], v168 offset:54272
	ds_read_b128 v[210:213], v168 offset:55296
	ds_read_b128 v[214:217], v168 offset:56320
	global_load_lds_dwordx4 v[162:163], off
	v_lshl_add_u64 v[162:163], v[218:219], 0, s[54:55]
	s_mov_b32 m0, s34
	s_nop 0
	global_load_lds_dwordx4 v[162:163], off
	v_lshl_add_u64 v[162:163], s[78:79], 0, v[146:147]
	s_mov_b32 m0, s35
	s_nop 0
	global_load_lds_dwordx4 v[162:163], off
	v_lshl_add_u64 v[162:163], s[78:79], 0, v[148:149]
	s_mov_b32 m0, s28
	s_nop 0
	global_load_lds_dwordx4 v[162:163], off
	v_lshl_add_u64 v[162:163], v[220:221], 0, s[54:55]
	s_mov_b32 m0, s90
	s_nop 0
	global_load_lds_dwordx4 v[162:163], off
	v_lshl_add_u64 v[162:163], v[222:223], 0, s[54:55]
	s_mov_b32 m0, s91
	s_nop 0
	global_load_lds_dwordx4 v[162:163], off
	s_waitcnt vmcnt(8)
	s_waitcnt lgkmcnt(0)
	s_barrier
	s_setprio 1
	s_waitcnt lgkmcnt(0)
	v_mfma_f32_16x16x32_bf16 v[62:65], v[82:85], v[186:189], v[62:65]
	v_mfma_f32_16x16x32_bf16 v[58:61], v[94:97], v[186:189], v[58:61]
	v_mfma_f32_16x16x32_bf16 v[46:49], v[82:85], v[194:197], v[46:49]
	v_mfma_f32_16x16x32_bf16 v[42:45], v[94:97], v[194:197], v[42:45]
	v_mfma_f32_16x16x32_bf16 v[30:33], v[82:85], v[202:205], v[30:33]
	v_mfma_f32_16x16x32_bf16 v[26:29], v[94:97], v[202:205], v[26:29]
	v_mfma_f32_16x16x32_bf16 v[14:17], v[82:85], v[210:213], v[14:17]
	v_mfma_f32_16x16x32_bf16 v[10:13], v[94:97], v[210:213], v[10:13]
	v_mfma_f32_16x16x32_bf16 v[62:65], v[90:93], v[190:193], v[62:65]
	v_mfma_f32_16x16x32_bf16 v[58:61], v[158:161], v[190:193], v[58:61]
	v_mfma_f32_16x16x32_bf16 v[46:49], v[90:93], v[198:201], v[46:49]
	v_mfma_f32_16x16x32_bf16 v[42:45], v[158:161], v[198:201], v[42:45]
	v_mfma_f32_16x16x32_bf16 v[30:33], v[90:93], v[206:209], v[30:33]
	v_mfma_f32_16x16x32_bf16 v[26:29], v[158:161], v[206:209], v[26:29]
	v_mfma_f32_16x16x32_bf16 v[14:17], v[90:93], v[214:217], v[14:17]
	v_mfma_f32_16x16x32_bf16 v[10:13], v[158:161], v[214:217], v[10:13]
	s_setprio 0
	s_setprio 1
	v_mfma_f32_16x16x32_bf16 v[54:57], v[170:173], v[186:189], v[54:57]
	v_mfma_f32_16x16x32_bf16 v[50:53], v[178:181], v[186:189], v[50:53]
	v_mfma_f32_16x16x32_bf16 v[38:41], v[170:173], v[194:197], v[38:41]
	v_mfma_f32_16x16x32_bf16 v[34:37], v[178:181], v[194:197], v[34:37]
	v_mfma_f32_16x16x32_bf16 v[22:25], v[170:173], v[202:205], v[22:25]
	v_mfma_f32_16x16x32_bf16 v[18:21], v[178:181], v[202:205], v[18:21]
	v_mfma_f32_16x16x32_bf16 v[6:9], v[170:173], v[210:213], v[6:9]
	v_mfma_f32_16x16x32_bf16 v[2:5], v[178:181], v[210:213], v[2:5]
	v_mfma_f32_16x16x32_bf16 v[54:57], v[174:177], v[190:193], v[54:57]
	v_mfma_f32_16x16x32_bf16 v[50:53], v[182:185], v[190:193], v[50:53]
	v_mfma_f32_16x16x32_bf16 v[38:41], v[174:177], v[198:201], v[38:41]
	v_mfma_f32_16x16x32_bf16 v[34:37], v[182:185], v[198:201], v[34:37]
	v_mfma_f32_16x16x32_bf16 v[22:25], v[174:177], v[206:209], v[22:25]
	v_mfma_f32_16x16x32_bf16 v[18:21], v[182:185], v[206:209], v[18:21]
	v_mfma_f32_16x16x32_bf16 v[6:9], v[174:177], v[214:217], v[6:9]
	v_mfma_f32_16x16x32_bf16 v[2:5], v[182:185], v[214:217], v[2:5]
	s_setprio 0
	s_barrier
	s_mov_b64 s[74:75], s[76:77]
	s_mov_b32 s96, s97
	s_cbranch_scc0 .LBB0_643
	s_and_b64 vcc, exec, s[56:57]
	s_cbranch_vccz .LBB0_646
	s_barrier

; #define PG8_STAGEA(bufoff, gbase, voff) PG8_STAGE_X(bufoff, gbase, voff, PG8_AUX_A)
; #define PG8_STAGEB(bufoff, gbase, voff) PG8_STAGE_X(bufoff, gbase, voff, PG8_AUX_B)
; #define PG8_LDA(dst, b, h) do { _Pragma("unroll") for (int m = 0; m < 4; ++m) _Pragma("unroll") for (int k = 0; k < 2; ++k) dst[m][k] = *(const PG8_LAS bf16x8*)(lds + PG8_SA(b, h) + aoff + m * 2048 + k * 1024); } while (0)
; #define PG8_LDB(dst, b, h) do { _Pragma("unroll") for (int n = 0; n < 2; ++n) _Pragma("unroll") for (int k = 0; k < 2; ++k) dst[n][k] = *(const PG8_LAS bf16x8*)(lds + PG8_SB(b, h) + boff + n * 2048 + k * 1024); } while (0)
; #define PG8_MMA(ai, bj, At, Bt) do { __builtin_amdgcn_s_setprio(1); _Pragma("unroll") for (int m = 0; m < 4; ++m) _Pragma("unroll") for (int n = 0; n < 2; ++n) _Pragma("unroll") for (int k = 0; k < 2; ++k) \
;         acc[ai][bj][m][n] = __builtin_amdgcn_mfma_f32_16x16x32_bf16(Bt[n][k], At[m][k], acc[ai][bj][m][n], 0, 0, 0); __builtin_amdgcn_s_setprio(0); } while (0)
; template <class Epi, class Sched, bool ALIGN_EPI = false, bool SP2 = false>
; __device__ __forceinline__ void gemm_phase(PG8_LAS unsigned char* lds, const Gemm g, const Sched& S, const Epi& E) {
;     ...
;         for (int t = 0; t < nt; t += 2) {
;             const bool last = (t == nt - 2);
;             if constexpr (HasMid<Epi>::value) { if (t == ns) E.mid(acc, cur, wr, wc, fr, fq); }
;             const char* sA1 = (t + 1 >= ns) ? cA2 : cA; const char* sA2 = (t + 2 >= ns) ? cA2 : cA; const char* sB2 = (t + 2 >= ns) ? cB2 : cB;
;             const char* a1 = sA1 + (size_t)(t + 1) * kstep;
;             const char* a2 = last ? nA : sA2 + (size_t)(t + 2) * kstep; const char* b2 = last ? nB : sB2 + (size_t)(t + 2) * kstep;
;             const char* a3 = a2 + kstep; const char* b3 = b2 + kstep;
;             if (last && has_next) S.a_ready(nxt);
;             if constexpr (SP2) {
;             PG8_LDB(B0, 0, 0); PG8_LDB(B1, 0, 1); PG8_SCHED; PG8_LDA(At, 0, 0); PG8_STAGEA(PG8_SA(1, 1), a1 + hstep, voffA);
;             PG8_WAIT_V(8); PG8_WAIT_L(0); PG8_BAR; PG8_MMA(0, 0, At, B0); PG8_MMA(0, 1, At, B1); PG8_BAR; PG8_SCHED;
;             PG8_LDA(At, 0, 1); PG8_STAGEB(PG8_SB(0, 0), b2, voffB); PG8_STAGEB(PG8_SB(0, 1), b2 + hstep, voffB); PG8_STAGEA(PG8_SA(0, 0), a2, voffA);
;             PG8_WAIT_V(8); PG8_WAIT_L(0); PG8_BAR; PG8_MMA(1, 0, At, B0); PG8_MMA(1, 1, At, B1); PG8_BAR; PG8_SCHED;
.LBB0_734:
	ds_read_b128 v[150:153], v156
	ds_read_b128 v[162:165], v156 offset:1024
	ds_read_b128 v[166:169], v156 offset:2048
	ds_read_b128 v[170:173], v156 offset:3072
	ds_read_b128 v[174:177], v157
	ds_read_b128 v[178:181], v157 offset:1024
	ds_read_b128 v[182:185], v157 offset:2048
	ds_read_b128 v[186:189], v157 offset:3072
	ds_read_b128 v[190:193], v158
	ds_read_b128 v[194:197], v158 offset:1024
	ds_read_b128 v[198:201], v158 offset:2048
	ds_read_b128 v[202:205], v158 offset:3072
	ds_read_b128 v[206:209], v158 offset:4096
	ds_read_b128 v[210:213], v158 offset:5120
	ds_read_b128 v[214:217], v158 offset:6144
	ds_read_b128 v[218:221], v158 offset:7168
	s_add_i32 s90, s74, 2
	s_cmp_gt_u32 s90, 29
	s_cselect_b64 s[34:35], -1, 0
	s_and_b64 vcc, s[34:35], exec
	s_cselect_b32 s29, s50, s70
	s_cselect_b32 s24, s47, s69
	s_cselect_b32 s25, s46, s68
	s_cselect_b32 s28, s51, s71
	s_add_u32 s29, s29, s72
	s_addc_u32 s28, s28, s73
	s_add_u32 s29, s29, 0xfff80080
	s_addc_u32 s28, s28, -1
	s_add_u32 s25, s25, s72
	s_addc_u32 s24, s24, s73
	s_add_u32 s25, s25, 0xfff80080
	s_addc_u32 s24, s24, -1
	s_cmp_eq_u32 s74, 28
	s_cselect_b32 s74, s87, s25
	s_cselect_b32 s77, s63, s28
	s_cselect_b32 s76, s86, s29
	s_cselect_b32 s75, s61, s24
	v_lshl_add_u64 v[222:223], v[146:147], 0, s[72:73]
	s_add_i32 m0, s21, 0xc000
	global_load_lds_dwordx4 v[222:223], off
	v_lshl_add_u64 v[222:223], v[148:149], 0, s[72:73]
	s_add_i32 m0, s21, 0xe000
	s_nop 0
	global_load_lds_dwordx4 v[222:223], off
	s_waitcnt vmcnt(8)
	s_waitcnt lgkmcnt(0)
	s_barrier
	s_setprio 1
	s_waitcnt lgkmcnt(0)
	v_mfma_f32_16x16x32_bf16 v[126:129], v[150:153], v[190:193], v[126:129]
	v_mfma_f32_16x16x32_bf16 v[122:125], v[166:169], v[190:193], v[122:125]
	v_mfma_f32_16x16x32_bf16 v[110:113], v[150:153], v[198:201], v[110:113]
	v_mfma_f32_16x16x32_bf16 v[106:109], v[166:169], v[198:201], v[106:109]
	v_mfma_f32_16x16x32_bf16 v[94:97], v[150:153], v[206:209], v[94:97]
	v_mfma_f32_16x16x32_bf16 v[90:93], v[166:169], v[206:209], v[90:93]
	v_mfma_f32_16x16x32_bf16 v[78:81], v[150:153], v[214:217], v[78:81]
	v_mfma_f32_16x16x32_bf16 v[74:77], v[166:169], v[214:217], v[74:77]
	v_mfma_f32_16x16x32_bf16 v[126:129], v[162:165], v[194:197], v[126:129]
	v_mfma_f32_16x16x32_bf16 v[122:125], v[170:173], v[194:197], v[122:125]
	v_mfma_f32_16x16x32_bf16 v[110:113], v[162:165], v[202:205], v[110:113]
	v_mfma_f32_16x16x32_bf16 v[106:109], v[170:173], v[202:205], v[106:109]
	v_mfma_f32_16x16x32_bf16 v[94:97], v[162:165], v[210:213], v[94:97]
	v_mfma_f32_16x16x32_bf16 v[90:93], v[170:173], v[210:213], v[90:93]
	v_mfma_f32_16x16x32_bf16 v[78:81], v[162:165], v[218:221], v[78:81]
	v_mfma_f32_16x16x32_bf16 v[74:77], v[170:173], v[218:221], v[74:77]
	s_setprio 0
	s_setprio 1
	v_mfma_f32_16x16x32_bf16 v[118:121], v[174:177], v[190:193], v[118:121]
	v_mfma_f32_16x16x32_bf16 v[114:117], v[182:185], v[190:193], v[114:117]
	v_mfma_f32_16x16x32_bf16 v[102:105], v[174:177], v[198:201], v[102:105]
	v_mfma_f32_16x16x32_bf16 v[98:101], v[182:185], v[198:201], v[98:101]
	v_mfma_f32_16x16x32_bf16 v[86:89], v[174:177], v[206:209], v[86:89]
	v_mfma_f32_16x16x32_bf16 v[82:85], v[182:185], v[206:209], v[82:85]
	v_mfma_f32_16x16x32_bf16 v[70:73], v[174:177], v[214:217], v[70:73]
	v_mfma_f32_16x16x32_bf16 v[66:69], v[182:185], v[214:217], v[66:69]
	v_mfma_f32_16x16x32_bf16 v[118:121], v[178:181], v[194:197], v[118:121]
	v_mfma_f32_16x16x32_bf16 v[114:117], v[186:189], v[194:197], v[114:117]
	v_mfma_f32_16x16x32_bf16 v[102:105], v[178:181], v[202:205], v[102:105]
	v_mfma_f32_16x16x32_bf16 v[98:101], v[186:189], v[202:205], v[98:101]
	v_mfma_f32_16x16x32_bf16 v[86:89], v[178:181], v[210:213], v[86:89]
	v_mfma_f32_16x16x32_bf16 v[82:85], v[186:189], v[210:213], v[82:85]
	v_mfma_f32_16x16x32_bf16 v[70:73], v[178:181], v[218:221], v[70:73]
	v_mfma_f32_16x16x32_bf16 v[66:69], v[186:189], v[218:221], v[66:69]
	s_setprio 0
	s_barrier
	s_add_i32 s24, s81, s9
	v_lshl_add_u64 v[222:223], s[74:75], 0, v[134:135]
	s_mov_b32 m0, s24
	ds_read_b128 v[190:193], v158 offset:16384
	ds_read_b128 v[194:197], v158 offset:17408
	ds_read_b128 v[198:201], v158 offset:18432
	ds_read_b128 v[202:205], v158 offset:19456
	ds_read_b128 v[206:209], v158 offset:20480
	ds_read_b128 v[210:213], v158 offset:21504
	ds_read_b128 v[214:217], v158 offset:22528
	ds_read_b128 v[218:221], v158 offset:23552
	global_load_lds_dwordx4 v[222:223], off
	s_add_i32 m0, s24, 0x2000
	s_add_u32 s34, s74, 0x80000
	v_lshl_add_u64 v[224:225], s[74:75], 0, v[130:131]
	s_addc_u32 s35, s75, 0
	s_add_i32 s24, s82, s9
	global_load_lds_dwordx4 v[224:225], off
	v_lshl_add_u64 v[226:227], s[34:35], 0, v[134:135]
	s_mov_b32 m0, s24
	v_lshl_add_u64 v[228:229], s[76:77], 0, v[132:133]
	global_load_lds_dwordx4 v[226:227], off
	v_lshl_add_u64 v[226:227], s[34:35], 0, v[130:131]
	s_add_i32 m0, s24, 0x2000
	s_nop 0
	global_load_lds_dwordx4 v[226:227], off
	v_lshl_add_u64 v[226:227], s[76:77], 0, v[136:137]
	s_mov_b32 m0, s21
	s_nop 0
	global_load_lds_dwordx4 v[226:227], off
	s_mov_b32 m0, s23
	s_nop 0
	global_load_lds_dwordx4 v[228:229], off
	s_waitcnt vmcnt(8)
	s_waitcnt lgkmcnt(0)
	s_barrier
; #define PG8_STAGEA(bufoff, gbase, voff) PG8_STAGE_X(bufoff, gbase, voff, PG8_AUX_A)
; #define PG8_STAGEB(bufoff, gbase, voff) PG8_STAGE_X(bufoff, gbase, voff, PG8_AUX_B)
; #define PG8_LDA(dst, b, h) do { _Pragma("unroll") for (int m = 0; m < 4; ++m) _Pragma("unroll") for (int k = 0; k < 2; ++k) dst[m][k] = *(const PG8_LAS bf16x8*)(lds + PG8_SA(b, h) + aoff + m * 2048 + k * 1024); } while (0)
; #define PG8_LDB(dst, b, h) do { _Pragma("unroll") for (int n = 0; n < 2; ++n) _Pragma("unroll") for (int k = 0; k < 2; ++k) dst[n][k] = *(const PG8_LAS bf16x8*)(lds + PG8_SB(b, h) + boff + n * 2048 + k * 1024); } while (0)
; #define PG8_MMA(ai, bj, At, Bt) do { __builtin_amdgcn_s_setprio(1); _Pragma("unroll") for (int m = 0; m < 4; ++m) _Pragma("unroll") for (int n = 0; n < 2; ++n) _Pragma("unroll") for (int k = 0; k < 2; ++k) \
;         acc[ai][bj][m][n] = __builtin_amdgcn_mfma_f32_16x16x32_bf16(Bt[n][k], At[m][k], acc[ai][bj][m][n], 0, 0, 0); __builtin_amdgcn_s_setprio(0); } while (0)
; #define PG8_WAIT_V(n) asm volatile("s_waitcnt vmcnt(" #n ")" ::: "memory")
; #define PG8_WAIT_L(n) asm volatile("s_waitcnt lgkmcnt(" #n ")" ::: "memory")
; #define PG8_BAR __builtin_amdgcn_s_barrier()
; #define PG8_SCHED __builtin_amdgcn_sched_barrier(0)
; template <class Epi, class Sched, bool ALIGN_EPI = false, bool SP2 = false>
; __device__ __forceinline__ void gemm_phase(PG8_LAS unsigned char* lds, const Gemm g, const Sched& S, const Epi& E) {
;     ...
;             PG8_WAIT_V(8); PG8_WAIT_L(0); PG8_BAR; PG8_MMA(0, 0, At, B0); PG8_MMA(0, 1, At, B1); PG8_BAR; PG8_SCHED;
;             PG8_LDA(At, 0, 1); PG8_STAGEB(PG8_SB(0, 0), b2, voffB); PG8_STAGEB(PG8_SB(0, 1), b2 + hstep, voffB); PG8_STAGEA(PG8_SA(0, 0), a2, voffA);
;             PG8_WAIT_V(8); PG8_WAIT_L(0); PG8_BAR; PG8_MMA(1, 0, At, B0); PG8_MMA(1, 1, At, B1); PG8_BAR; PG8_SCHED;
;             PG8_LDB(B0, 1, 0); PG8_LDB(B1, 1, 1); PG8_SCHED; PG8_LDA(At, 1, 0); PG8_STAGEA(PG8_SA(0, 1), a2 + hstep, voffA);
;             PG8_WAIT_V(8); PG8_WAIT_L(0); PG8_BAR; PG8_MMA(0, 0, At, B0); PG8_MMA(0, 1, At, B1); PG8_BAR; PG8_SCHED;
	s_setprio 1
	s_waitcnt lgkmcnt(0)
	v_mfma_f32_16x16x32_bf16 v[62:65], v[150:153], v[190:193], v[62:65]
	v_mfma_f32_16x16x32_bf16 v[58:61], v[166:169], v[190:193], v[58:61]
	v_mfma_f32_16x16x32_bf16 v[46:49], v[150:153], v[198:201], v[46:49]
	v_mfma_f32_16x16x32_bf16 v[42:45], v[166:169], v[198:201], v[42:45]
	v_mfma_f32_16x16x32_bf16 v[30:33], v[150:153], v[206:209], v[30:33]
	v_mfma_f32_16x16x32_bf16 v[26:29], v[166:169], v[206:209], v[26:29]
	v_mfma_f32_16x16x32_bf16 v[14:17], v[150:153], v[214:217], v[14:17]
	v_mfma_f32_16x16x32_bf16 v[10:13], v[166:169], v[214:217], v[10:13]
	v_mfma_f32_16x16x32_bf16 v[62:65], v[162:165], v[194:197], v[62:65]
	v_mfma_f32_16x16x32_bf16 v[58:61], v[170:173], v[194:197], v[58:61]
	v_mfma_f32_16x16x32_bf16 v[46:49], v[162:165], v[202:205], v[46:49]
	v_mfma_f32_16x16x32_bf16 v[42:45], v[170:173], v[202:205], v[42:45]
	v_mfma_f32_16x16x32_bf16 v[30:33], v[162:165], v[210:213], v[30:33]
	v_mfma_f32_16x16x32_bf16 v[26:29], v[170:173], v[210:213], v[26:29]
	v_mfma_f32_16x16x32_bf16 v[14:17], v[162:165], v[218:221], v[14:17]
	v_mfma_f32_16x16x32_bf16 v[10:13], v[170:173], v[218:221], v[10:13]
	s_setprio 0
	s_setprio 1
	v_mfma_f32_16x16x32_bf16 v[54:57], v[174:177], v[190:193], v[54:57]
	v_mfma_f32_16x16x32_bf16 v[50:53], v[182:185], v[190:193], v[50:53]
	v_mfma_f32_16x16x32_bf16 v[38:41], v[174:177], v[198:201], v[38:41]
	v_mfma_f32_16x16x32_bf16 v[34:37], v[182:185], v[198:201], v[34:37]
	v_mfma_f32_16x16x32_bf16 v[22:25], v[174:177], v[206:209], v[22:25]
	v_mfma_f32_16x16x32_bf16 v[18:21], v[182:185], v[206:209], v[18:21]
	v_mfma_f32_16x16x32_bf16 v[6:9], v[174:177], v[214:217], v[6:9]
	v_mfma_f32_16x16x32_bf16 v[2:5], v[182:185], v[214:217], v[2:5]
	v_mfma_f32_16x16x32_bf16 v[54:57], v[178:181], v[194:197], v[54:57]
	v_mfma_f32_16x16x32_bf16 v[50:53], v[186:189], v[194:197], v[50:53]
	v_mfma_f32_16x16x32_bf16 v[38:41], v[178:181], v[202:205], v[38:41]
	v_mfma_f32_16x16x32_bf16 v[34:37], v[186:189], v[202:205], v[34:37]
	v_mfma_f32_16x16x32_bf16 v[22:25], v[178:181], v[210:213], v[22:25]
	v_mfma_f32_16x16x32_bf16 v[18:21], v[186:189], v[210:213], v[18:21]
	v_mfma_f32_16x16x32_bf16 v[6:9], v[178:181], v[218:221], v[6:9]
	v_mfma_f32_16x16x32_bf16 v[2:5], v[186:189], v[218:221], v[2:5]
	s_setprio 0
	s_barrier
	s_add_i32 s24, 0, 0x18000
	v_add_u32_e32 v161, s24, v154
	s_add_i32 s25, 0, 0x1c000
	ds_read_b128 v[150:153], v161
	ds_read_b128 v[162:165], v161 offset:1024
	ds_read_b128 v[166:169], v161 offset:2048
	ds_read_b128 v[170:173], v161 offset:3072
	v_add_u32_e32 v161, s25, v154
	ds_read_b128 v[174:177], v161
	ds_read_b128 v[178:181], v161 offset:1024
	ds_read_b128 v[182:185], v161 offset:2048
	ds_read_b128 v[186:189], v161 offset:3072
	s_add_u32 s34, s76, 0x80000
	s_addc_u32 s35, s77, 0
	s_mov_b32 m0, s26
	v_lshl_add_u64 v[230:231], s[34:35], 0, v[136:137]
	ds_read_b128 v[190:193], v158 offset:32768
	ds_read_b128 v[194:197], v158 offset:33792
	ds_read_b128 v[198:201], v158 offset:34816
	ds_read_b128 v[202:205], v158 offset:35840
	ds_read_b128 v[206:209], v158 offset:36864
	ds_read_b128 v[210:213], v158 offset:37888
	ds_read_b128 v[214:217], v158 offset:38912
	ds_read_b128 v[218:221], v158 offset:39936
	global_load_lds_dwordx4 v[230:231], off
	v_lshl_add_u64 v[230:231], s[34:35], 0, v[132:133]
	s_mov_b32 m0, s27
	s_nop 0
	global_load_lds_dwordx4 v[230:231], off
	s_waitcnt vmcnt(8)
	s_waitcnt lgkmcnt(0)
	s_barrier
	s_setprio 1
	s_waitcnt lgkmcnt(0)
	v_mfma_f32_16x16x32_bf16 v[126:129], v[150:153], v[190:193], v[126:129]
	v_mfma_f32_16x16x32_bf16 v[122:125], v[166:169], v[190:193], v[122:125]
	v_mfma_f32_16x16x32_bf16 v[110:113], v[150:153], v[198:201], v[110:113]
	v_mfma_f32_16x16x32_bf16 v[106:109], v[166:169], v[198:201], v[106:109]
	v_mfma_f32_16x16x32_bf16 v[94:97], v[150:153], v[206:209], v[94:97]
	v_mfma_f32_16x16x32_bf16 v[90:93], v[166:169], v[206:209], v[90:93]
	v_mfma_f32_16x16x32_bf16 v[78:81], v[150:153], v[214:217], v[78:81]
	v_mfma_f32_16x16x32_bf16 v[74:77], v[166:169], v[214:217], v[74:77]
	v_mfma_f32_16x16x32_bf16 v[126:129], v[162:165], v[194:197], v[126:129]
	v_mfma_f32_16x16x32_bf16 v[122:125], v[170:173], v[194:197], v[122:125]
	v_mfma_f32_16x16x32_bf16 v[110:113], v[162:165], v[202:205], v[110:113]
	v_mfma_f32_16x16x32_bf16 v[106:109], v[170:173], v[202:205], v[106:109]
	v_mfma_f32_16x16x32_bf16 v[94:97], v[162:165], v[210:213], v[94:97]
	v_mfma_f32_16x16x32_bf16 v[90:93], v[170:173], v[210:213], v[90:93]
	v_mfma_f32_16x16x32_bf16 v[78:81], v[162:165], v[218:221], v[78:81]
	v_mfma_f32_16x16x32_bf16 v[74:77], v[170:173], v[218:221], v[74:77]
	s_setprio 0
	s_setprio 1
	v_mfma_f32_16x16x32_bf16 v[118:121], v[174:177], v[190:193], v[118:121]
	v_mfma_f32_16x16x32_bf16 v[114:117], v[182:185], v[190:193], v[114:117]
	v_mfma_f32_16x16x32_bf16 v[102:105], v[174:177], v[198:201], v[102:105]
	v_mfma_f32_16x16x32_bf16 v[98:101], v[182:185], v[198:201], v[98:101]
	v_mfma_f32_16x16x32_bf16 v[86:89], v[174:177], v[206:209], v[86:89]
	v_mfma_f32_16x16x32_bf16 v[82:85], v[182:185], v[206:209], v[82:85]
	v_mfma_f32_16x16x32_bf16 v[70:73], v[174:177], v[214:217], v[70:73]
	v_mfma_f32_16x16x32_bf16 v[66:69], v[182:185], v[214:217], v[66:69]
	v_mfma_f32_16x16x32_bf16 v[118:121], v[178:181], v[194:197], v[118:121]
	v_mfma_f32_16x16x32_bf16 v[114:117], v[186:189], v[194:197], v[114:117]
	v_mfma_f32_16x16x32_bf16 v[102:105], v[178:181], v[202:205], v[102:105]
	v_mfma_f32_16x16x32_bf16 v[98:101], v[186:189], v[202:205], v[98:101]
	v_mfma_f32_16x16x32_bf16 v[86:89], v[178:181], v[210:213], v[86:89]
	v_mfma_f32_16x16x32_bf16 v[82:85], v[186:189], v[210:213], v[82:85]
	v_mfma_f32_16x16x32_bf16 v[70:73], v[178:181], v[218:221], v[70:73]
	v_mfma_f32_16x16x32_bf16 v[66:69], v[186:189], v[218:221], v[66:69]
	s_setprio 0
	s_barrier
; #define PG8_STAGEA(bufoff, gbase, voff) PG8_STAGE_X(bufoff, gbase, voff, PG8_AUX_A)
; #define PG8_STAGEB(bufoff, gbase, voff) PG8_STAGE_X(bufoff, gbase, voff, PG8_AUX_B)
; #define PG8_LDA(dst, b, h) do { _Pragma("unroll") for (int m = 0; m < 4; ++m) _Pragma("unroll") for (int k = 0; k < 2; ++k) dst[m][k] = *(const PG8_LAS bf16x8*)(lds + PG8_SA(b, h) + aoff + m * 2048 + k * 1024); } while (0)
; #define PG8_MMA(ai, bj, At, Bt) do { __builtin_amdgcn_s_setprio(1); _Pragma("unroll") for (int m = 0; m < 4; ++m) _Pragma("unroll") for (int n = 0; n < 2; ++n) _Pragma("unroll") for (int k = 0; k < 2; ++k) \
;         acc[ai][bj][m][n] = __builtin_amdgcn_mfma_f32_16x16x32_bf16(Bt[n][k], At[m][k], acc[ai][bj][m][n], 0, 0, 0); __builtin_amdgcn_s_setprio(0); } while (0)
; #define PG8_WAIT_V(n) asm volatile("s_waitcnt vmcnt(" #n ")" ::: "memory")
; #define PG8_WAIT_L(n) asm volatile("s_waitcnt lgkmcnt(" #n ")" ::: "memory")
; #define PG8_BAR __builtin_amdgcn_s_barrier()
; #define PG8_SCHED __builtin_amdgcn_sched_barrier(0)
; template <class Epi, class Sched, bool ALIGN_EPI = false, bool SP2 = false>
; __device__ __forceinline__ void gemm_phase(PG8_LAS unsigned char* lds, const Gemm g, const Sched& S, const Epi& E) {
;     ...
;             PG8_WAIT_V(8); PG8_WAIT_L(0); PG8_BAR; PG8_MMA(0, 0, At, B0); PG8_MMA(0, 1, At, B1); PG8_BAR; PG8_SCHED;
;             PG8_LDA(At, 1, 1); PG8_STAGEB(PG8_SB(1, 0), b3, voffB); PG8_STAGEB(PG8_SB(1, 1), b3 + hstep, voffB); PG8_STAGEA(PG8_SA(1, 0), a3, voffA);
;             PG8_WAIT_V(8); PG8_WAIT_L(0); PG8_BAR; PG8_MMA(1, 0, At, B0); PG8_MMA(1, 1, At, B1); PG8_BAR; PG8_SCHED;
	s_add_i32 s24, s24, s9
	v_lshl_add_u64 v[222:223], v[222:223], 0, s[54:55]
	s_mov_b32 m0, s24
	ds_read_b128 v[190:193], v158 offset:49152
	ds_read_b128 v[194:197], v158 offset:50176
	ds_read_b128 v[198:201], v158 offset:51200
	ds_read_b128 v[202:205], v158 offset:52224
	ds_read_b128 v[206:209], v158 offset:53248
	ds_read_b128 v[210:213], v158 offset:54272
	ds_read_b128 v[214:217], v158 offset:55296
	ds_read_b128 v[218:221], v158 offset:56320
	global_load_lds_dwordx4 v[222:223], off
	s_add_i32 m0, s24, 0x2000
	s_add_u32 s34, s74, 0x80080
	v_lshl_add_u64 v[222:223], v[224:225], 0, s[54:55]
	s_addc_u32 s35, s75, 0
	s_add_i32 s24, s25, s9
	global_load_lds_dwordx4 v[222:223], off
	v_lshl_add_u64 v[222:223], s[34:35], 0, v[134:135]
	s_mov_b32 m0, s24
	s_nop 0
	global_load_lds_dwordx4 v[222:223], off
	v_lshl_add_u64 v[222:223], s[34:35], 0, v[130:131]
	s_add_i32 m0, s24, 0x2000
	s_nop 0
	global_load_lds_dwordx4 v[222:223], off
	v_lshl_add_u64 v[222:223], v[226:227], 0, s[54:55]
	s_mov_b32 m0, s79
	s_nop 0
	global_load_lds_dwordx4 v[222:223], off
	v_lshl_add_u64 v[222:223], v[228:229], 0, s[54:55]
	s_mov_b32 m0, s80
	s_nop 0
	global_load_lds_dwordx4 v[222:223], off
	s_waitcnt vmcnt(8)
	s_waitcnt lgkmcnt(0)
	s_barrier
	s_setprio 1
	s_waitcnt lgkmcnt(0)
	v_mfma_f32_16x16x32_bf16 v[62:65], v[150:153], v[190:193], v[62:65]
	v_mfma_f32_16x16x32_bf16 v[58:61], v[166:169], v[190:193], v[58:61]
	v_mfma_f32_16x16x32_bf16 v[46:49], v[150:153], v[198:201], v[46:49]
	v_mfma_f32_16x16x32_bf16 v[42:45], v[166:169], v[198:201], v[42:45]
	v_mfma_f32_16x16x32_bf16 v[30:33], v[150:153], v[206:209], v[30:33]
	v_mfma_f32_16x16x32_bf16 v[26:29], v[166:169], v[206:209], v[26:29]
	v_mfma_f32_16x16x32_bf16 v[14:17], v[150:153], v[214:217], v[14:17]
	v_mfma_f32_16x16x32_bf16 v[10:13], v[166:169], v[214:217], v[10:13]
	v_mfma_f32_16x16x32_bf16 v[62:65], v[162:165], v[194:197], v[62:65]
	v_mfma_f32_16x16x32_bf16 v[58:61], v[170:173], v[194:197], v[58:61]
	v_mfma_f32_16x16x32_bf16 v[46:49], v[162:165], v[202:205], v[46:49]
	v_mfma_f32_16x16x32_bf16 v[42:45], v[170:173], v[202:205], v[42:45]
	v_mfma_f32_16x16x32_bf16 v[30:33], v[162:165], v[210:213], v[30:33]
	v_mfma_f32_16x16x32_bf16 v[26:29], v[170:173], v[210:213], v[26:29]
	v_mfma_f32_16x16x32_bf16 v[14:17], v[162:165], v[218:221], v[14:17]
	v_mfma_f32_16x16x32_bf16 v[10:13], v[170:173], v[218:221], v[10:13]
	s_setprio 0
	s_setprio 1
	v_mfma_f32_16x16x32_bf16 v[54:57], v[174:177], v[190:193], v[54:57]
	v_mfma_f32_16x16x32_bf16 v[50:53], v[182:185], v[190:193], v[50:53]
	v_mfma_f32_16x16x32_bf16 v[38:41], v[174:177], v[198:201], v[38:41]
	v_mfma_f32_16x16x32_bf16 v[34:37], v[182:185], v[198:201], v[34:37]
	v_mfma_f32_16x16x32_bf16 v[22:25], v[174:177], v[206:209], v[22:25]
	v_mfma_f32_16x16x32_bf16 v[18:21], v[182:185], v[206:209], v[18:21]
	v_mfma_f32_16x16x32_bf16 v[6:9], v[174:177], v[214:217], v[6:9]
	v_mfma_f32_16x16x32_bf16 v[2:5], v[182:185], v[214:217], v[2:5]
	v_mfma_f32_16x16x32_bf16 v[54:57], v[178:181], v[194:197], v[54:57]
	v_mfma_f32_16x16x32_bf16 v[50:53], v[186:189], v[194:197], v[50:53]
	v_mfma_f32_16x16x32_bf16 v[38:41], v[178:181], v[202:205], v[38:41]
	v_mfma_f32_16x16x32_bf16 v[34:37], v[186:189], v[202:205], v[34:37]
	v_mfma_f32_16x16x32_bf16 v[22:25], v[178:181], v[210:213], v[22:25]
	v_mfma_f32_16x16x32_bf16 v[18:21], v[186:189], v[210:213], v[18:21]
	v_mfma_f32_16x16x32_bf16 v[6:9], v[178:181], v[218:221], v[6:9]
	v_mfma_f32_16x16x32_bf16 v[2:5], v[186:189], v[218:221], v[2:5]
	s_setprio 0
	s_barrier
	s_add_u32 s72, s72, 0x100
	s_addc_u32 s73, s73, 0
	s_mov_b32 s74, s90
	s_cbranch_vccz .LBB0_734
	s_and_b64 vcc, exec, s[56:57]
	s_cbranch_vccz .LBB0_737
	s_barrier

; #define PG8_STAGEA(bufoff, gbase, voff) PG8_STAGE_X(bufoff, gbase, voff, PG8_AUX_A)
; #define PG8_STAGEB(bufoff, gbase, voff) PG8_STAGE_X(bufoff, gbase, voff, PG8_AUX_B)
; #define PG8_LDA(dst, b, h) do { _Pragma("unroll") for (int m = 0; m < 4; ++m) _Pragma("unroll") for (int k = 0; k < 2; ++k) dst[m][k] = *(const PG8_LAS bf16x8*)(lds + PG8_SA(b, h) + aoff + m * 2048 + k * 1024); } while (0)
; #define PG8_LDB(dst, b, h) do { _Pragma("unroll") for (int n = 0; n < 2; ++n) _Pragma("unroll") for (int k = 0; k < 2; ++k) dst[n][k] = *(const PG8_LAS bf16x8*)(lds + PG8_SB(b, h) + boff + n * 2048 + k * 1024); } while (0)
; #define PG8_MMA(ai, bj, At, Bt) do { __builtin_amdgcn_s_setprio(1); _Pragma("unroll") for (int m = 0; m < 4; ++m) _Pragma("unroll") for (int n = 0; n < 2; ++n) _Pragma("unroll") for (int k = 0; k < 2; ++k) \
;         acc[ai][bj][m][n] = __builtin_amdgcn_mfma_f32_16x16x32_bf16(Bt[n][k], At[m][k], acc[ai][bj][m][n], 0, 0, 0); __builtin_amdgcn_s_setprio(0); } while (0)
; template <class Epi, class Sched, bool ALIGN_EPI = false, bool SP2 = false>
; __device__ __forceinline__ void gemm_phase(PG8_LAS unsigned char* lds, const Gemm g, const Sched& S, const Epi& E) {
;     ...
;         for (int t = 0; t < nt; t += 2) {
;             const bool last = (t == nt - 2);
;             if constexpr (HasMid<Epi>::value) { if (t == ns) E.mid(acc, cur, wr, wc, fr, fq); }
;             const char* sA1 = (t + 1 >= ns) ? cA2 : cA; const char* sA2 = (t + 2 >= ns) ? cA2 : cA; const char* sB2 = (t + 2 >= ns) ? cB2 : cB;
;             const char* a1 = sA1 + (size_t)(t + 1) * kstep;
;             const char* a2 = last ? nA : sA2 + (size_t)(t + 2) * kstep; const char* b2 = last ? nB : sB2 + (size_t)(t + 2) * kstep;
;             const char* a3 = a2 + kstep; const char* b3 = b2 + kstep;
;             if (last && has_next) S.a_ready(nxt);
;             if constexpr (SP2) {
;             PG8_LDB(B0, 0, 0); PG8_LDB(B1, 0, 1); PG8_SCHED; PG8_LDA(At, 0, 0); PG8_STAGEA(PG8_SA(1, 1), a1 + hstep, voffA);
;             PG8_WAIT_V(8); PG8_WAIT_L(0); PG8_BAR; PG8_MMA(0, 0, At, B0); PG8_MMA(0, 1, At, B1); PG8_BAR; PG8_SCHED;
;             PG8_LDA(At, 0, 1); PG8_STAGEB(PG8_SB(0, 0), b2, voffB); PG8_STAGEB(PG8_SB(0, 1), b2 + hstep, voffB); PG8_STAGEA(PG8_SA(0, 0), a2, voffA);
;             PG8_WAIT_V(8); PG8_WAIT_L(0); PG8_BAR; PG8_MMA(1, 0, At, B0); PG8_MMA(1, 1, At, B1); PG8_BAR; PG8_SCHED;
.LBB0_750:
	ds_read_b128 v[152:155], v148
	ds_read_b128 v[156:159], v148 offset:1024
	ds_read_b128 v[160:163], v148 offset:2048
	ds_read_b128 v[164:167], v148 offset:3072
	ds_read_b128 v[168:171], v149
	ds_read_b128 v[172:175], v149 offset:1024
	ds_read_b128 v[176:179], v149 offset:2048
	ds_read_b128 v[180:183], v149 offset:3072
	ds_read_b128 v[184:187], v150
	ds_read_b128 v[188:191], v150 offset:1024
	ds_read_b128 v[192:195], v150 offset:2048
	ds_read_b128 v[196:199], v150 offset:3072
	ds_read_b128 v[200:203], v150 offset:4096
	ds_read_b128 v[204:207], v150 offset:5120
	ds_read_b128 v[208:211], v150 offset:6144
	ds_read_b128 v[212:215], v150 offset:7168
	s_add_i32 s91, s70, 2
	s_cmp_gt_u32 s91, 29
	s_cselect_b64 s[34:35], -1, 0
	s_and_b64 vcc, s[34:35], exec
	s_cselect_b32 s29, s4, s66
	s_cselect_b32 s24, s3, s65
	s_cselect_b32 s25, s2, s64
	s_cselect_b32 s28, s5, s67
	s_add_u32 s29, s29, s68
	s_addc_u32 s28, s28, s69
	s_add_u32 s29, s29, 0xfff80080
	s_addc_u32 s28, s28, -1
	s_add_u32 s25, s25, s68
	s_addc_u32 s24, s24, s69
	s_add_u32 s25, s25, 0xfff80080
	s_addc_u32 s24, s24, -1
	s_cmp_eq_u32 s70, 28
	s_cselect_b32 s70, s90, s25
	s_cselect_b32 s73, s55, s28
	s_cselect_b32 s72, s87, s29
	s_cselect_b32 s71, s53, s24
	v_lshl_add_u64 v[216:217], v[142:143], 0, s[68:69]
	s_add_i32 m0, s63, 0xc000
	global_load_lds_dwordx4 v[216:217], off
	v_lshl_add_u64 v[216:217], v[144:145], 0, s[68:69]
	s_add_i32 m0, s63, 0xe000
	s_nop 0
	global_load_lds_dwordx4 v[216:217], off
	s_waitcnt vmcnt(8)
	s_waitcnt lgkmcnt(0)
	s_barrier
	s_setprio 1
	s_waitcnt lgkmcnt(0)
	v_mfma_f32_16x16x32_bf16 v[126:129], v[152:155], v[184:187], v[126:129]
	v_mfma_f32_16x16x32_bf16 v[122:125], v[160:163], v[184:187], v[122:125]
	v_mfma_f32_16x16x32_bf16 v[118:121], v[152:155], v[192:195], v[118:121]
	v_mfma_f32_16x16x32_bf16 v[110:113], v[160:163], v[192:195], v[110:113]
	v_mfma_f32_16x16x32_bf16 v[102:105], v[152:155], v[200:203], v[102:105]
	v_mfma_f32_16x16x32_bf16 v[94:97], v[160:163], v[200:203], v[94:97]
	v_mfma_f32_16x16x32_bf16 v[86:89], v[152:155], v[208:211], v[86:89]
	v_mfma_f32_16x16x32_bf16 v[78:81], v[160:163], v[208:211], v[78:81]
	v_mfma_f32_16x16x32_bf16 v[126:129], v[156:159], v[188:191], v[126:129]
	v_mfma_f32_16x16x32_bf16 v[122:125], v[164:167], v[188:191], v[122:125]
	v_mfma_f32_16x16x32_bf16 v[118:121], v[156:159], v[196:199], v[118:121]
	v_mfma_f32_16x16x32_bf16 v[110:113], v[164:167], v[196:199], v[110:113]
	v_mfma_f32_16x16x32_bf16 v[102:105], v[156:159], v[204:207], v[102:105]
	v_mfma_f32_16x16x32_bf16 v[94:97], v[164:167], v[204:207], v[94:97]
	v_mfma_f32_16x16x32_bf16 v[86:89], v[156:159], v[212:215], v[86:89]
	v_mfma_f32_16x16x32_bf16 v[78:81], v[164:167], v[212:215], v[78:81]
	s_setprio 0
	s_setprio 1
	v_mfma_f32_16x16x32_bf16 v[114:117], v[168:171], v[184:187], v[114:117]
	v_mfma_f32_16x16x32_bf16 v[106:109], v[176:179], v[184:187], v[106:109]
	v_mfma_f32_16x16x32_bf16 v[98:101], v[168:171], v[192:195], v[98:101]
	v_mfma_f32_16x16x32_bf16 v[90:93], v[176:179], v[192:195], v[90:93]
	v_mfma_f32_16x16x32_bf16 v[82:85], v[168:171], v[200:203], v[82:85]
	v_mfma_f32_16x16x32_bf16 v[74:77], v[176:179], v[200:203], v[74:77]
	v_mfma_f32_16x16x32_bf16 v[70:73], v[168:171], v[208:211], v[70:73]
	v_mfma_f32_16x16x32_bf16 v[66:69], v[176:179], v[208:211], v[66:69]
	v_mfma_f32_16x16x32_bf16 v[114:117], v[172:175], v[188:191], v[114:117]
	v_mfma_f32_16x16x32_bf16 v[106:109], v[180:183], v[188:191], v[106:109]
	v_mfma_f32_16x16x32_bf16 v[98:101], v[172:175], v[196:199], v[98:101]
	v_mfma_f32_16x16x32_bf16 v[90:93], v[180:183], v[196:199], v[90:93]
	v_mfma_f32_16x16x32_bf16 v[82:85], v[172:175], v[204:207], v[82:85]
	v_mfma_f32_16x16x32_bf16 v[74:77], v[180:183], v[204:207], v[74:77]
	v_mfma_f32_16x16x32_bf16 v[70:73], v[172:175], v[212:215], v[70:73]
	v_mfma_f32_16x16x32_bf16 v[66:69], v[180:183], v[212:215], v[66:69]
	s_setprio 0
	s_barrier
	s_add_i32 s24, s82, s74
	v_lshl_add_u64 v[216:217], s[70:71], 0, v[134:135]
	s_mov_b32 m0, s24
	ds_read_b128 v[184:187], v150 offset:16384
	ds_read_b128 v[188:191], v150 offset:17408
	ds_read_b128 v[192:195], v150 offset:18432
	ds_read_b128 v[196:199], v150 offset:19456
	ds_read_b128 v[200:203], v150 offset:20480
	ds_read_b128 v[204:207], v150 offset:21504
	ds_read_b128 v[208:211], v150 offset:22528
	ds_read_b128 v[212:215], v150 offset:23552
	global_load_lds_dwordx4 v[216:217], off
	s_add_i32 m0, s24, 0x2000
	s_add_u32 s34, s70, 0x80000
	v_lshl_add_u64 v[218:219], s[70:71], 0, v[130:131]
	s_addc_u32 s35, s71, 0
	s_add_i32 s24, s83, s74
	global_load_lds_dwordx4 v[218:219], off
	v_lshl_add_u64 v[220:221], s[34:35], 0, v[134:135]
	s_mov_b32 m0, s24
	v_lshl_add_u64 v[222:223], s[72:73], 0, v[132:133]
	global_load_lds_dwordx4 v[220:221], off
	v_lshl_add_u64 v[220:221], s[34:35], 0, v[130:131]
	s_add_i32 m0, s24, 0x2000
	s_nop 0
	global_load_lds_dwordx4 v[220:221], off
	v_lshl_add_u64 v[220:221], s[72:73], 0, v[136:137]
	s_mov_b32 m0, s63
	s_nop 0
	global_load_lds_dwordx4 v[220:221], off
	s_mov_b32 m0, s76
	s_nop 0
	global_load_lds_dwordx4 v[222:223], off
	s_waitcnt vmcnt(8)
	s_waitcnt lgkmcnt(0)
	s_barrier
; #define PG8_STAGEA(bufoff, gbase, voff) PG8_STAGE_X(bufoff, gbase, voff, PG8_AUX_A)
; #define PG8_STAGEB(bufoff, gbase, voff) PG8_STAGE_X(bufoff, gbase, voff, PG8_AUX_B)
; #define PG8_LDA(dst, b, h) do { _Pragma("unroll") for (int m = 0; m < 4; ++m) _Pragma("unroll") for (int k = 0; k < 2; ++k) dst[m][k] = *(const PG8_LAS bf16x8*)(lds + PG8_SA(b, h) + aoff + m * 2048 + k * 1024); } while (0)
; #define PG8_LDB(dst, b, h) do { _Pragma("unroll") for (int n = 0; n < 2; ++n) _Pragma("unroll") for (int k = 0; k < 2; ++k) dst[n][k] = *(const PG8_LAS bf16x8*)(lds + PG8_SB(b, h) + boff + n * 2048 + k * 1024); } while (0)
; #define PG8_MMA(ai, bj, At, Bt) do { __builtin_amdgcn_s_setprio(1); _Pragma("unroll") for (int m = 0; m < 4; ++m) _Pragma("unroll") for (int n = 0; n < 2; ++n) _Pragma("unroll") for (int k = 0; k < 2; ++k) \
;         acc[ai][bj][m][n] = __builtin_amdgcn_mfma_f32_16x16x32_bf16(Bt[n][k], At[m][k], acc[ai][bj][m][n], 0, 0, 0); __builtin_amdgcn_s_setprio(0); } while (0)
; #define PG8_WAIT_V(n) asm volatile("s_waitcnt vmcnt(" #n ")" ::: "memory")
; #define PG8_WAIT_L(n) asm volatile("s_waitcnt lgkmcnt(" #n ")" ::: "memory")
; #define PG8_BAR __builtin_amdgcn_s_barrier()
; #define PG8_SCHED __builtin_amdgcn_sched_barrier(0)
; template <class Epi, class Sched, bool ALIGN_EPI = false, bool SP2 = false>
; __device__ __forceinline__ void gemm_phase(PG8_LAS unsigned char* lds, const Gemm g, const Sched& S, const Epi& E) {
;     ...
;             PG8_WAIT_V(8); PG8_WAIT_L(0); PG8_BAR; PG8_MMA(0, 0, At, B0); PG8_MMA(0, 1, At, B1); PG8_BAR; PG8_SCHED;
;             PG8_LDA(At, 0, 1); PG8_STAGEB(PG8_SB(0, 0), b2, voffB); PG8_STAGEB(PG8_SB(0, 1), b2 + hstep, voffB); PG8_STAGEA(PG8_SA(0, 0), a2, voffA);
;             PG8_WAIT_V(8); PG8_WAIT_L(0); PG8_BAR; PG8_MMA(1, 0, At, B0); PG8_MMA(1, 1, At, B1); PG8_BAR; PG8_SCHED;
;             PG8_LDB(B0, 1, 0); PG8_LDB(B1, 1, 1); PG8_SCHED; PG8_LDA(At, 1, 0); PG8_STAGEA(PG8_SA(0, 1), a2 + hstep, voffA);
;             PG8_WAIT_V(8); PG8_WAIT_L(0); PG8_BAR; PG8_MMA(0, 0, At, B0); PG8_MMA(0, 1, At, B1); PG8_BAR; PG8_SCHED;
	s_setprio 1
	s_waitcnt lgkmcnt(0)
	v_mfma_f32_16x16x32_bf16 v[62:65], v[152:155], v[184:187], v[62:65]
	v_mfma_f32_16x16x32_bf16 v[58:61], v[160:163], v[184:187], v[58:61]
	v_mfma_f32_16x16x32_bf16 v[54:57], v[152:155], v[192:195], v[54:57]
	v_mfma_f32_16x16x32_bf16 v[46:49], v[160:163], v[192:195], v[46:49]
	v_mfma_f32_16x16x32_bf16 v[38:41], v[152:155], v[200:203], v[38:41]
	v_mfma_f32_16x16x32_bf16 v[30:33], v[160:163], v[200:203], v[30:33]
	v_mfma_f32_16x16x32_bf16 v[22:25], v[152:155], v[208:211], v[22:25]
	v_mfma_f32_16x16x32_bf16 v[14:17], v[160:163], v[208:211], v[14:17]
	v_mfma_f32_16x16x32_bf16 v[62:65], v[156:159], v[188:191], v[62:65]
	v_mfma_f32_16x16x32_bf16 v[58:61], v[164:167], v[188:191], v[58:61]
	v_mfma_f32_16x16x32_bf16 v[54:57], v[156:159], v[196:199], v[54:57]
	v_mfma_f32_16x16x32_bf16 v[46:49], v[164:167], v[196:199], v[46:49]
	v_mfma_f32_16x16x32_bf16 v[38:41], v[156:159], v[204:207], v[38:41]
	v_mfma_f32_16x16x32_bf16 v[30:33], v[164:167], v[204:207], v[30:33]
	v_mfma_f32_16x16x32_bf16 v[22:25], v[156:159], v[212:215], v[22:25]
	v_mfma_f32_16x16x32_bf16 v[14:17], v[164:167], v[212:215], v[14:17]
	s_setprio 0
	s_setprio 1
	v_mfma_f32_16x16x32_bf16 v[50:53], v[168:171], v[184:187], v[50:53]
	v_mfma_f32_16x16x32_bf16 v[42:45], v[176:179], v[184:187], v[42:45]
	v_mfma_f32_16x16x32_bf16 v[34:37], v[168:171], v[192:195], v[34:37]
	v_mfma_f32_16x16x32_bf16 v[26:29], v[176:179], v[192:195], v[26:29]
	v_mfma_f32_16x16x32_bf16 v[18:21], v[168:171], v[200:203], v[18:21]
	v_mfma_f32_16x16x32_bf16 v[10:13], v[176:179], v[200:203], v[10:13]
	v_mfma_f32_16x16x32_bf16 v[6:9], v[168:171], v[208:211], v[6:9]
	v_mfma_f32_16x16x32_bf16 v[2:5], v[176:179], v[208:211], v[2:5]
	v_mfma_f32_16x16x32_bf16 v[50:53], v[172:175], v[188:191], v[50:53]
	v_mfma_f32_16x16x32_bf16 v[42:45], v[180:183], v[188:191], v[42:45]
	v_mfma_f32_16x16x32_bf16 v[34:37], v[172:175], v[196:199], v[34:37]
	v_mfma_f32_16x16x32_bf16 v[26:29], v[180:183], v[196:199], v[26:29]
	v_mfma_f32_16x16x32_bf16 v[18:21], v[172:175], v[204:207], v[18:21]
	v_mfma_f32_16x16x32_bf16 v[10:13], v[180:183], v[204:207], v[10:13]
	v_mfma_f32_16x16x32_bf16 v[6:9], v[172:175], v[212:215], v[6:9]
	v_mfma_f32_16x16x32_bf16 v[2:5], v[180:183], v[212:215], v[2:5]
	s_setprio 0
	s_barrier
	s_add_i32 s24, 0, 0x18000
	v_add_u32_e32 v151, s24, v146
	s_add_i32 s25, 0, 0x1c000
	ds_read_b128 v[152:155], v151
	ds_read_b128 v[156:159], v151 offset:1024
	ds_read_b128 v[160:163], v151 offset:2048
	ds_read_b128 v[164:167], v151 offset:3072
	v_add_u32_e32 v151, s25, v146
	ds_read_b128 v[168:171], v151
	ds_read_b128 v[172:175], v151 offset:1024
	ds_read_b128 v[176:179], v151 offset:2048
	ds_read_b128 v[180:183], v151 offset:3072
	s_add_u32 s34, s72, 0x80000
	s_addc_u32 s35, s73, 0
	s_mov_b32 m0, s77
	v_lshl_add_u64 v[224:225], s[34:35], 0, v[136:137]
	ds_read_b128 v[184:187], v150 offset:32768
	ds_read_b128 v[188:191], v150 offset:33792
	ds_read_b128 v[192:195], v150 offset:34816
	ds_read_b128 v[196:199], v150 offset:35840
	ds_read_b128 v[200:203], v150 offset:36864
	ds_read_b128 v[204:207], v150 offset:37888
	ds_read_b128 v[208:211], v150 offset:38912
	ds_read_b128 v[212:215], v150 offset:39936
	global_load_lds_dwordx4 v[224:225], off
	v_lshl_add_u64 v[224:225], s[34:35], 0, v[132:133]
	s_mov_b32 m0, s78
	s_nop 0
	global_load_lds_dwordx4 v[224:225], off
	s_waitcnt vmcnt(8)
	s_waitcnt lgkmcnt(0)
	s_barrier
	s_setprio 1
	s_waitcnt lgkmcnt(0)
	v_mfma_f32_16x16x32_bf16 v[126:129], v[152:155], v[184:187], v[126:129]
	v_mfma_f32_16x16x32_bf16 v[122:125], v[160:163], v[184:187], v[122:125]
	v_mfma_f32_16x16x32_bf16 v[118:121], v[152:155], v[192:195], v[118:121]
	v_mfma_f32_16x16x32_bf16 v[110:113], v[160:163], v[192:195], v[110:113]
	v_mfma_f32_16x16x32_bf16 v[102:105], v[152:155], v[200:203], v[102:105]
	v_mfma_f32_16x16x32_bf16 v[94:97], v[160:163], v[200:203], v[94:97]
	v_mfma_f32_16x16x32_bf16 v[86:89], v[152:155], v[208:211], v[86:89]
	v_mfma_f32_16x16x32_bf16 v[78:81], v[160:163], v[208:211], v[78:81]
	v_mfma_f32_16x16x32_bf16 v[126:129], v[156:159], v[188:191], v[126:129]
	v_mfma_f32_16x16x32_bf16 v[122:125], v[164:167], v[188:191], v[122:125]
	v_mfma_f32_16x16x32_bf16 v[118:121], v[156:159], v[196:199], v[118:121]
	v_mfma_f32_16x16x32_bf16 v[110:113], v[164:167], v[196:199], v[110:113]
	v_mfma_f32_16x16x32_bf16 v[102:105], v[156:159], v[204:207], v[102:105]
	v_mfma_f32_16x16x32_bf16 v[94:97], v[164:167], v[204:207], v[94:97]
	v_mfma_f32_16x16x32_bf16 v[86:89], v[156:159], v[212:215], v[86:89]
	v_mfma_f32_16x16x32_bf16 v[78:81], v[164:167], v[212:215], v[78:81]
	s_setprio 0
	s_setprio 1
	v_mfma_f32_16x16x32_bf16 v[114:117], v[168:171], v[184:187], v[114:117]
	v_mfma_f32_16x16x32_bf16 v[106:109], v[176:179], v[184:187], v[106:109]
	v_mfma_f32_16x16x32_bf16 v[98:101], v[168:171], v[192:195], v[98:101]
	v_mfma_f32_16x16x32_bf16 v[90:93], v[176:179], v[192:195], v[90:93]
	v_mfma_f32_16x16x32_bf16 v[82:85], v[168:171], v[200:203], v[82:85]
	v_mfma_f32_16x16x32_bf16 v[74:77], v[176:179], v[200:203], v[74:77]
	v_mfma_f32_16x16x32_bf16 v[70:73], v[168:171], v[208:211], v[70:73]
	v_mfma_f32_16x16x32_bf16 v[66:69], v[176:179], v[208:211], v[66:69]
	v_mfma_f32_16x16x32_bf16 v[114:117], v[172:175], v[188:191], v[114:117]
	v_mfma_f32_16x16x32_bf16 v[106:109], v[180:183], v[188:191], v[106:109]
	v_mfma_f32_16x16x32_bf16 v[98:101], v[172:175], v[196:199], v[98:101]
	v_mfma_f32_16x16x32_bf16 v[90:93], v[180:183], v[196:199], v[90:93]
	v_mfma_f32_16x16x32_bf16 v[82:85], v[172:175], v[204:207], v[82:85]
	v_mfma_f32_16x16x32_bf16 v[74:77], v[180:183], v[204:207], v[74:77]
	v_mfma_f32_16x16x32_bf16 v[70:73], v[172:175], v[212:215], v[70:73]
	v_mfma_f32_16x16x32_bf16 v[66:69], v[180:183], v[212:215], v[66:69]
	s_setprio 0
	s_barrier
; #define PG8_STAGEA(bufoff, gbase, voff) PG8_STAGE_X(bufoff, gbase, voff, PG8_AUX_A)
; #define PG8_STAGEB(bufoff, gbase, voff) PG8_STAGE_X(bufoff, gbase, voff, PG8_AUX_B)
; #define PG8_LDA(dst, b, h) do { _Pragma("unroll") for (int m = 0; m < 4; ++m) _Pragma("unroll") for (int k = 0; k < 2; ++k) dst[m][k] = *(const PG8_LAS bf16x8*)(lds + PG8_SA(b, h) + aoff + m * 2048 + k * 1024); } while (0)
; #define PG8_MMA(ai, bj, At, Bt) do { __builtin_amdgcn_s_setprio(1); _Pragma("unroll") for (int m = 0; m < 4; ++m) _Pragma("unroll") for (int n = 0; n < 2; ++n) _Pragma("unroll") for (int k = 0; k < 2; ++k) \
;         acc[ai][bj][m][n] = __builtin_amdgcn_mfma_f32_16x16x32_bf16(Bt[n][k], At[m][k], acc[ai][bj][m][n], 0, 0, 0); __builtin_amdgcn_s_setprio(0); } while (0)
; #define PG8_WAIT_V(n) asm volatile("s_waitcnt vmcnt(" #n ")" ::: "memory")
; #define PG8_WAIT_L(n) asm volatile("s_waitcnt lgkmcnt(" #n ")" ::: "memory")
; #define PG8_BAR __builtin_amdgcn_s_barrier()
; #define PG8_SCHED __builtin_amdgcn_sched_barrier(0)
; template <class Epi, class Sched, bool ALIGN_EPI = false, bool SP2 = false>
; __device__ __forceinline__ void gemm_phase(PG8_LAS unsigned char* lds, const Gemm g, const Sched& S, const Epi& E) {
;     ...
;             PG8_WAIT_V(8); PG8_WAIT_L(0); PG8_BAR; PG8_MMA(0, 0, At, B0); PG8_MMA(0, 1, At, B1); PG8_BAR; PG8_SCHED;
;             PG8_LDA(At, 1, 1); PG8_STAGEB(PG8_SB(1, 0), b3, voffB); PG8_STAGEB(PG8_SB(1, 1), b3 + hstep, voffB); PG8_STAGEA(PG8_SA(1, 0), a3, voffA);
;             PG8_WAIT_V(8); PG8_WAIT_L(0); PG8_BAR; PG8_MMA(1, 0, At, B0); PG8_MMA(1, 1, At, B1); PG8_BAR; PG8_SCHED;
	s_add_i32 s24, s24, s74
	v_lshl_add_u64 v[216:217], v[216:217], 0, s[46:47]
	s_mov_b32 m0, s24
	ds_read_b128 v[184:187], v150 offset:49152
	ds_read_b128 v[188:191], v150 offset:50176
	ds_read_b128 v[192:195], v150 offset:51200
	ds_read_b128 v[196:199], v150 offset:52224
	ds_read_b128 v[200:203], v150 offset:53248
	ds_read_b128 v[204:207], v150 offset:54272
	ds_read_b128 v[208:211], v150 offset:55296
	ds_read_b128 v[212:215], v150 offset:56320
	global_load_lds_dwordx4 v[216:217], off
	s_add_i32 m0, s24, 0x2000
	s_add_u32 s34, s70, 0x80080
	v_lshl_add_u64 v[216:217], v[218:219], 0, s[46:47]
	s_addc_u32 s35, s71, 0
	s_add_i32 s24, s25, s74
	global_load_lds_dwordx4 v[216:217], off
	v_lshl_add_u64 v[216:217], s[34:35], 0, v[134:135]
	s_mov_b32 m0, s24
	s_nop 0
	global_load_lds_dwordx4 v[216:217], off
	v_lshl_add_u64 v[216:217], s[34:35], 0, v[130:131]
	s_add_i32 m0, s24, 0x2000
	s_nop 0
	global_load_lds_dwordx4 v[216:217], off
	v_lshl_add_u64 v[216:217], v[220:221], 0, s[46:47]
	s_mov_b32 m0, s79
	s_nop 0
	global_load_lds_dwordx4 v[216:217], off
	v_lshl_add_u64 v[216:217], v[222:223], 0, s[46:47]
	s_mov_b32 m0, s80
	s_nop 0
	global_load_lds_dwordx4 v[216:217], off
	s_waitcnt vmcnt(8)
	s_waitcnt lgkmcnt(0)
	s_barrier
	s_setprio 1
	s_waitcnt lgkmcnt(0)
	v_mfma_f32_16x16x32_bf16 v[62:65], v[152:155], v[184:187], v[62:65]
	v_mfma_f32_16x16x32_bf16 v[58:61], v[160:163], v[184:187], v[58:61]
	v_mfma_f32_16x16x32_bf16 v[54:57], v[152:155], v[192:195], v[54:57]
	v_mfma_f32_16x16x32_bf16 v[46:49], v[160:163], v[192:195], v[46:49]
	v_mfma_f32_16x16x32_bf16 v[38:41], v[152:155], v[200:203], v[38:41]
	v_mfma_f32_16x16x32_bf16 v[30:33], v[160:163], v[200:203], v[30:33]
	v_mfma_f32_16x16x32_bf16 v[22:25], v[152:155], v[208:211], v[22:25]
	v_mfma_f32_16x16x32_bf16 v[14:17], v[160:163], v[208:211], v[14:17]
	v_mfma_f32_16x16x32_bf16 v[62:65], v[156:159], v[188:191], v[62:65]
	v_mfma_f32_16x16x32_bf16 v[58:61], v[164:167], v[188:191], v[58:61]
	v_mfma_f32_16x16x32_bf16 v[54:57], v[156:159], v[196:199], v[54:57]
	v_mfma_f32_16x16x32_bf16 v[46:49], v[164:167], v[196:199], v[46:49]
	v_mfma_f32_16x16x32_bf16 v[38:41], v[156:159], v[204:207], v[38:41]
	v_mfma_f32_16x16x32_bf16 v[30:33], v[164:167], v[204:207], v[30:33]
	v_mfma_f32_16x16x32_bf16 v[22:25], v[156:159], v[212:215], v[22:25]
	v_mfma_f32_16x16x32_bf16 v[14:17], v[164:167], v[212:215], v[14:17]
	s_setprio 0
	s_setprio 1
	v_mfma_f32_16x16x32_bf16 v[50:53], v[168:171], v[184:187], v[50:53]
	v_mfma_f32_16x16x32_bf16 v[42:45], v[176:179], v[184:187], v[42:45]
	v_mfma_f32_16x16x32_bf16 v[34:37], v[168:171], v[192:195], v[34:37]
	v_mfma_f32_16x16x32_bf16 v[26:29], v[176:179], v[192:195], v[26:29]
	v_mfma_f32_16x16x32_bf16 v[18:21], v[168:171], v[200:203], v[18:21]
	v_mfma_f32_16x16x32_bf16 v[10:13], v[176:179], v[200:203], v[10:13]
	v_mfma_f32_16x16x32_bf16 v[6:9], v[168:171], v[208:211], v[6:9]
	v_mfma_f32_16x16x32_bf16 v[2:5], v[176:179], v[208:211], v[2:5]
	v_mfma_f32_16x16x32_bf16 v[50:53], v[172:175], v[188:191], v[50:53]
	v_mfma_f32_16x16x32_bf16 v[42:45], v[180:183], v[188:191], v[42:45]
	v_mfma_f32_16x16x32_bf16 v[34:37], v[172:175], v[196:199], v[34:37]
	v_mfma_f32_16x16x32_bf16 v[26:29], v[180:183], v[196:199], v[26:29]
	v_mfma_f32_16x16x32_bf16 v[18:21], v[172:175], v[204:207], v[18:21]
	v_mfma_f32_16x16x32_bf16 v[10:13], v[180:183], v[204:207], v[10:13]
	v_mfma_f32_16x16x32_bf16 v[6:9], v[172:175], v[212:215], v[6:9]
	v_mfma_f32_16x16x32_bf16 v[2:5], v[180:183], v[212:215], v[2:5]
	s_setprio 0
	s_barrier
	s_add_u32 s68, s68, 0x100
	s_addc_u32 s69, s69, 0
	s_mov_b32 s70, s91
	s_cbranch_vccz .LBB0_750
	s_and_b64 vcc, exec, s[48:49]
	s_cbranch_vccz .LBB0_753
	s_barrier

; #define PG8_STAGEA(bufoff, gbase, voff) PG8_STAGE_X(bufoff, gbase, voff, PG8_AUX_A)
; #define PG8_STAGEB(bufoff, gbase, voff) PG8_STAGE_X(bufoff, gbase, voff, PG8_AUX_B)
; #define PG8_LDA(dst, b, h) do { _Pragma("unroll") for (int m = 0; m < 4; ++m) _Pragma("unroll") for (int k = 0; k < 2; ++k) dst[m][k] = *(const PG8_LAS bf16x8*)(lds + PG8_SA(b, h) + aoff + m * 2048 + k * 1024); } while (0)
; #define PG8_LDB(dst, b, h) do { _Pragma("unroll") for (int n = 0; n < 2; ++n) _Pragma("unroll") for (int k = 0; k < 2; ++k) dst[n][k] = *(const PG8_LAS bf16x8*)(lds + PG8_SB(b, h) + boff + n * 2048 + k * 1024); } while (0)
; #define PG8_MMA(ai, bj, At, Bt) do { __builtin_amdgcn_s_setprio(1); _Pragma("unroll") for (int m = 0; m < 4; ++m) _Pragma("unroll") for (int n = 0; n < 2; ++n) _Pragma("unroll") for (int k = 0; k < 2; ++k) \
;         acc[ai][bj][m][n] = __builtin_amdgcn_mfma_f32_16x16x32_bf16(Bt[n][k], At[m][k], acc[ai][bj][m][n], 0, 0, 0); __builtin_amdgcn_s_setprio(0); } while (0)
; template <class Epi, class Sched, bool ALIGN_EPI = false, bool SP2 = false>
; __device__ __forceinline__ void gemm_phase(PG8_LAS unsigned char* lds, const Gemm g, const Sched& S, const Epi& E) {
;     ...
;         for (int t = 0; t < nt; t += 2) {
;             const bool last = (t == nt - 2);
;             if constexpr (HasMid<Epi>::value) { if (t == ns) E.mid(acc, cur, wr, wc, fr, fq); }
;             const char* sA1 = (t + 1 >= ns) ? cA2 : cA; const char* sA2 = (t + 2 >= ns) ? cA2 : cA; const char* sB2 = (t + 2 >= ns) ? cB2 : cB;
;             const char* a1 = sA1 + (size_t)(t + 1) * kstep;
;             const char* a2 = last ? nA : sA2 + (size_t)(t + 2) * kstep; const char* b2 = last ? nB : sB2 + (size_t)(t + 2) * kstep;
;             const char* a3 = a2 + kstep; const char* b3 = b2 + kstep;
;             if (last && has_next) S.a_ready(nxt);
;             if constexpr (SP2) {
;             PG8_LDB(B0, 0, 0); PG8_LDB(B1, 0, 1); PG8_SCHED; PG8_LDA(At, 0, 0); PG8_STAGEA(PG8_SA(1, 1), a1 + hstep, voffA);
;             PG8_WAIT_V(8); PG8_WAIT_L(0); PG8_BAR; PG8_MMA(0, 0, At, B0); PG8_MMA(0, 1, At, B1); PG8_BAR; PG8_SCHED;
;             PG8_LDA(At, 0, 1); PG8_STAGEB(PG8_SB(0, 0), b2, voffB); PG8_STAGEB(PG8_SB(0, 1), b2 + hstep, voffB); PG8_STAGEA(PG8_SA(0, 0), a2, voffA);
;             PG8_WAIT_V(8); PG8_WAIT_L(0); PG8_BAR; PG8_MMA(1, 0, At, B0); PG8_MMA(1, 1, At, B1); PG8_BAR; PG8_SCHED;
.LBB0_766:
	ds_read_b128 v[152:155], v148
	ds_read_b128 v[156:159], v148 offset:1024
	ds_read_b128 v[160:163], v148 offset:2048
	ds_read_b128 v[164:167], v148 offset:3072
	ds_read_b128 v[168:171], v149
	ds_read_b128 v[172:175], v149 offset:1024
	ds_read_b128 v[176:179], v149 offset:2048
	ds_read_b128 v[180:183], v149 offset:3072
	ds_read_b128 v[184:187], v150
	ds_read_b128 v[188:191], v150 offset:1024
	ds_read_b128 v[192:195], v150 offset:2048
	ds_read_b128 v[196:199], v150 offset:3072
	ds_read_b128 v[200:203], v150 offset:4096
	ds_read_b128 v[204:207], v150 offset:5120
	ds_read_b128 v[208:211], v150 offset:6144
	ds_read_b128 v[212:215], v150 offset:7168
	s_add_i32 s91, s70, 2
	s_cmp_gt_u32 s91, 29
	s_cselect_b64 s[72:73], -1, 0
	s_and_b64 vcc, s[72:73], exec
	s_cselect_b32 s29, s4, s66
	s_cselect_b32 s24, s3, s65
	s_cselect_b32 s25, s2, s64
	s_cselect_b32 s28, s5, s67
	s_add_u32 s29, s29, s68
	s_addc_u32 s28, s28, s69
	s_add_u32 s29, s29, 0xfff80080
	s_addc_u32 s28, s28, -1
	s_add_u32 s25, s25, s68
	s_addc_u32 s24, s24, s69
	s_add_u32 s25, s25, 0xfff80080
	s_addc_u32 s24, s24, -1
	s_cmp_eq_u32 s70, 28
	s_cselect_b32 s70, s90, s25
	s_cselect_b32 s73, s55, s28
	s_cselect_b32 s72, s87, s29
	s_cselect_b32 s71, s53, s24
	v_lshl_add_u64 v[216:217], v[142:143], 0, s[68:69]
	s_add_i32 m0, s63, 0xc000
	global_load_lds_dwordx4 v[216:217], off
	v_lshl_add_u64 v[216:217], v[144:145], 0, s[68:69]
	s_add_i32 m0, s63, 0xe000
	s_nop 0
	global_load_lds_dwordx4 v[216:217], off
	s_waitcnt vmcnt(8)
	s_waitcnt lgkmcnt(0)
	s_barrier
	s_setprio 1
	s_waitcnt lgkmcnt(0)
	v_mfma_f32_16x16x32_bf16 v[126:129], v[152:155], v[184:187], v[126:129]
	v_mfma_f32_16x16x32_bf16 v[122:125], v[160:163], v[184:187], v[122:125]
	v_mfma_f32_16x16x32_bf16 v[118:121], v[152:155], v[192:195], v[118:121]
	v_mfma_f32_16x16x32_bf16 v[110:113], v[160:163], v[192:195], v[110:113]
	v_mfma_f32_16x16x32_bf16 v[102:105], v[152:155], v[200:203], v[102:105]
	v_mfma_f32_16x16x32_bf16 v[94:97], v[160:163], v[200:203], v[94:97]
	v_mfma_f32_16x16x32_bf16 v[86:89], v[152:155], v[208:211], v[86:89]
	v_mfma_f32_16x16x32_bf16 v[78:81], v[160:163], v[208:211], v[78:81]
	v_mfma_f32_16x16x32_bf16 v[126:129], v[156:159], v[188:191], v[126:129]
	v_mfma_f32_16x16x32_bf16 v[122:125], v[164:167], v[188:191], v[122:125]
	v_mfma_f32_16x16x32_bf16 v[118:121], v[156:159], v[196:199], v[118:121]
	v_mfma_f32_16x16x32_bf16 v[110:113], v[164:167], v[196:199], v[110:113]
	v_mfma_f32_16x16x32_bf16 v[102:105], v[156:159], v[204:207], v[102:105]
	v_mfma_f32_16x16x32_bf16 v[94:97], v[164:167], v[204:207], v[94:97]
	v_mfma_f32_16x16x32_bf16 v[86:89], v[156:159], v[212:215], v[86:89]
	v_mfma_f32_16x16x32_bf16 v[78:81], v[164:167], v[212:215], v[78:81]
	s_setprio 0
	s_setprio 1
	v_mfma_f32_16x16x32_bf16 v[114:117], v[168:171], v[184:187], v[114:117]
	v_mfma_f32_16x16x32_bf16 v[106:109], v[176:179], v[184:187], v[106:109]
	v_mfma_f32_16x16x32_bf16 v[98:101], v[168:171], v[192:195], v[98:101]
	v_mfma_f32_16x16x32_bf16 v[90:93], v[176:179], v[192:195], v[90:93]
	v_mfma_f32_16x16x32_bf16 v[82:85], v[168:171], v[200:203], v[82:85]
	v_mfma_f32_16x16x32_bf16 v[74:77], v[176:179], v[200:203], v[74:77]
	v_mfma_f32_16x16x32_bf16 v[70:73], v[168:171], v[208:211], v[70:73]
	v_mfma_f32_16x16x32_bf16 v[66:69], v[176:179], v[208:211], v[66:69]
	v_mfma_f32_16x16x32_bf16 v[114:117], v[172:175], v[188:191], v[114:117]
	v_mfma_f32_16x16x32_bf16 v[106:109], v[180:183], v[188:191], v[106:109]
	v_mfma_f32_16x16x32_bf16 v[98:101], v[172:175], v[196:199], v[98:101]
	v_mfma_f32_16x16x32_bf16 v[90:93], v[180:183], v[196:199], v[90:93]
	v_mfma_f32_16x16x32_bf16 v[82:85], v[172:175], v[204:207], v[82:85]
	v_mfma_f32_16x16x32_bf16 v[74:77], v[180:183], v[204:207], v[74:77]
	v_mfma_f32_16x16x32_bf16 v[70:73], v[172:175], v[212:215], v[70:73]
	v_mfma_f32_16x16x32_bf16 v[66:69], v[180:183], v[212:215], v[66:69]
	s_setprio 0
	s_barrier
	s_add_i32 s24, s81, s23
	v_lshl_add_u64 v[216:217], s[70:71], 0, v[134:135]
	s_mov_b32 m0, s24
	ds_read_b128 v[184:187], v150 offset:16384
	ds_read_b128 v[188:191], v150 offset:17408
	ds_read_b128 v[192:195], v150 offset:18432
	ds_read_b128 v[196:199], v150 offset:19456
	ds_read_b128 v[200:203], v150 offset:20480
	ds_read_b128 v[204:207], v150 offset:21504
	ds_read_b128 v[208:211], v150 offset:22528
	ds_read_b128 v[212:215], v150 offset:23552
	global_load_lds_dwordx4 v[216:217], off
	s_add_i32 m0, s24, 0x2000
	s_add_u32 s92, s70, 0x80000
	v_lshl_add_u64 v[218:219], s[70:71], 0, v[130:131]
	s_addc_u32 s93, s71, 0
	s_add_i32 s24, s82, s23
	global_load_lds_dwordx4 v[218:219], off
	v_lshl_add_u64 v[220:221], s[92:93], 0, v[134:135]
	s_mov_b32 m0, s24
	v_lshl_add_u64 v[222:223], s[72:73], 0, v[132:133]
	global_load_lds_dwordx4 v[220:221], off
	v_lshl_add_u64 v[220:221], s[92:93], 0, v[130:131]
	s_add_i32 m0, s24, 0x2000
	s_nop 0
	global_load_lds_dwordx4 v[220:221], off
	v_lshl_add_u64 v[220:221], s[72:73], 0, v[136:137]
	s_mov_b32 m0, s63
	s_nop 0
	global_load_lds_dwordx4 v[220:221], off
	s_mov_b32 m0, s75
	s_nop 0
	global_load_lds_dwordx4 v[222:223], off
	s_waitcnt vmcnt(8)
	s_waitcnt lgkmcnt(0)
	s_barrier
; #define PG8_STAGEA(bufoff, gbase, voff) PG8_STAGE_X(bufoff, gbase, voff, PG8_AUX_A)
; #define PG8_STAGEB(bufoff, gbase, voff) PG8_STAGE_X(bufoff, gbase, voff, PG8_AUX_B)
; #define PG8_LDA(dst, b, h) do { _Pragma("unroll") for (int m = 0; m < 4; ++m) _Pragma("unroll") for (int k = 0; k < 2; ++k) dst[m][k] = *(const PG8_LAS bf16x8*)(lds + PG8_SA(b, h) + aoff + m * 2048 + k * 1024); } while (0)
; #define PG8_LDB(dst, b, h) do { _Pragma("unroll") for (int n = 0; n < 2; ++n) _Pragma("unroll") for (int k = 0; k < 2; ++k) dst[n][k] = *(const PG8_LAS bf16x8*)(lds + PG8_SB(b, h) + boff + n * 2048 + k * 1024); } while (0)
; #define PG8_MMA(ai, bj, At, Bt) do { __builtin_amdgcn_s_setprio(1); _Pragma("unroll") for (int m = 0; m < 4; ++m) _Pragma("unroll") for (int n = 0; n < 2; ++n) _Pragma("unroll") for (int k = 0; k < 2; ++k) \
;         acc[ai][bj][m][n] = __builtin_amdgcn_mfma_f32_16x16x32_bf16(Bt[n][k], At[m][k], acc[ai][bj][m][n], 0, 0, 0); __builtin_amdgcn_s_setprio(0); } while (0)
; #define PG8_WAIT_V(n) asm volatile("s_waitcnt vmcnt(" #n ")" ::: "memory")
; #define PG8_WAIT_L(n) asm volatile("s_waitcnt lgkmcnt(" #n ")" ::: "memory")
; #define PG8_BAR __builtin_amdgcn_s_barrier()
; #define PG8_SCHED __builtin_amdgcn_sched_barrier(0)
; template <class Epi, class Sched, bool ALIGN_EPI = false, bool SP2 = false>
; __device__ __forceinline__ void gemm_phase(PG8_LAS unsigned char* lds, const Gemm g, const Sched& S, const Epi& E) {
;     ...
;             PG8_WAIT_V(8); PG8_WAIT_L(0); PG8_BAR; PG8_MMA(0, 0, At, B0); PG8_MMA(0, 1, At, B1); PG8_BAR; PG8_SCHED;
;             PG8_LDA(At, 0, 1); PG8_STAGEB(PG8_SB(0, 0), b2, voffB); PG8_STAGEB(PG8_SB(0, 1), b2 + hstep, voffB); PG8_STAGEA(PG8_SA(0, 0), a2, voffA);
;             PG8_WAIT_V(8); PG8_WAIT_L(0); PG8_BAR; PG8_MMA(1, 0, At, B0); PG8_MMA(1, 1, At, B1); PG8_BAR; PG8_SCHED;
;             PG8_LDB(B0, 1, 0); PG8_LDB(B1, 1, 1); PG8_SCHED; PG8_LDA(At, 1, 0); PG8_STAGEA(PG8_SA(0, 1), a2 + hstep, voffA);
;             PG8_WAIT_V(8); PG8_WAIT_L(0); PG8_BAR; PG8_MMA(0, 0, At, B0); PG8_MMA(0, 1, At, B1); PG8_BAR; PG8_SCHED;
	s_setprio 1
	s_waitcnt lgkmcnt(0)
	v_mfma_f32_16x16x32_bf16 v[62:65], v[152:155], v[184:187], v[62:65]
	v_mfma_f32_16x16x32_bf16 v[58:61], v[160:163], v[184:187], v[58:61]
	v_mfma_f32_16x16x32_bf16 v[54:57], v[152:155], v[192:195], v[54:57]
	v_mfma_f32_16x16x32_bf16 v[46:49], v[160:163], v[192:195], v[46:49]
	v_mfma_f32_16x16x32_bf16 v[38:41], v[152:155], v[200:203], v[38:41]
	v_mfma_f32_16x16x32_bf16 v[30:33], v[160:163], v[200:203], v[30:33]
	v_mfma_f32_16x16x32_bf16 v[22:25], v[152:155], v[208:211], v[22:25]
	v_mfma_f32_16x16x32_bf16 v[14:17], v[160:163], v[208:211], v[14:17]
	v_mfma_f32_16x16x32_bf16 v[62:65], v[156:159], v[188:191], v[62:65]
	v_mfma_f32_16x16x32_bf16 v[58:61], v[164:167], v[188:191], v[58:61]
	v_mfma_f32_16x16x32_bf16 v[54:57], v[156:159], v[196:199], v[54:57]
	v_mfma_f32_16x16x32_bf16 v[46:49], v[164:167], v[196:199], v[46:49]
	v_mfma_f32_16x16x32_bf16 v[38:41], v[156:159], v[204:207], v[38:41]
	v_mfma_f32_16x16x32_bf16 v[30:33], v[164:167], v[204:207], v[30:33]
	v_mfma_f32_16x16x32_bf16 v[22:25], v[156:159], v[212:215], v[22:25]
	v_mfma_f32_16x16x32_bf16 v[14:17], v[164:167], v[212:215], v[14:17]
	s_setprio 0
	s_setprio 1
	v_mfma_f32_16x16x32_bf16 v[50:53], v[168:171], v[184:187], v[50:53]
	v_mfma_f32_16x16x32_bf16 v[42:45], v[176:179], v[184:187], v[42:45]
	v_mfma_f32_16x16x32_bf16 v[34:37], v[168:171], v[192:195], v[34:37]
	v_mfma_f32_16x16x32_bf16 v[26:29], v[176:179], v[192:195], v[26:29]
	v_mfma_f32_16x16x32_bf16 v[18:21], v[168:171], v[200:203], v[18:21]
	v_mfma_f32_16x16x32_bf16 v[10:13], v[176:179], v[200:203], v[10:13]
	v_mfma_f32_16x16x32_bf16 v[6:9], v[168:171], v[208:211], v[6:9]
	v_mfma_f32_16x16x32_bf16 v[2:5], v[176:179], v[208:211], v[2:5]
	v_mfma_f32_16x16x32_bf16 v[50:53], v[172:175], v[188:191], v[50:53]
	v_mfma_f32_16x16x32_bf16 v[42:45], v[180:183], v[188:191], v[42:45]
	v_mfma_f32_16x16x32_bf16 v[34:37], v[172:175], v[196:199], v[34:37]
	v_mfma_f32_16x16x32_bf16 v[26:29], v[180:183], v[196:199], v[26:29]
	v_mfma_f32_16x16x32_bf16 v[18:21], v[172:175], v[204:207], v[18:21]
	v_mfma_f32_16x16x32_bf16 v[10:13], v[180:183], v[204:207], v[10:13]
	v_mfma_f32_16x16x32_bf16 v[6:9], v[172:175], v[212:215], v[6:9]
	v_mfma_f32_16x16x32_bf16 v[2:5], v[180:183], v[212:215], v[2:5]
	s_setprio 0
	s_barrier
	s_add_i32 s24, 0, 0x18000
	v_add_u32_e32 v151, s24, v146
	s_add_i32 s25, 0, 0x1c000
	ds_read_b128 v[152:155], v151
	ds_read_b128 v[156:159], v151 offset:1024
	ds_read_b128 v[160:163], v151 offset:2048
	ds_read_b128 v[164:167], v151 offset:3072
	v_add_u32_e32 v151, s25, v146
	ds_read_b128 v[168:171], v151
	ds_read_b128 v[172:175], v151 offset:1024
	ds_read_b128 v[176:179], v151 offset:2048
	ds_read_b128 v[180:183], v151 offset:3072
	s_add_u32 s72, s72, 0x80000
	s_addc_u32 s73, s73, 0
	s_mov_b32 m0, s76
	v_lshl_add_u64 v[224:225], s[72:73], 0, v[136:137]
	ds_read_b128 v[184:187], v150 offset:32768
	ds_read_b128 v[188:191], v150 offset:33792
	ds_read_b128 v[192:195], v150 offset:34816
	ds_read_b128 v[196:199], v150 offset:35840
	ds_read_b128 v[200:203], v150 offset:36864
	ds_read_b128 v[204:207], v150 offset:37888
	ds_read_b128 v[208:211], v150 offset:38912
	ds_read_b128 v[212:215], v150 offset:39936
	global_load_lds_dwordx4 v[224:225], off
	v_lshl_add_u64 v[224:225], s[72:73], 0, v[132:133]
	s_mov_b32 m0, s77
	s_nop 0
	global_load_lds_dwordx4 v[224:225], off
	s_waitcnt vmcnt(8)
	s_waitcnt lgkmcnt(0)
	s_barrier
	s_setprio 1
	s_waitcnt lgkmcnt(0)
	v_mfma_f32_16x16x32_bf16 v[126:129], v[152:155], v[184:187], v[126:129]
	v_mfma_f32_16x16x32_bf16 v[122:125], v[160:163], v[184:187], v[122:125]
	v_mfma_f32_16x16x32_bf16 v[118:121], v[152:155], v[192:195], v[118:121]
	v_mfma_f32_16x16x32_bf16 v[110:113], v[160:163], v[192:195], v[110:113]
	v_mfma_f32_16x16x32_bf16 v[102:105], v[152:155], v[200:203], v[102:105]
	v_mfma_f32_16x16x32_bf16 v[94:97], v[160:163], v[200:203], v[94:97]
	v_mfma_f32_16x16x32_bf16 v[86:89], v[152:155], v[208:211], v[86:89]
	v_mfma_f32_16x16x32_bf16 v[78:81], v[160:163], v[208:211], v[78:81]
	v_mfma_f32_16x16x32_bf16 v[126:129], v[156:159], v[188:191], v[126:129]
	v_mfma_f32_16x16x32_bf16 v[122:125], v[164:167], v[188:191], v[122:125]
	v_mfma_f32_16x16x32_bf16 v[118:121], v[156:159], v[196:199], v[118:121]
	v_mfma_f32_16x16x32_bf16 v[110:113], v[164:167], v[196:199], v[110:113]
	v_mfma_f32_16x16x32_bf16 v[102:105], v[156:159], v[204:207], v[102:105]
	v_mfma_f32_16x16x32_bf16 v[94:97], v[164:167], v[204:207], v[94:97]
	v_mfma_f32_16x16x32_bf16 v[86:89], v[156:159], v[212:215], v[86:89]
	v_mfma_f32_16x16x32_bf16 v[78:81], v[164:167], v[212:215], v[78:81]
	s_setprio 0
	s_setprio 1
	v_mfma_f32_16x16x32_bf16 v[114:117], v[168:171], v[184:187], v[114:117]
	v_mfma_f32_16x16x32_bf16 v[106:109], v[176:179], v[184:187], v[106:109]
	v_mfma_f32_16x16x32_bf16 v[98:101], v[168:171], v[192:195], v[98:101]
	v_mfma_f32_16x16x32_bf16 v[90:93], v[176:179], v[192:195], v[90:93]
	v_mfma_f32_16x16x32_bf16 v[82:85], v[168:171], v[200:203], v[82:85]
	v_mfma_f32_16x16x32_bf16 v[74:77], v[176:179], v[200:203], v[74:77]
	v_mfma_f32_16x16x32_bf16 v[70:73], v[168:171], v[208:211], v[70:73]
	v_mfma_f32_16x16x32_bf16 v[66:69], v[176:179], v[208:211], v[66:69]
	v_mfma_f32_16x16x32_bf16 v[114:117], v[172:175], v[188:191], v[114:117]
	v_mfma_f32_16x16x32_bf16 v[106:109], v[180:183], v[188:191], v[106:109]
	v_mfma_f32_16x16x32_bf16 v[98:101], v[172:175], v[196:199], v[98:101]
	v_mfma_f32_16x16x32_bf16 v[90:93], v[180:183], v[196:199], v[90:93]
	v_mfma_f32_16x16x32_bf16 v[82:85], v[172:175], v[204:207], v[82:85]
	v_mfma_f32_16x16x32_bf16 v[74:77], v[180:183], v[204:207], v[74:77]
	v_mfma_f32_16x16x32_bf16 v[70:73], v[172:175], v[212:215], v[70:73]
	v_mfma_f32_16x16x32_bf16 v[66:69], v[180:183], v[212:215], v[66:69]
	s_setprio 0
	s_barrier
; #define PG8_STAGEA(bufoff, gbase, voff) PG8_STAGE_X(bufoff, gbase, voff, PG8_AUX_A)
; #define PG8_STAGEB(bufoff, gbase, voff) PG8_STAGE_X(bufoff, gbase, voff, PG8_AUX_B)
; #define PG8_LDA(dst, b, h) do { _Pragma("unroll") for (int m = 0; m < 4; ++m) _Pragma("unroll") for (int k = 0; k < 2; ++k) dst[m][k] = *(const PG8_LAS bf16x8*)(lds + PG8_SA(b, h) + aoff + m * 2048 + k * 1024); } while (0)
; #define PG8_MMA(ai, bj, At, Bt) do { __builtin_amdgcn_s_setprio(1); _Pragma("unroll") for (int m = 0; m < 4; ++m) _Pragma("unroll") for (int n = 0; n < 2; ++n) _Pragma("unroll") for (int k = 0; k < 2; ++k) \
;         acc[ai][bj][m][n] = __builtin_amdgcn_mfma_f32_16x16x32_bf16(Bt[n][k], At[m][k], acc[ai][bj][m][n], 0, 0, 0); __builtin_amdgcn_s_setprio(0); } while (0)
; #define PG8_WAIT_V(n) asm volatile("s_waitcnt vmcnt(" #n ")" ::: "memory")
; #define PG8_WAIT_L(n) asm volatile("s_waitcnt lgkmcnt(" #n ")" ::: "memory")
; #define PG8_BAR __builtin_amdgcn_s_barrier()
; #define PG8_SCHED __builtin_amdgcn_sched_barrier(0)
; template <class Epi, class Sched, bool ALIGN_EPI = false, bool SP2 = false>
; __device__ __forceinline__ void gemm_phase(PG8_LAS unsigned char* lds, const Gemm g, const Sched& S, const Epi& E) {
;     ...
;             PG8_WAIT_V(8); PG8_WAIT_L(0); PG8_BAR; PG8_MMA(0, 0, At, B0); PG8_MMA(0, 1, At, B1); PG8_BAR; PG8_SCHED;
;             PG8_LDA(At, 1, 1); PG8_STAGEB(PG8_SB(1, 0), b3, voffB); PG8_STAGEB(PG8_SB(1, 1), b3 + hstep, voffB); PG8_STAGEA(PG8_SA(1, 0), a3, voffA);
;             PG8_WAIT_V(8); PG8_WAIT_L(0); PG8_BAR; PG8_MMA(1, 0, At, B0); PG8_MMA(1, 1, At, B1); PG8_BAR; PG8_SCHED;
	s_add_i32 s24, s24, s23
	v_lshl_add_u64 v[216:217], v[216:217], 0, s[36:37]
	s_mov_b32 m0, s24
	ds_read_b128 v[184:187], v150 offset:49152
	ds_read_b128 v[188:191], v150 offset:50176
	ds_read_b128 v[192:195], v150 offset:51200
	ds_read_b128 v[196:199], v150 offset:52224
	ds_read_b128 v[200:203], v150 offset:53248
	ds_read_b128 v[204:207], v150 offset:54272
	ds_read_b128 v[208:211], v150 offset:55296
	ds_read_b128 v[212:215], v150 offset:56320
	global_load_lds_dwordx4 v[216:217], off
	s_add_i32 m0, s24, 0x2000
	s_add_u32 s70, s70, 0x80080
	v_lshl_add_u64 v[216:217], v[218:219], 0, s[36:37]
	s_addc_u32 s71, s71, 0
	s_add_i32 s24, s25, s23
	global_load_lds_dwordx4 v[216:217], off
	v_lshl_add_u64 v[216:217], s[70:71], 0, v[134:135]
	s_mov_b32 m0, s24
	s_nop 0
	global_load_lds_dwordx4 v[216:217], off
	v_lshl_add_u64 v[216:217], s[70:71], 0, v[130:131]
	s_add_i32 m0, s24, 0x2000
	s_nop 0
	global_load_lds_dwordx4 v[216:217], off
	v_lshl_add_u64 v[216:217], v[220:221], 0, s[36:37]
	s_mov_b32 m0, s79
	s_nop 0
	global_load_lds_dwordx4 v[216:217], off
	v_lshl_add_u64 v[216:217], v[222:223], 0, s[36:37]
	s_mov_b32 m0, s80
	s_nop 0
	global_load_lds_dwordx4 v[216:217], off
	s_waitcnt vmcnt(8)
	s_waitcnt lgkmcnt(0)
	s_barrier
	s_setprio 1
	s_waitcnt lgkmcnt(0)
	v_mfma_f32_16x16x32_bf16 v[62:65], v[152:155], v[184:187], v[62:65]
	v_mfma_f32_16x16x32_bf16 v[58:61], v[160:163], v[184:187], v[58:61]
	v_mfma_f32_16x16x32_bf16 v[54:57], v[152:155], v[192:195], v[54:57]
	v_mfma_f32_16x16x32_bf16 v[46:49], v[160:163], v[192:195], v[46:49]
	v_mfma_f32_16x16x32_bf16 v[38:41], v[152:155], v[200:203], v[38:41]
	v_mfma_f32_16x16x32_bf16 v[30:33], v[160:163], v[200:203], v[30:33]
	v_mfma_f32_16x16x32_bf16 v[22:25], v[152:155], v[208:211], v[22:25]
	v_mfma_f32_16x16x32_bf16 v[14:17], v[160:163], v[208:211], v[14:17]
	v_mfma_f32_16x16x32_bf16 v[62:65], v[156:159], v[188:191], v[62:65]
	v_mfma_f32_16x16x32_bf16 v[58:61], v[164:167], v[188:191], v[58:61]
	v_mfma_f32_16x16x32_bf16 v[54:57], v[156:159], v[196:199], v[54:57]
	v_mfma_f32_16x16x32_bf16 v[46:49], v[164:167], v[196:199], v[46:49]
	v_mfma_f32_16x16x32_bf16 v[38:41], v[156:159], v[204:207], v[38:41]
	v_mfma_f32_16x16x32_bf16 v[30:33], v[164:167], v[204:207], v[30:33]
	v_mfma_f32_16x16x32_bf16 v[22:25], v[156:159], v[212:215], v[22:25]
	v_mfma_f32_16x16x32_bf16 v[14:17], v[164:167], v[212:215], v[14:17]
	s_setprio 0
	s_setprio 1
	v_mfma_f32_16x16x32_bf16 v[50:53], v[168:171], v[184:187], v[50:53]
	v_mfma_f32_16x16x32_bf16 v[42:45], v[176:179], v[184:187], v[42:45]
	v_mfma_f32_16x16x32_bf16 v[34:37], v[168:171], v[192:195], v[34:37]
	v_mfma_f32_16x16x32_bf16 v[26:29], v[176:179], v[192:195], v[26:29]
	v_mfma_f32_16x16x32_bf16 v[18:21], v[168:171], v[200:203], v[18:21]
	v_mfma_f32_16x16x32_bf16 v[10:13], v[176:179], v[200:203], v[10:13]
	v_mfma_f32_16x16x32_bf16 v[6:9], v[168:171], v[208:211], v[6:9]
	v_mfma_f32_16x16x32_bf16 v[2:5], v[176:179], v[208:211], v[2:5]
	v_mfma_f32_16x16x32_bf16 v[50:53], v[172:175], v[188:191], v[50:53]
	v_mfma_f32_16x16x32_bf16 v[42:45], v[180:183], v[188:191], v[42:45]
	v_mfma_f32_16x16x32_bf16 v[34:37], v[172:175], v[196:199], v[34:37]
	v_mfma_f32_16x16x32_bf16 v[26:29], v[180:183], v[196:199], v[26:29]
	v_mfma_f32_16x16x32_bf16 v[18:21], v[172:175], v[204:207], v[18:21]
	v_mfma_f32_16x16x32_bf16 v[10:13], v[180:183], v[204:207], v[10:13]
	v_mfma_f32_16x16x32_bf16 v[6:9], v[172:175], v[212:215], v[6:9]
	v_mfma_f32_16x16x32_bf16 v[2:5], v[180:183], v[212:215], v[2:5]
	s_setprio 0
	s_barrier
	s_add_u32 s68, s68, 0x100
	s_addc_u32 s69, s69, 0
	s_mov_b32 s70, s91
	s_cbranch_vccz .LBB0_766
	s_and_b64 vcc, exec, s[46:47]
	s_cbranch_vccz .LBB0_769
	s_barrier

; #define PG8_STAGEA(bufoff, gbase, voff) PG8_STAGE_X(bufoff, gbase, voff, PG8_AUX_A)
; #define PG8_STAGEB(bufoff, gbase, voff) PG8_STAGE_X(bufoff, gbase, voff, PG8_AUX_B)
; #define PG8_LDA(dst, b, h) do { _Pragma("unroll") for (int m = 0; m < 4; ++m) _Pragma("unroll") for (int k = 0; k < 2; ++k) dst[m][k] = *(const PG8_LAS bf16x8*)(lds + PG8_SA(b, h) + aoff + m * 2048 + k * 1024); } while (0)
; #define PG8_LDB(dst, b, h) do { _Pragma("unroll") for (int n = 0; n < 2; ++n) _Pragma("unroll") for (int k = 0; k < 2; ++k) dst[n][k] = *(const PG8_LAS bf16x8*)(lds + PG8_SB(b, h) + boff + n * 2048 + k * 1024); } while (0)
; #define PG8_MMA(ai, bj, At, Bt) do { __builtin_amdgcn_s_setprio(1); _Pragma("unroll") for (int m = 0; m < 4; ++m) _Pragma("unroll") for (int n = 0; n < 2; ++n) _Pragma("unroll") for (int k = 0; k < 2; ++k) \
;         acc[ai][bj][m][n] = __builtin_amdgcn_mfma_f32_16x16x32_bf16(Bt[n][k], At[m][k], acc[ai][bj][m][n], 0, 0, 0); __builtin_amdgcn_s_setprio(0); } while (0)
; template <class Epi, class Sched, bool ALIGN_EPI = false, bool SP2 = false>
; __device__ __forceinline__ void gemm_phase(PG8_LAS unsigned char* lds, const Gemm g, const Sched& S, const Epi& E) {
;     ...
;         for (int t = 0; t < nt; t += 2) {
;             const bool last = (t == nt - 2);
;             if constexpr (HasMid<Epi>::value) { if (t == ns) E.mid(acc, cur, wr, wc, fr, fq); }
;             const char* sA1 = (t + 1 >= ns) ? cA2 : cA; const char* sA2 = (t + 2 >= ns) ? cA2 : cA; const char* sB2 = (t + 2 >= ns) ? cB2 : cB;
;             const char* a1 = sA1 + (size_t)(t + 1) * kstep;
;             const char* a2 = last ? nA : sA2 + (size_t)(t + 2) * kstep; const char* b2 = last ? nB : sB2 + (size_t)(t + 2) * kstep;
;             const char* a3 = a2 + kstep; const char* b3 = b2 + kstep;
;             if (last && has_next) S.a_ready(nxt);
;             if constexpr (SP2) {
;             PG8_LDB(B0, 0, 0); PG8_LDB(B1, 0, 1); PG8_SCHED; PG8_LDA(At, 0, 0); PG8_STAGEA(PG8_SA(1, 1), a1 + hstep, voffA);
;             PG8_WAIT_V(8); PG8_WAIT_L(0); PG8_BAR; PG8_MMA(0, 0, At, B0); PG8_MMA(0, 1, At, B1); PG8_BAR; PG8_SCHED;
;             PG8_LDA(At, 0, 1); PG8_STAGEB(PG8_SB(0, 0), b2, voffB); PG8_STAGEB(PG8_SB(0, 1), b2 + hstep, voffB); PG8_STAGEA(PG8_SA(0, 0), a2, voffA);
;             PG8_WAIT_V(8); PG8_WAIT_L(0); PG8_BAR; PG8_MMA(1, 0, At, B0); PG8_MMA(1, 1, At, B1); PG8_BAR; PG8_SCHED;
.LBB0_920:
	ds_read_b128 v[82:85], v164
	ds_read_b128 v[90:93], v164 offset:1024
	ds_read_b128 v[94:97], v164 offset:2048
	ds_read_b128 v[158:161], v164 offset:3072
	ds_read_b128 v[168:171], v165
	ds_read_b128 v[172:175], v165 offset:1024
	ds_read_b128 v[176:179], v165 offset:2048
	ds_read_b128 v[180:183], v165 offset:3072
	ds_read_b128 v[184:187], v166
	ds_read_b128 v[188:191], v166 offset:1024
	ds_read_b128 v[192:195], v166 offset:2048
	ds_read_b128 v[196:199], v166 offset:3072
	ds_read_b128 v[200:203], v166 offset:4096
	ds_read_b128 v[204:207], v166 offset:5120
	ds_read_b128 v[208:211], v166 offset:6144
	ds_read_b128 v[212:215], v166 offset:7168
	s_add_i32 s87, s66, 2
	s_cmp_lt_u32 s87, 6
	s_cselect_b32 s29, s62, s40
	s_cselect_b32 s24, s61, s37
	s_cselect_b32 s25, s60, s36
	s_cselect_b32 s28, s63, s41
	s_add_u32 s29, s29, s64
	s_addc_u32 s28, s28, s65
	s_add_u32 s29, s29, 0xfffe0080
	s_addc_u32 s28, s28, -1
	s_add_u32 s25, s25, s64
	s_addc_u32 s24, s24, s65
	s_add_u32 s25, s25, 0xfffe0080
	s_addc_u32 s24, s24, -1
	s_cmp_eq_u32 s66, 4
	s_cselect_b32 s73, s51, s28
	s_cselect_b32 s72, s57, s29
	s_cselect_b32 s75, s49, s24
	s_cselect_b32 s74, s86, s25
	s_add_i32 s25, s84, s23
	s_add_i32 m0, s26, 0xc000
	s_add_i32 s24, s26, 0xe000
	s_add_i32 s28, s25, 0x2000
	s_add_u32 s76, s74, 0x20000
	s_addc_u32 s77, s75, 0
	s_add_i32 s29, s85, s23
	s_add_i32 s92, s29, 0x2000
	s_add_i32 s93, 0, 0x18000
	s_add_i32 s94, 0, 0x1c000
	s_add_u32 s70, s72, 0x20000
	s_addc_u32 s71, s73, 0
	s_add_i32 s90, s93, s23
	s_add_i32 s88, s90, 0x2000
	s_add_u32 s68, s74, 0x20080
	s_addc_u32 s69, s75, 0
	s_add_i32 s89, s94, s23
	s_add_i32 s91, s89, 0x2000
	s_add_u32 s66, s64, 0x100
	s_addc_u32 s67, s65, 0
	s_cmp_gt_u32 s87, 5
	v_lshl_add_u64 v[216:217], v[70:71], 0, s[64:65]
	global_load_lds_dwordx4 v[216:217], off
	v_lshl_add_u64 v[216:217], v[72:73], 0, s[64:65]
	s_mov_b32 m0, s24
	s_nop 0
	global_load_lds_dwordx4 v[216:217], off
	s_waitcnt vmcnt(8)
	s_waitcnt lgkmcnt(0)
	s_barrier
	s_setprio 1
	s_waitcnt lgkmcnt(0)
	v_mfma_f32_16x16x32_bf16 v[142:145], v[82:85], v[184:187], v[142:145]
	v_mfma_f32_16x16x32_bf16 v[138:141], v[94:97], v[184:187], v[138:141]
	v_mfma_f32_16x16x32_bf16 v[126:129], v[82:85], v[192:195], v[126:129]
	v_mfma_f32_16x16x32_bf16 v[122:125], v[94:97], v[192:195], v[122:125]
	v_mfma_f32_16x16x32_bf16 v[110:113], v[82:85], v[200:203], v[110:113]
	v_mfma_f32_16x16x32_bf16 v[106:109], v[94:97], v[200:203], v[106:109]
	v_mfma_f32_16x16x32_bf16 v[86:89], v[82:85], v[208:211], v[86:89]
	v_mfma_f32_16x16x32_bf16 v[78:81], v[94:97], v[208:211], v[78:81]
	v_mfma_f32_16x16x32_bf16 v[142:145], v[90:93], v[188:191], v[142:145]
	v_mfma_f32_16x16x32_bf16 v[138:141], v[158:161], v[188:191], v[138:141]
	v_mfma_f32_16x16x32_bf16 v[126:129], v[90:93], v[196:199], v[126:129]
	v_mfma_f32_16x16x32_bf16 v[122:125], v[158:161], v[196:199], v[122:125]
	v_mfma_f32_16x16x32_bf16 v[110:113], v[90:93], v[204:207], v[110:113]
	v_mfma_f32_16x16x32_bf16 v[106:109], v[158:161], v[204:207], v[106:109]
	v_mfma_f32_16x16x32_bf16 v[86:89], v[90:93], v[212:215], v[86:89]
	v_mfma_f32_16x16x32_bf16 v[78:81], v[158:161], v[212:215], v[78:81]
	s_setprio 0
	s_setprio 1
	v_mfma_f32_16x16x32_bf16 v[134:137], v[168:171], v[184:187], v[134:137]
	v_mfma_f32_16x16x32_bf16 v[130:133], v[176:179], v[184:187], v[130:133]
	v_mfma_f32_16x16x32_bf16 v[118:121], v[168:171], v[192:195], v[118:121]
	v_mfma_f32_16x16x32_bf16 v[114:117], v[176:179], v[192:195], v[114:117]
	v_mfma_f32_16x16x32_bf16 v[102:105], v[168:171], v[200:203], v[102:105]
	v_mfma_f32_16x16x32_bf16 v[98:101], v[176:179], v[200:203], v[98:101]
	v_mfma_f32_16x16x32_bf16 v[74:77], v[168:171], v[208:211], v[74:77]
	v_mfma_f32_16x16x32_bf16 v[66:69], v[176:179], v[208:211], v[66:69]
	v_mfma_f32_16x16x32_bf16 v[134:137], v[172:175], v[188:191], v[134:137]
	v_mfma_f32_16x16x32_bf16 v[130:133], v[180:183], v[188:191], v[130:133]
	v_mfma_f32_16x16x32_bf16 v[118:121], v[172:175], v[196:199], v[118:121]
	v_mfma_f32_16x16x32_bf16 v[114:117], v[180:183], v[196:199], v[114:117]
	v_mfma_f32_16x16x32_bf16 v[102:105], v[172:175], v[204:207], v[102:105]
	v_mfma_f32_16x16x32_bf16 v[98:101], v[180:183], v[204:207], v[98:101]
	v_mfma_f32_16x16x32_bf16 v[74:77], v[172:175], v[212:215], v[74:77]
	v_mfma_f32_16x16x32_bf16 v[66:69], v[180:183], v[212:215], v[66:69]
	s_setprio 0
	s_barrier
	s_mov_b32 m0, s25
	v_lshl_add_u64 v[216:217], s[74:75], 0, v[146:147]
	ds_read_b128 v[184:187], v166 offset:16384
	ds_read_b128 v[188:191], v166 offset:17408
	ds_read_b128 v[192:195], v166 offset:18432
	ds_read_b128 v[196:199], v166 offset:19456
	ds_read_b128 v[200:203], v166 offset:20480
	ds_read_b128 v[204:207], v166 offset:21504
	ds_read_b128 v[208:211], v166 offset:22528
	ds_read_b128 v[212:215], v166 offset:23552
	global_load_lds_dwordx4 v[216:217], off
	v_lshl_add_u64 v[218:219], s[74:75], 0, v[148:149]
	s_mov_b32 m0, s28
	v_lshl_add_u64 v[220:221], s[76:77], 0, v[146:147]
	global_load_lds_dwordx4 v[218:219], off
	s_mov_b32 m0, s29
	v_lshl_add_u64 v[222:223], s[72:73], 0, v[148:149]
	global_load_lds_dwordx4 v[220:221], off
	v_lshl_add_u64 v[220:221], s[76:77], 0, v[148:149]
	s_mov_b32 m0, s92
	s_nop 0
	global_load_lds_dwordx4 v[220:221], off
	v_lshl_add_u64 v[220:221], s[72:73], 0, v[146:147]
	s_mov_b32 m0, s26
	s_nop 0
	global_load_lds_dwordx4 v[220:221], off
	s_mov_b32 m0, s27
	s_nop 0
	global_load_lds_dwordx4 v[222:223], off
	s_waitcnt vmcnt(8)
	s_waitcnt lgkmcnt(0)
	s_barrier
; #define PG8_STAGEA(bufoff, gbase, voff) PG8_STAGE_X(bufoff, gbase, voff, PG8_AUX_A)
; #define PG8_STAGEB(bufoff, gbase, voff) PG8_STAGE_X(bufoff, gbase, voff, PG8_AUX_B)
; #define PG8_LDA(dst, b, h) do { _Pragma("unroll") for (int m = 0; m < 4; ++m) _Pragma("unroll") for (int k = 0; k < 2; ++k) dst[m][k] = *(const PG8_LAS bf16x8*)(lds + PG8_SA(b, h) + aoff + m * 2048 + k * 1024); } while (0)
; #define PG8_LDB(dst, b, h) do { _Pragma("unroll") for (int n = 0; n < 2; ++n) _Pragma("unroll") for (int k = 0; k < 2; ++k) dst[n][k] = *(const PG8_LAS bf16x8*)(lds + PG8_SB(b, h) + boff + n * 2048 + k * 1024); } while (0)
; #define PG8_MMA(ai, bj, At, Bt) do { __builtin_amdgcn_s_setprio(1); _Pragma("unroll") for (int m = 0; m < 4; ++m) _Pragma("unroll") for (int n = 0; n < 2; ++n) _Pragma("unroll") for (int k = 0; k < 2; ++k) \
;         acc[ai][bj][m][n] = __builtin_amdgcn_mfma_f32_16x16x32_bf16(Bt[n][k], At[m][k], acc[ai][bj][m][n], 0, 0, 0); __builtin_amdgcn_s_setprio(0); } while (0)
; #define PG8_WAIT_V(n) asm volatile("s_waitcnt vmcnt(" #n ")" ::: "memory")
; #define PG8_WAIT_L(n) asm volatile("s_waitcnt lgkmcnt(" #n ")" ::: "memory")
; #define PG8_BAR __builtin_amdgcn_s_barrier()
; #define PG8_SCHED __builtin_amdgcn_sched_barrier(0)
; template <class Epi, class Sched, bool ALIGN_EPI = false, bool SP2 = false>
; __device__ __forceinline__ void gemm_phase(PG8_LAS unsigned char* lds, const Gemm g, const Sched& S, const Epi& E) {
;     ...
;             PG8_WAIT_V(8); PG8_WAIT_L(0); PG8_BAR; PG8_MMA(0, 0, At, B0); PG8_MMA(0, 1, At, B1); PG8_BAR; PG8_SCHED;
;             PG8_LDA(At, 0, 1); PG8_STAGEB(PG8_SB(0, 0), b2, voffB); PG8_STAGEB(PG8_SB(0, 1), b2 + hstep, voffB); PG8_STAGEA(PG8_SA(0, 0), a2, voffA);
;             PG8_WAIT_V(8); PG8_WAIT_L(0); PG8_BAR; PG8_MMA(1, 0, At, B0); PG8_MMA(1, 1, At, B1); PG8_BAR; PG8_SCHED;
;             PG8_LDB(B0, 1, 0); PG8_LDB(B1, 1, 1); PG8_SCHED; PG8_LDA(At, 1, 0); PG8_STAGEA(PG8_SA(0, 1), a2 + hstep, voffA);
;             PG8_WAIT_V(8); PG8_WAIT_L(0); PG8_BAR; PG8_MMA(0, 0, At, B0); PG8_MMA(0, 1, At, B1); PG8_BAR; PG8_SCHED;
	s_setprio 1
	s_waitcnt lgkmcnt(0)
	v_mfma_f32_16x16x32_bf16 v[62:65], v[82:85], v[184:187], v[62:65]
	v_mfma_f32_16x16x32_bf16 v[58:61], v[94:97], v[184:187], v[58:61]
	v_mfma_f32_16x16x32_bf16 v[46:49], v[82:85], v[192:195], v[46:49]
	v_mfma_f32_16x16x32_bf16 v[42:45], v[94:97], v[192:195], v[42:45]
	v_mfma_f32_16x16x32_bf16 v[30:33], v[82:85], v[200:203], v[30:33]
	v_mfma_f32_16x16x32_bf16 v[26:29], v[94:97], v[200:203], v[26:29]
	v_mfma_f32_16x16x32_bf16 v[14:17], v[82:85], v[208:211], v[14:17]
	v_mfma_f32_16x16x32_bf16 v[10:13], v[94:97], v[208:211], v[10:13]
	v_mfma_f32_16x16x32_bf16 v[62:65], v[90:93], v[188:191], v[62:65]
	v_mfma_f32_16x16x32_bf16 v[58:61], v[158:161], v[188:191], v[58:61]
	v_mfma_f32_16x16x32_bf16 v[46:49], v[90:93], v[196:199], v[46:49]
	v_mfma_f32_16x16x32_bf16 v[42:45], v[158:161], v[196:199], v[42:45]
	v_mfma_f32_16x16x32_bf16 v[30:33], v[90:93], v[204:207], v[30:33]
	v_mfma_f32_16x16x32_bf16 v[26:29], v[158:161], v[204:207], v[26:29]
	v_mfma_f32_16x16x32_bf16 v[14:17], v[90:93], v[212:215], v[14:17]
	v_mfma_f32_16x16x32_bf16 v[10:13], v[158:161], v[212:215], v[10:13]
	s_setprio 0
	s_setprio 1
	v_mfma_f32_16x16x32_bf16 v[54:57], v[168:171], v[184:187], v[54:57]
	v_mfma_f32_16x16x32_bf16 v[50:53], v[176:179], v[184:187], v[50:53]
	v_mfma_f32_16x16x32_bf16 v[38:41], v[168:171], v[192:195], v[38:41]
	v_mfma_f32_16x16x32_bf16 v[34:37], v[176:179], v[192:195], v[34:37]
	v_mfma_f32_16x16x32_bf16 v[22:25], v[168:171], v[200:203], v[22:25]
	v_mfma_f32_16x16x32_bf16 v[18:21], v[176:179], v[200:203], v[18:21]
	v_mfma_f32_16x16x32_bf16 v[6:9], v[168:171], v[208:211], v[6:9]
	v_mfma_f32_16x16x32_bf16 v[2:5], v[176:179], v[208:211], v[2:5]
	v_mfma_f32_16x16x32_bf16 v[54:57], v[172:175], v[188:191], v[54:57]
	v_mfma_f32_16x16x32_bf16 v[50:53], v[180:183], v[188:191], v[50:53]
	v_mfma_f32_16x16x32_bf16 v[38:41], v[172:175], v[196:199], v[38:41]
	v_mfma_f32_16x16x32_bf16 v[34:37], v[180:183], v[196:199], v[34:37]
	v_mfma_f32_16x16x32_bf16 v[22:25], v[172:175], v[204:207], v[22:25]
	v_mfma_f32_16x16x32_bf16 v[18:21], v[180:183], v[204:207], v[18:21]
	v_mfma_f32_16x16x32_bf16 v[6:9], v[172:175], v[212:215], v[6:9]
	v_mfma_f32_16x16x32_bf16 v[2:5], v[180:183], v[212:215], v[2:5]
	s_setprio 0
	s_barrier
	v_add_u32_e32 v158, s93, v162
	v_add_u32_e32 v180, s94, v162
	ds_read_b128 v[82:85], v158
	ds_read_b128 v[90:93], v158 offset:1024
	ds_read_b128 v[94:97], v158 offset:2048
	ds_read_b128 v[158:161], v158 offset:3072
	ds_read_b128 v[168:171], v180
	ds_read_b128 v[172:175], v180 offset:1024
	ds_read_b128 v[176:179], v180 offset:2048
	ds_read_b128 v[180:183], v180 offset:3072
	s_mov_b32 m0, s33
	v_lshl_add_u64 v[224:225], s[70:71], 0, v[146:147]
	ds_read_b128 v[184:187], v166 offset:32768
	ds_read_b128 v[188:191], v166 offset:33792
	ds_read_b128 v[192:195], v166 offset:34816
	ds_read_b128 v[196:199], v166 offset:35840
	ds_read_b128 v[200:203], v166 offset:36864
	ds_read_b128 v[204:207], v166 offset:37888
	ds_read_b128 v[208:211], v166 offset:38912
	ds_read_b128 v[212:215], v166 offset:39936
	global_load_lds_dwordx4 v[224:225], off
	v_lshl_add_u64 v[224:225], s[70:71], 0, v[148:149]
	s_mov_b32 m0, s59
	s_nop 0
	global_load_lds_dwordx4 v[224:225], off
	s_waitcnt vmcnt(8)
	s_waitcnt lgkmcnt(0)
	s_barrier
	s_setprio 1
	s_waitcnt lgkmcnt(0)
	v_mfma_f32_16x16x32_bf16 v[142:145], v[82:85], v[184:187], v[142:145]
	v_mfma_f32_16x16x32_bf16 v[138:141], v[94:97], v[184:187], v[138:141]
	v_mfma_f32_16x16x32_bf16 v[126:129], v[82:85], v[192:195], v[126:129]
	v_mfma_f32_16x16x32_bf16 v[122:125], v[94:97], v[192:195], v[122:125]
	v_mfma_f32_16x16x32_bf16 v[110:113], v[82:85], v[200:203], v[110:113]
	v_mfma_f32_16x16x32_bf16 v[106:109], v[94:97], v[200:203], v[106:109]
	v_mfma_f32_16x16x32_bf16 v[86:89], v[82:85], v[208:211], v[86:89]
	v_mfma_f32_16x16x32_bf16 v[78:81], v[94:97], v[208:211], v[78:81]
	v_mfma_f32_16x16x32_bf16 v[142:145], v[90:93], v[188:191], v[142:145]
	v_mfma_f32_16x16x32_bf16 v[138:141], v[158:161], v[188:191], v[138:141]
	v_mfma_f32_16x16x32_bf16 v[126:129], v[90:93], v[196:199], v[126:129]
	v_mfma_f32_16x16x32_bf16 v[122:125], v[158:161], v[196:199], v[122:125]
	v_mfma_f32_16x16x32_bf16 v[110:113], v[90:93], v[204:207], v[110:113]
	v_mfma_f32_16x16x32_bf16 v[106:109], v[158:161], v[204:207], v[106:109]
	v_mfma_f32_16x16x32_bf16 v[86:89], v[90:93], v[212:215], v[86:89]
	v_mfma_f32_16x16x32_bf16 v[78:81], v[158:161], v[212:215], v[78:81]
	s_setprio 0
	s_setprio 1
	v_mfma_f32_16x16x32_bf16 v[134:137], v[168:171], v[184:187], v[134:137]
	v_mfma_f32_16x16x32_bf16 v[130:133], v[176:179], v[184:187], v[130:133]
	v_mfma_f32_16x16x32_bf16 v[118:121], v[168:171], v[192:195], v[118:121]
	v_mfma_f32_16x16x32_bf16 v[114:117], v[176:179], v[192:195], v[114:117]
	v_mfma_f32_16x16x32_bf16 v[102:105], v[168:171], v[200:203], v[102:105]
	v_mfma_f32_16x16x32_bf16 v[98:101], v[176:179], v[200:203], v[98:101]
	v_mfma_f32_16x16x32_bf16 v[74:77], v[168:171], v[208:211], v[74:77]
	v_mfma_f32_16x16x32_bf16 v[66:69], v[176:179], v[208:211], v[66:69]
	v_mfma_f32_16x16x32_bf16 v[134:137], v[172:175], v[188:191], v[134:137]
	v_mfma_f32_16x16x32_bf16 v[130:133], v[180:183], v[188:191], v[130:133]
	v_mfma_f32_16x16x32_bf16 v[118:121], v[172:175], v[196:199], v[118:121]
	v_mfma_f32_16x16x32_bf16 v[114:117], v[180:183], v[196:199], v[114:117]
	v_mfma_f32_16x16x32_bf16 v[102:105], v[172:175], v[204:207], v[102:105]
	v_mfma_f32_16x16x32_bf16 v[98:101], v[180:183], v[204:207], v[98:101]
	v_mfma_f32_16x16x32_bf16 v[74:77], v[172:175], v[212:215], v[74:77]
	v_mfma_f32_16x16x32_bf16 v[66:69], v[180:183], v[212:215], v[66:69]
	s_setprio 0
	s_barrier
; #define PG8_STAGEA(bufoff, gbase, voff) PG8_STAGE_X(bufoff, gbase, voff, PG8_AUX_A)
; #define PG8_STAGEB(bufoff, gbase, voff) PG8_STAGE_X(bufoff, gbase, voff, PG8_AUX_B)
; #define PG8_LDA(dst, b, h) do { _Pragma("unroll") for (int m = 0; m < 4; ++m) _Pragma("unroll") for (int k = 0; k < 2; ++k) dst[m][k] = *(const PG8_LAS bf16x8*)(lds + PG8_SA(b, h) + aoff + m * 2048 + k * 1024); } while (0)
; #define PG8_MMA(ai, bj, At, Bt) do { __builtin_amdgcn_s_setprio(1); _Pragma("unroll") for (int m = 0; m < 4; ++m) _Pragma("unroll") for (int n = 0; n < 2; ++n) _Pragma("unroll") for (int k = 0; k < 2; ++k) \
;         acc[ai][bj][m][n] = __builtin_amdgcn_mfma_f32_16x16x32_bf16(Bt[n][k], At[m][k], acc[ai][bj][m][n], 0, 0, 0); __builtin_amdgcn_s_setprio(0); } while (0)
; #define PG8_WAIT_V(n) asm volatile("s_waitcnt vmcnt(" #n ")" ::: "memory")
; #define PG8_WAIT_L(n) asm volatile("s_waitcnt lgkmcnt(" #n ")" ::: "memory")
; #define PG8_BAR __builtin_amdgcn_s_barrier()
; #define PG8_SCHED __builtin_amdgcn_sched_barrier(0)
; template <class Epi, class Sched, bool ALIGN_EPI = false, bool SP2 = false>
; __device__ __forceinline__ void gemm_phase(PG8_LAS unsigned char* lds, const Gemm g, const Sched& S, const Epi& E) {
;     ...
;             PG8_WAIT_V(8); PG8_WAIT_L(0); PG8_BAR; PG8_MMA(0, 0, At, B0); PG8_MMA(0, 1, At, B1); PG8_BAR; PG8_SCHED;
;             PG8_LDA(At, 1, 1); PG8_STAGEB(PG8_SB(1, 0), b3, voffB); PG8_STAGEB(PG8_SB(1, 1), b3 + hstep, voffB); PG8_STAGEA(PG8_SA(1, 0), a3, voffA);
;             PG8_WAIT_V(8); PG8_WAIT_L(0); PG8_BAR; PG8_MMA(1, 0, At, B0); PG8_MMA(1, 1, At, B1); PG8_BAR; PG8_SCHED;
	s_mov_b32 m0, s90
	v_lshl_add_u64 v[216:217], v[216:217], 0, s[44:45]
	ds_read_b128 v[184:187], v166 offset:49152
	ds_read_b128 v[188:191], v166 offset:50176
	ds_read_b128 v[192:195], v166 offset:51200
	ds_read_b128 v[196:199], v166 offset:52224
	ds_read_b128 v[200:203], v166 offset:53248
	ds_read_b128 v[204:207], v166 offset:54272
	ds_read_b128 v[208:211], v166 offset:55296
	ds_read_b128 v[212:215], v166 offset:56320
	global_load_lds_dwordx4 v[216:217], off
	v_lshl_add_u64 v[216:217], v[218:219], 0, s[44:45]
	s_mov_b32 m0, s88
	s_nop 0
	global_load_lds_dwordx4 v[216:217], off
	v_lshl_add_u64 v[216:217], s[68:69], 0, v[146:147]
	s_mov_b32 m0, s89
	s_nop 0
	global_load_lds_dwordx4 v[216:217], off
	v_lshl_add_u64 v[216:217], s[68:69], 0, v[148:149]
	s_mov_b32 m0, s91
	s_nop 0
	global_load_lds_dwordx4 v[216:217], off
	v_lshl_add_u64 v[216:217], v[220:221], 0, s[44:45]
	s_mov_b32 m0, s79
	s_nop 0
	global_load_lds_dwordx4 v[216:217], off
	v_lshl_add_u64 v[216:217], v[222:223], 0, s[44:45]
	s_mov_b32 m0, s80
	s_nop 0
	global_load_lds_dwordx4 v[216:217], off
	s_waitcnt vmcnt(8)
	s_waitcnt lgkmcnt(0)
	s_barrier
	s_setprio 1
	s_waitcnt lgkmcnt(0)
	v_mfma_f32_16x16x32_bf16 v[62:65], v[82:85], v[184:187], v[62:65]
	v_mfma_f32_16x16x32_bf16 v[58:61], v[94:97], v[184:187], v[58:61]
	v_mfma_f32_16x16x32_bf16 v[46:49], v[82:85], v[192:195], v[46:49]
	v_mfma_f32_16x16x32_bf16 v[42:45], v[94:97], v[192:195], v[42:45]
	v_mfma_f32_16x16x32_bf16 v[30:33], v[82:85], v[200:203], v[30:33]
	v_mfma_f32_16x16x32_bf16 v[26:29], v[94:97], v[200:203], v[26:29]
	v_mfma_f32_16x16x32_bf16 v[14:17], v[82:85], v[208:211], v[14:17]
	v_mfma_f32_16x16x32_bf16 v[10:13], v[94:97], v[208:211], v[10:13]
	v_mfma_f32_16x16x32_bf16 v[62:65], v[90:93], v[188:191], v[62:65]
	v_mfma_f32_16x16x32_bf16 v[58:61], v[158:161], v[188:191], v[58:61]
	v_mfma_f32_16x16x32_bf16 v[46:49], v[90:93], v[196:199], v[46:49]
	v_mfma_f32_16x16x32_bf16 v[42:45], v[158:161], v[196:199], v[42:45]
	v_mfma_f32_16x16x32_bf16 v[30:33], v[90:93], v[204:207], v[30:33]
	v_mfma_f32_16x16x32_bf16 v[26:29], v[158:161], v[204:207], v[26:29]
	v_mfma_f32_16x16x32_bf16 v[14:17], v[90:93], v[212:215], v[14:17]
	v_mfma_f32_16x16x32_bf16 v[10:13], v[158:161], v[212:215], v[10:13]
	s_setprio 0
	s_setprio 1
	v_mfma_f32_16x16x32_bf16 v[54:57], v[168:171], v[184:187], v[54:57]
	v_mfma_f32_16x16x32_bf16 v[50:53], v[176:179], v[184:187], v[50:53]
	v_mfma_f32_16x16x32_bf16 v[38:41], v[168:171], v[192:195], v[38:41]
	v_mfma_f32_16x16x32_bf16 v[34:37], v[176:179], v[192:195], v[34:37]
	v_mfma_f32_16x16x32_bf16 v[22:25], v[168:171], v[200:203], v[22:25]
	v_mfma_f32_16x16x32_bf16 v[18:21], v[176:179], v[200:203], v[18:21]
	v_mfma_f32_16x16x32_bf16 v[6:9], v[168:171], v[208:211], v[6:9]
	v_mfma_f32_16x16x32_bf16 v[2:5], v[176:179], v[208:211], v[2:5]
	v_mfma_f32_16x16x32_bf16 v[54:57], v[172:175], v[188:191], v[54:57]
	v_mfma_f32_16x16x32_bf16 v[50:53], v[180:183], v[188:191], v[50:53]
	v_mfma_f32_16x16x32_bf16 v[38:41], v[172:175], v[196:199], v[38:41]
	v_mfma_f32_16x16x32_bf16 v[34:37], v[180:183], v[196:199], v[34:37]
	v_mfma_f32_16x16x32_bf16 v[22:25], v[172:175], v[204:207], v[22:25]
	v_mfma_f32_16x16x32_bf16 v[18:21], v[180:183], v[204:207], v[18:21]
	v_mfma_f32_16x16x32_bf16 v[6:9], v[172:175], v[212:215], v[6:9]
	v_mfma_f32_16x16x32_bf16 v[2:5], v[180:183], v[212:215], v[2:5]
	s_setprio 0
	s_barrier
	s_mov_b64 s[64:65], s[66:67]
	s_mov_b32 s66, s87
	s_cbranch_scc0 .LBB0_920
	s_and_b64 vcc, exec, s[46:47]
	s_cbranch_vccz .LBB0_923
	s_barrier

; #define PG8_STAGEA(bufoff, gbase, voff) PG8_STAGE_X(bufoff, gbase, voff, PG8_AUX_A)
; #define PG8_STAGEB(bufoff, gbase, voff) PG8_STAGE_X(bufoff, gbase, voff, PG8_AUX_B)
; #define PG8_LDA(dst, b, h) do { _Pragma("unroll") for (int m = 0; m < 4; ++m) _Pragma("unroll") for (int k = 0; k < 2; ++k) dst[m][k] = *(const PG8_LAS bf16x8*)(lds + PG8_SA(b, h) + aoff + m * 2048 + k * 1024); } while (0)
; #define PG8_LDB(dst, b, h) do { _Pragma("unroll") for (int n = 0; n < 2; ++n) _Pragma("unroll") for (int k = 0; k < 2; ++k) dst[n][k] = *(const PG8_LAS bf16x8*)(lds + PG8_SB(b, h) + boff + n * 2048 + k * 1024); } while (0)
; #define PG8_MMA(ai, bj, At, Bt) do { __builtin_amdgcn_s_setprio(1); _Pragma("unroll") for (int m = 0; m < 4; ++m) _Pragma("unroll") for (int n = 0; n < 2; ++n) _Pragma("unroll") for (int k = 0; k < 2; ++k) \
;         acc[ai][bj][m][n] = __builtin_amdgcn_mfma_f32_16x16x32_bf16(Bt[n][k], At[m][k], acc[ai][bj][m][n], 0, 0, 0); __builtin_amdgcn_s_setprio(0); } while (0)
; #define PG8_WAIT_V(n) asm volatile("s_waitcnt vmcnt(" #n ")" ::: "memory")
; #define PG8_WAIT_L(n) asm volatile("s_waitcnt lgkmcnt(" #n ")" ::: "memory")
; template <class Epi, class Sched, bool ALIGN_EPI = false, bool SP2 = false>
; __device__ __forceinline__ void gemm_phase(PG8_LAS unsigned char* lds, const Gemm g, const Sched& S, const Epi& E) {
;     ...
;             const char* sA1 = (t + 1 >= ns) ? cA2 : cA; const char* sA2 = (t + 2 >= ns) ? cA2 : cA; const char* sB2 = (t + 2 >= ns) ? cB2 : cB;
;             const char* a1 = sA1 + (size_t)(t + 1) * kstep;
;             const char* a2 = last ? nA : sA2 + (size_t)(t + 2) * kstep; const char* b2 = last ? nB : sB2 + (size_t)(t + 2) * kstep;
;             const char* a3 = a2 + kstep; const char* b3 = b2 + kstep;
;             if (last && has_next) S.a_ready(nxt);
;             if constexpr (SP2) {
;             PG8_LDB(B0, 0, 0); PG8_LDB(B1, 0, 1); PG8_SCHED; PG8_LDA(At, 0, 0); PG8_STAGEA(PG8_SA(1, 1), a1 + hstep, voffA);
;             PG8_WAIT_V(8); PG8_WAIT_L(0); PG8_BAR; PG8_MMA(0, 0, At, B0); PG8_MMA(0, 1, At, B1); PG8_BAR; PG8_SCHED;
;             PG8_LDA(At, 0, 1); PG8_STAGEB(PG8_SB(0, 0), b2, voffB); PG8_STAGEB(PG8_SB(0, 1), b2 + hstep, voffB); PG8_STAGEA(PG8_SA(0, 0), a2, voffA);
;             PG8_WAIT_V(8); PG8_WAIT_L(0); PG8_BAR; PG8_MMA(1, 0, At, B0); PG8_MMA(1, 1, At, B1); PG8_BAR; PG8_SCHED;
.LBB0_1007:
	ds_read_b128 v[158:161], v152
	ds_read_b128 v[162:165], v152 offset:1024
	ds_read_b128 v[166:169], v152 offset:2048
	ds_read_b128 v[170:173], v152 offset:3072
	ds_read_b128 v[174:177], v153
	ds_read_b128 v[178:181], v153 offset:1024
	ds_read_b128 v[182:185], v153 offset:2048
	ds_read_b128 v[186:189], v153 offset:3072
	ds_read_b128 v[190:193], v154
	ds_read_b128 v[194:197], v154 offset:1024
	ds_read_b128 v[198:201], v154 offset:2048
	ds_read_b128 v[202:205], v154 offset:3072
	ds_read_b128 v[206:209], v154 offset:4096
	ds_read_b128 v[210:213], v154 offset:5120
	ds_read_b128 v[214:217], v154 offset:6144
	ds_read_b128 v[218:221], v154 offset:7168
	s_add_i32 s76, s58, 2
	s_cmp_gt_u32 s76, 29
	s_cselect_b64 s[60:61], -1, 0
	s_and_b64 vcc, s[60:61], exec
	s_cselect_b32 s29, s34, s54
	s_cselect_b32 s24, s27, s53
	s_cselect_b32 s25, s26, s52
	s_cselect_b32 s28, s35, s55
	s_add_u32 s29, s29, s56
	s_addc_u32 s28, s28, s57
	s_add_u32 s29, s29, 0xfff80080
	s_addc_u32 s28, s28, -1
	s_add_u32 s25, s25, s56
	s_addc_u32 s24, s24, s57
	s_add_u32 s25, s25, 0xfff80080
	s_addc_u32 s24, s24, -1
	s_cmp_eq_u32 s58, 28
	s_cselect_b32 s58, s75, s25
	s_cselect_b32 s61, s47, s28
	s_cselect_b32 s60, s74, s29
	s_cselect_b32 s59, s45, s24
	v_lshl_add_u64 v[222:223], v[146:147], 0, s[56:57]
	s_add_i32 m0, s33, 0xc000
	global_load_lds_dwordx4 v[222:223], off
	v_lshl_add_u64 v[222:223], v[148:149], 0, s[56:57]
	s_add_i32 m0, s33, 0xe000
	s_nop 0
	global_load_lds_dwordx4 v[222:223], off
	s_waitcnt vmcnt(8)
	s_waitcnt lgkmcnt(0)
	s_barrier
	s_setprio 1
	s_waitcnt lgkmcnt(0)
	v_mfma_f32_16x16x32_bf16 v[118:121], v[158:161], v[190:193], v[118:121]
	v_mfma_f32_16x16x32_bf16 v[114:117], v[166:169], v[190:193], v[114:117]
	v_mfma_f32_16x16x32_bf16 v[102:105], v[158:161], v[198:201], v[102:105]
	v_mfma_f32_16x16x32_bf16 v[98:101], v[166:169], v[198:201], v[98:101]
	v_mfma_f32_16x16x32_bf16 v[86:89], v[158:161], v[206:209], v[86:89]
	v_mfma_f32_16x16x32_bf16 v[82:85], v[166:169], v[206:209], v[82:85]
	v_mfma_f32_16x16x32_bf16 v[70:73], v[158:161], v[214:217], v[70:73]
	v_mfma_f32_16x16x32_bf16 v[66:69], v[166:169], v[214:217], v[66:69]
	v_mfma_f32_16x16x32_bf16 v[118:121], v[162:165], v[194:197], v[118:121]
	v_mfma_f32_16x16x32_bf16 v[114:117], v[170:173], v[194:197], v[114:117]
	v_mfma_f32_16x16x32_bf16 v[102:105], v[162:165], v[202:205], v[102:105]
	v_mfma_f32_16x16x32_bf16 v[98:101], v[170:173], v[202:205], v[98:101]
	v_mfma_f32_16x16x32_bf16 v[86:89], v[162:165], v[210:213], v[86:89]
	v_mfma_f32_16x16x32_bf16 v[82:85], v[170:173], v[210:213], v[82:85]
	v_mfma_f32_16x16x32_bf16 v[70:73], v[162:165], v[218:221], v[70:73]
	v_mfma_f32_16x16x32_bf16 v[66:69], v[170:173], v[218:221], v[66:69]
	s_setprio 0
	s_setprio 1
	v_mfma_f32_16x16x32_bf16 v[126:129], v[174:177], v[190:193], v[126:129]
	v_mfma_f32_16x16x32_bf16 v[122:125], v[182:185], v[190:193], v[122:125]
	v_mfma_f32_16x16x32_bf16 v[110:113], v[174:177], v[198:201], v[110:113]
	v_mfma_f32_16x16x32_bf16 v[106:109], v[182:185], v[198:201], v[106:109]
	v_mfma_f32_16x16x32_bf16 v[94:97], v[174:177], v[206:209], v[94:97]
	v_mfma_f32_16x16x32_bf16 v[90:93], v[182:185], v[206:209], v[90:93]
	v_mfma_f32_16x16x32_bf16 v[78:81], v[174:177], v[214:217], v[78:81]
	v_mfma_f32_16x16x32_bf16 v[74:77], v[182:185], v[214:217], v[74:77]
	v_mfma_f32_16x16x32_bf16 v[126:129], v[178:181], v[194:197], v[126:129]
	v_mfma_f32_16x16x32_bf16 v[122:125], v[186:189], v[194:197], v[122:125]
	v_mfma_f32_16x16x32_bf16 v[110:113], v[178:181], v[202:205], v[110:113]
	v_mfma_f32_16x16x32_bf16 v[106:109], v[186:189], v[202:205], v[106:109]
	v_mfma_f32_16x16x32_bf16 v[94:97], v[178:181], v[210:213], v[94:97]
	v_mfma_f32_16x16x32_bf16 v[90:93], v[186:189], v[210:213], v[90:93]
	v_mfma_f32_16x16x32_bf16 v[78:81], v[178:181], v[218:221], v[78:81]
	v_mfma_f32_16x16x32_bf16 v[74:77], v[186:189], v[218:221], v[74:77]
	s_setprio 0
	s_barrier
	s_add_i32 s24, s70, s11
	v_lshl_add_u64 v[222:223], s[58:59], 0, v[134:135]
	s_mov_b32 m0, s24
	ds_read_b128 v[190:193], v154 offset:16384
	ds_read_b128 v[194:197], v154 offset:17408
	ds_read_b128 v[198:201], v154 offset:18432
	ds_read_b128 v[202:205], v154 offset:19456
	ds_read_b128 v[206:209], v154 offset:20480
	ds_read_b128 v[210:213], v154 offset:21504
	ds_read_b128 v[214:217], v154 offset:22528
	ds_read_b128 v[218:221], v154 offset:23552
	global_load_lds_dwordx4 v[222:223], off
	s_add_i32 m0, s24, 0x2000
	s_add_u32 s78, s58, 0x80000
	v_lshl_add_u64 v[224:225], s[58:59], 0, v[130:131]
	s_addc_u32 s79, s59, 0
	s_add_i32 s24, s71, s11
	global_load_lds_dwordx4 v[224:225], off
	v_lshl_add_u64 v[226:227], s[78:79], 0, v[134:135]
	s_mov_b32 m0, s24
	v_lshl_add_u64 v[228:229], s[60:61], 0, v[132:133]
	global_load_lds_dwordx4 v[226:227], off
	v_lshl_add_u64 v[226:227], s[78:79], 0, v[130:131]
	s_add_i32 m0, s24, 0x2000
	s_nop 0
	global_load_lds_dwordx4 v[226:227], off
	v_lshl_add_u64 v[226:227], s[60:61], 0, v[136:137]
	s_mov_b32 m0, s33
	s_nop 0
	global_load_lds_dwordx4 v[226:227], off
	s_mov_b32 m0, s62
	s_nop 0
	global_load_lds_dwordx4 v[228:229], off
	s_waitcnt vmcnt(8)
	s_waitcnt lgkmcnt(0)
	s_barrier
; #define PG8_STAGEA(bufoff, gbase, voff) PG8_STAGE_X(bufoff, gbase, voff, PG8_AUX_A)
; #define PG8_LDA(dst, b, h) do { _Pragma("unroll") for (int m = 0; m < 4; ++m) _Pragma("unroll") for (int k = 0; k < 2; ++k) dst[m][k] = *(const PG8_LAS bf16x8*)(lds + PG8_SA(b, h) + aoff + m * 2048 + k * 1024); } while (0)
; #define PG8_LDB(dst, b, h) do { _Pragma("unroll") for (int n = 0; n < 2; ++n) _Pragma("unroll") for (int k = 0; k < 2; ++k) dst[n][k] = *(const PG8_LAS bf16x8*)(lds + PG8_SB(b, h) + boff + n * 2048 + k * 1024); } while (0)
; #define PG8_MMA(ai, bj, At, Bt) do { __builtin_amdgcn_s_setprio(1); _Pragma("unroll") for (int m = 0; m < 4; ++m) _Pragma("unroll") for (int n = 0; n < 2; ++n) _Pragma("unroll") for (int k = 0; k < 2; ++k) \
;         acc[ai][bj][m][n] = __builtin_amdgcn_mfma_f32_16x16x32_bf16(Bt[n][k], At[m][k], acc[ai][bj][m][n], 0, 0, 0); __builtin_amdgcn_s_setprio(0); } while (0)
; #define PG8_WAIT_V(n) asm volatile("s_waitcnt vmcnt(" #n ")" ::: "memory")
; #define PG8_WAIT_L(n) asm volatile("s_waitcnt lgkmcnt(" #n ")" ::: "memory")
; #define PG8_BAR __builtin_amdgcn_s_barrier()
; #define PG8_SCHED __builtin_amdgcn_sched_barrier(0)
; template <class Epi, class Sched, bool ALIGN_EPI = false, bool SP2 = false>
; __device__ __forceinline__ void gemm_phase(PG8_LAS unsigned char* lds, const Gemm g, const Sched& S, const Epi& E) {
;     ...
;             PG8_WAIT_V(8); PG8_WAIT_L(0); PG8_BAR; PG8_MMA(1, 0, At, B0); PG8_MMA(1, 1, At, B1); PG8_BAR; PG8_SCHED;
;             PG8_LDB(B0, 1, 0); PG8_LDB(B1, 1, 1); PG8_SCHED; PG8_LDA(At, 1, 0); PG8_STAGEA(PG8_SA(0, 1), a2 + hstep, voffA);
;             PG8_WAIT_V(8); PG8_WAIT_L(0); PG8_BAR; PG8_MMA(0, 0, At, B0); PG8_MMA(0, 1, At, B1); PG8_BAR; PG8_SCHED;
	s_setprio 1
	s_waitcnt lgkmcnt(0)
	v_mfma_f32_16x16x32_bf16 v[54:57], v[158:161], v[190:193], v[54:57]
	v_mfma_f32_16x16x32_bf16 v[50:53], v[166:169], v[190:193], v[50:53]
	v_mfma_f32_16x16x32_bf16 v[38:41], v[158:161], v[198:201], v[38:41]
	v_mfma_f32_16x16x32_bf16 v[34:37], v[166:169], v[198:201], v[34:37]
	v_mfma_f32_16x16x32_bf16 v[22:25], v[158:161], v[206:209], v[22:25]
	v_mfma_f32_16x16x32_bf16 v[18:21], v[166:169], v[206:209], v[18:21]
	v_mfma_f32_16x16x32_bf16 v[6:9], v[158:161], v[214:217], v[6:9]
	v_mfma_f32_16x16x32_bf16 v[2:5], v[166:169], v[214:217], v[2:5]
	v_mfma_f32_16x16x32_bf16 v[54:57], v[162:165], v[194:197], v[54:57]
	v_mfma_f32_16x16x32_bf16 v[50:53], v[170:173], v[194:197], v[50:53]
	v_mfma_f32_16x16x32_bf16 v[38:41], v[162:165], v[202:205], v[38:41]
	v_mfma_f32_16x16x32_bf16 v[34:37], v[170:173], v[202:205], v[34:37]
	v_mfma_f32_16x16x32_bf16 v[22:25], v[162:165], v[210:213], v[22:25]
	v_mfma_f32_16x16x32_bf16 v[18:21], v[170:173], v[210:213], v[18:21]
	v_mfma_f32_16x16x32_bf16 v[6:9], v[162:165], v[218:221], v[6:9]
	v_mfma_f32_16x16x32_bf16 v[2:5], v[170:173], v[218:221], v[2:5]
	s_setprio 0
	s_setprio 1
	v_mfma_f32_16x16x32_bf16 v[62:65], v[174:177], v[190:193], v[62:65]
	v_mfma_f32_16x16x32_bf16 v[58:61], v[182:185], v[190:193], v[58:61]
	v_mfma_f32_16x16x32_bf16 v[46:49], v[174:177], v[198:201], v[46:49]
	v_mfma_f32_16x16x32_bf16 v[42:45], v[182:185], v[198:201], v[42:45]
	v_mfma_f32_16x16x32_bf16 v[30:33], v[174:177], v[206:209], v[30:33]
	v_mfma_f32_16x16x32_bf16 v[26:29], v[182:185], v[206:209], v[26:29]
	v_mfma_f32_16x16x32_bf16 v[14:17], v[174:177], v[214:217], v[14:17]
	v_mfma_f32_16x16x32_bf16 v[10:13], v[182:185], v[214:217], v[10:13]
	v_mfma_f32_16x16x32_bf16 v[62:65], v[178:181], v[194:197], v[62:65]
	v_mfma_f32_16x16x32_bf16 v[58:61], v[186:189], v[194:197], v[58:61]
	v_mfma_f32_16x16x32_bf16 v[46:49], v[178:181], v[202:205], v[46:49]
	v_mfma_f32_16x16x32_bf16 v[42:45], v[186:189], v[202:205], v[42:45]
	v_mfma_f32_16x16x32_bf16 v[30:33], v[178:181], v[210:213], v[30:33]
	v_mfma_f32_16x16x32_bf16 v[26:29], v[186:189], v[210:213], v[26:29]
	v_mfma_f32_16x16x32_bf16 v[14:17], v[178:181], v[218:221], v[14:17]
	v_mfma_f32_16x16x32_bf16 v[10:13], v[186:189], v[218:221], v[10:13]
	s_setprio 0
	s_barrier
	s_add_i32 s24, 0, 0x18000
	v_add_u32_e32 v157, s24, v150
	s_add_i32 s25, 0, 0x1c000
	ds_read_b128 v[158:161], v157
	ds_read_b128 v[162:165], v157 offset:1024
	ds_read_b128 v[166:169], v157 offset:2048
	ds_read_b128 v[170:173], v157 offset:3072
	v_add_u32_e32 v157, s25, v150
	ds_read_b128 v[174:177], v157
	ds_read_b128 v[178:181], v157 offset:1024
	ds_read_b128 v[182:185], v157 offset:2048
	ds_read_b128 v[186:189], v157 offset:3072
	s_add_u32 s60, s60, 0x80000
	s_addc_u32 s61, s61, 0
	s_mov_b32 m0, s63
	v_lshl_add_u64 v[230:231], s[60:61], 0, v[136:137]
	ds_read_b128 v[190:193], v154 offset:32768
	ds_read_b128 v[194:197], v154 offset:33792
	ds_read_b128 v[198:201], v154 offset:34816
	ds_read_b128 v[202:205], v154 offset:35840
	ds_read_b128 v[206:209], v154 offset:36864
	ds_read_b128 v[210:213], v154 offset:37888
	ds_read_b128 v[214:217], v154 offset:38912
	ds_read_b128 v[218:221], v154 offset:39936
	global_load_lds_dwordx4 v[230:231], off
	v_lshl_add_u64 v[230:231], s[60:61], 0, v[132:133]
	s_mov_b32 m0, s64
	s_nop 0
	global_load_lds_dwordx4 v[230:231], off
	s_waitcnt vmcnt(8)
	s_waitcnt lgkmcnt(0)
	s_barrier
	s_setprio 1
	s_waitcnt lgkmcnt(0)
	v_mfma_f32_16x16x32_bf16 v[118:121], v[158:161], v[190:193], v[118:121]
	v_mfma_f32_16x16x32_bf16 v[114:117], v[166:169], v[190:193], v[114:117]
	v_mfma_f32_16x16x32_bf16 v[102:105], v[158:161], v[198:201], v[102:105]
	v_mfma_f32_16x16x32_bf16 v[98:101], v[166:169], v[198:201], v[98:101]
	v_mfma_f32_16x16x32_bf16 v[86:89], v[158:161], v[206:209], v[86:89]
	v_mfma_f32_16x16x32_bf16 v[82:85], v[166:169], v[206:209], v[82:85]
	v_mfma_f32_16x16x32_bf16 v[70:73], v[158:161], v[214:217], v[70:73]
	v_mfma_f32_16x16x32_bf16 v[66:69], v[166:169], v[214:217], v[66:69]
	v_mfma_f32_16x16x32_bf16 v[118:121], v[162:165], v[194:197], v[118:121]
	v_mfma_f32_16x16x32_bf16 v[114:117], v[170:173], v[194:197], v[114:117]
	v_mfma_f32_16x16x32_bf16 v[102:105], v[162:165], v[202:205], v[102:105]
	v_mfma_f32_16x16x32_bf16 v[98:101], v[170:173], v[202:205], v[98:101]
	v_mfma_f32_16x16x32_bf16 v[86:89], v[162:165], v[210:213], v[86:89]
	v_mfma_f32_16x16x32_bf16 v[82:85], v[170:173], v[210:213], v[82:85]
	v_mfma_f32_16x16x32_bf16 v[70:73], v[162:165], v[218:221], v[70:73]
	v_mfma_f32_16x16x32_bf16 v[66:69], v[170:173], v[218:221], v[66:69]
	s_setprio 0
	s_setprio 1
	v_mfma_f32_16x16x32_bf16 v[126:129], v[174:177], v[190:193], v[126:129]
	v_mfma_f32_16x16x32_bf16 v[122:125], v[182:185], v[190:193], v[122:125]
	v_mfma_f32_16x16x32_bf16 v[110:113], v[174:177], v[198:201], v[110:113]
	v_mfma_f32_16x16x32_bf16 v[106:109], v[182:185], v[198:201], v[106:109]
	v_mfma_f32_16x16x32_bf16 v[94:97], v[174:177], v[206:209], v[94:97]
	v_mfma_f32_16x16x32_bf16 v[90:93], v[182:185], v[206:209], v[90:93]
	v_mfma_f32_16x16x32_bf16 v[78:81], v[174:177], v[214:217], v[78:81]
	v_mfma_f32_16x16x32_bf16 v[74:77], v[182:185], v[214:217], v[74:77]
	v_mfma_f32_16x16x32_bf16 v[126:129], v[178:181], v[194:197], v[126:129]
	v_mfma_f32_16x16x32_bf16 v[122:125], v[186:189], v[194:197], v[122:125]
	v_mfma_f32_16x16x32_bf16 v[110:113], v[178:181], v[202:205], v[110:113]
	v_mfma_f32_16x16x32_bf16 v[106:109], v[186:189], v[202:205], v[106:109]
	v_mfma_f32_16x16x32_bf16 v[94:97], v[178:181], v[210:213], v[94:97]
	v_mfma_f32_16x16x32_bf16 v[90:93], v[186:189], v[210:213], v[90:93]
	v_mfma_f32_16x16x32_bf16 v[78:81], v[178:181], v[218:221], v[78:81]
	v_mfma_f32_16x16x32_bf16 v[74:77], v[186:189], v[218:221], v[74:77]
	s_setprio 0
	s_barrier
; #define PG8_STAGEA(bufoff, gbase, voff) PG8_STAGE_X(bufoff, gbase, voff, PG8_AUX_A)
; #define PG8_STAGEB(bufoff, gbase, voff) PG8_STAGE_X(bufoff, gbase, voff, PG8_AUX_B)
; #define PG8_LDA(dst, b, h) do { _Pragma("unroll") for (int m = 0; m < 4; ++m) _Pragma("unroll") for (int k = 0; k < 2; ++k) dst[m][k] = *(const PG8_LAS bf16x8*)(lds + PG8_SA(b, h) + aoff + m * 2048 + k * 1024); } while (0)
; #define PG8_MMA(ai, bj, At, Bt) do { __builtin_amdgcn_s_setprio(1); _Pragma("unroll") for (int m = 0; m < 4; ++m) _Pragma("unroll") for (int n = 0; n < 2; ++n) _Pragma("unroll") for (int k = 0; k < 2; ++k) \
;         acc[ai][bj][m][n] = __builtin_amdgcn_mfma_f32_16x16x32_bf16(Bt[n][k], At[m][k], acc[ai][bj][m][n], 0, 0, 0); __builtin_amdgcn_s_setprio(0); } while (0)
; #define PG8_WAIT_V(n) asm volatile("s_waitcnt vmcnt(" #n ")" ::: "memory")
; #define PG8_WAIT_L(n) asm volatile("s_waitcnt lgkmcnt(" #n ")" ::: "memory")
; #define PG8_BAR __builtin_amdgcn_s_barrier()
; #define PG8_SCHED __builtin_amdgcn_sched_barrier(0)
; template <class Epi, class Sched, bool ALIGN_EPI = false, bool SP2 = false>
; __device__ __forceinline__ void gemm_phase(PG8_LAS unsigned char* lds, const Gemm g, const Sched& S, const Epi& E) {
;     ...
;             PG8_LDA(At, 1, 1); PG8_STAGEB(PG8_SB(1, 0), b3, voffB); PG8_STAGEB(PG8_SB(1, 1), b3 + hstep, voffB); PG8_STAGEA(PG8_SA(1, 0), a3, voffA);
;             PG8_WAIT_V(8); PG8_WAIT_L(0); PG8_BAR; PG8_MMA(1, 0, At, B0); PG8_MMA(1, 1, At, B1); PG8_BAR; PG8_SCHED;
;     ...
;         if constexpr (ALIGN_EPI) { if (wr == 0) PG8_BAR; }
	s_add_i32 s24, s24, s11
	v_lshl_add_u64 v[222:223], v[222:223], 0, s[40:41]
	s_mov_b32 m0, s24
	ds_read_b128 v[190:193], v154 offset:49152
	ds_read_b128 v[194:197], v154 offset:50176
	ds_read_b128 v[198:201], v154 offset:51200
	ds_read_b128 v[202:205], v154 offset:52224
	ds_read_b128 v[206:209], v154 offset:53248
	ds_read_b128 v[210:213], v154 offset:54272
	ds_read_b128 v[214:217], v154 offset:55296
	ds_read_b128 v[218:221], v154 offset:56320
	global_load_lds_dwordx4 v[222:223], off
	s_add_i32 m0, s24, 0x2000
	s_add_u32 s58, s58, 0x80080
	v_lshl_add_u64 v[222:223], v[224:225], 0, s[40:41]
	s_addc_u32 s59, s59, 0
	s_add_i32 s24, s25, s11
	global_load_lds_dwordx4 v[222:223], off
	v_lshl_add_u64 v[222:223], s[58:59], 0, v[134:135]
	s_mov_b32 m0, s24
	s_nop 0
	global_load_lds_dwordx4 v[222:223], off
	v_lshl_add_u64 v[222:223], s[58:59], 0, v[130:131]
	s_add_i32 m0, s24, 0x2000
	s_nop 0
	global_load_lds_dwordx4 v[222:223], off
	v_lshl_add_u64 v[222:223], v[226:227], 0, s[40:41]
	s_mov_b32 m0, s67
	s_nop 0
	global_load_lds_dwordx4 v[222:223], off
	v_lshl_add_u64 v[222:223], v[228:229], 0, s[40:41]
	s_mov_b32 m0, s68
	s_nop 0
	global_load_lds_dwordx4 v[222:223], off
	s_waitcnt vmcnt(8)
	s_waitcnt lgkmcnt(0)
	s_barrier
	s_setprio 1
	s_waitcnt lgkmcnt(0)
	v_mfma_f32_16x16x32_bf16 v[54:57], v[158:161], v[190:193], v[54:57]
	v_mfma_f32_16x16x32_bf16 v[50:53], v[166:169], v[190:193], v[50:53]
	v_mfma_f32_16x16x32_bf16 v[38:41], v[158:161], v[198:201], v[38:41]
	v_mfma_f32_16x16x32_bf16 v[34:37], v[166:169], v[198:201], v[34:37]
	v_mfma_f32_16x16x32_bf16 v[22:25], v[158:161], v[206:209], v[22:25]
	v_mfma_f32_16x16x32_bf16 v[18:21], v[166:169], v[206:209], v[18:21]
	v_mfma_f32_16x16x32_bf16 v[6:9], v[158:161], v[214:217], v[6:9]
	v_mfma_f32_16x16x32_bf16 v[2:5], v[166:169], v[214:217], v[2:5]
	v_mfma_f32_16x16x32_bf16 v[54:57], v[162:165], v[194:197], v[54:57]
	v_mfma_f32_16x16x32_bf16 v[50:53], v[170:173], v[194:197], v[50:53]
	v_mfma_f32_16x16x32_bf16 v[38:41], v[162:165], v[202:205], v[38:41]
	v_mfma_f32_16x16x32_bf16 v[34:37], v[170:173], v[202:205], v[34:37]
	v_mfma_f32_16x16x32_bf16 v[22:25], v[162:165], v[210:213], v[22:25]
	v_mfma_f32_16x16x32_bf16 v[18:21], v[170:173], v[210:213], v[18:21]
	v_mfma_f32_16x16x32_bf16 v[6:9], v[162:165], v[218:221], v[6:9]
	v_mfma_f32_16x16x32_bf16 v[2:5], v[170:173], v[218:221], v[2:5]
	s_setprio 0
	s_setprio 1
	v_mfma_f32_16x16x32_bf16 v[62:65], v[174:177], v[190:193], v[62:65]
	v_mfma_f32_16x16x32_bf16 v[58:61], v[182:185], v[190:193], v[58:61]
	v_mfma_f32_16x16x32_bf16 v[46:49], v[174:177], v[198:201], v[46:49]
	v_mfma_f32_16x16x32_bf16 v[42:45], v[182:185], v[198:201], v[42:45]
	v_mfma_f32_16x16x32_bf16 v[30:33], v[174:177], v[206:209], v[30:33]
	v_mfma_f32_16x16x32_bf16 v[26:29], v[182:185], v[206:209], v[26:29]
	v_mfma_f32_16x16x32_bf16 v[14:17], v[174:177], v[214:217], v[14:17]
	v_mfma_f32_16x16x32_bf16 v[10:13], v[182:185], v[214:217], v[10:13]
	v_mfma_f32_16x16x32_bf16 v[62:65], v[178:181], v[194:197], v[62:65]
	v_mfma_f32_16x16x32_bf16 v[58:61], v[186:189], v[194:197], v[58:61]
	v_mfma_f32_16x16x32_bf16 v[46:49], v[178:181], v[202:205], v[46:49]
	v_mfma_f32_16x16x32_bf16 v[42:45], v[186:189], v[202:205], v[42:45]
	v_mfma_f32_16x16x32_bf16 v[30:33], v[178:181], v[210:213], v[30:33]
	v_mfma_f32_16x16x32_bf16 v[26:29], v[186:189], v[210:213], v[26:29]
	v_mfma_f32_16x16x32_bf16 v[14:17], v[178:181], v[218:221], v[14:17]
	v_mfma_f32_16x16x32_bf16 v[10:13], v[186:189], v[218:221], v[10:13]
	s_setprio 0
	s_barrier
	s_add_u32 s56, s56, 0x100
	s_addc_u32 s57, s57, 0
	s_mov_b32 s58, s76
	s_cbranch_vccz .LBB0_1007
	s_and_b64 vcc, exec, s[42:43]
	s_cbranch_vccz .LBB0_1010
	s_barrier

; #define PG8_STAGEA(bufoff, gbase, voff) PG8_STAGE_X(bufoff, gbase, voff, PG8_AUX_A)
; #define PG8_STAGEB(bufoff, gbase, voff) PG8_STAGE_X(bufoff, gbase, voff, PG8_AUX_B)
; #define PG8_LDA(dst, b, h) do { _Pragma("unroll") for (int m = 0; m < 4; ++m) _Pragma("unroll") for (int k = 0; k < 2; ++k) dst[m][k] = *(const PG8_LAS bf16x8*)(lds + PG8_SA(b, h) + aoff + m * 2048 + k * 1024); } while (0)
; #define PG8_LDB(dst, b, h) do { _Pragma("unroll") for (int n = 0; n < 2; ++n) _Pragma("unroll") for (int k = 0; k < 2; ++k) dst[n][k] = *(const PG8_LAS bf16x8*)(lds + PG8_SB(b, h) + boff + n * 2048 + k * 1024); } while (0)
; #define PG8_MMA(ai, bj, At, Bt) do { __builtin_amdgcn_s_setprio(1); _Pragma("unroll") for (int m = 0; m < 4; ++m) _Pragma("unroll") for (int n = 0; n < 2; ++n) _Pragma("unroll") for (int k = 0; k < 2; ++k) \
;         acc[ai][bj][m][n] = __builtin_amdgcn_mfma_f32_16x16x32_bf16(Bt[n][k], At[m][k], acc[ai][bj][m][n], 0, 0, 0); __builtin_amdgcn_s_setprio(0); } while (0)
; #define PG8_WAIT_V(n) asm volatile("s_waitcnt vmcnt(" #n ")" ::: "memory")
; #define PG8_WAIT_L(n) asm volatile("s_waitcnt lgkmcnt(" #n ")" ::: "memory")
; template <class Epi, class Sched, bool ALIGN_EPI = false, bool SP2 = false>
; __device__ __forceinline__ void gemm_phase(PG8_LAS unsigned char* lds, const Gemm g, const Sched& S, const Epi& E) {
;     ...
;             const char* sA1 = (t + 1 >= ns) ? cA2 : cA; const char* sA2 = (t + 2 >= ns) ? cA2 : cA; const char* sB2 = (t + 2 >= ns) ? cB2 : cB;
;             const char* a1 = sA1 + (size_t)(t + 1) * kstep;
;             const char* a2 = last ? nA : sA2 + (size_t)(t + 2) * kstep; const char* b2 = last ? nB : sB2 + (size_t)(t + 2) * kstep;
;             const char* a3 = a2 + kstep; const char* b3 = b2 + kstep;
;             if (last && has_next) S.a_ready(nxt);
;             if constexpr (SP2) {
;             PG8_LDB(B0, 0, 0); PG8_LDB(B1, 0, 1); PG8_SCHED; PG8_LDA(At, 0, 0); PG8_STAGEA(PG8_SA(1, 1), a1 + hstep, voffA);
;             PG8_WAIT_V(8); PG8_WAIT_L(0); PG8_BAR; PG8_MMA(0, 0, At, B0); PG8_MMA(0, 1, At, B1); PG8_BAR; PG8_SCHED;
;             PG8_LDA(At, 0, 1); PG8_STAGEB(PG8_SB(0, 0), b2, voffB); PG8_STAGEB(PG8_SB(0, 1), b2 + hstep, voffB); PG8_STAGEA(PG8_SA(0, 0), a2, voffA);
;             PG8_WAIT_V(8); PG8_WAIT_L(0); PG8_BAR; PG8_MMA(1, 0, At, B0); PG8_MMA(1, 1, At, B1); PG8_BAR; PG8_SCHED;
.LBB0_1090:
	ds_read_b128 v[154:157], v150
	ds_read_b128 v[158:161], v150 offset:1024
	ds_read_b128 v[162:165], v150 offset:2048
	ds_read_b128 v[166:169], v150 offset:3072
	ds_read_b128 v[170:173], v151
	ds_read_b128 v[174:177], v151 offset:1024
	ds_read_b128 v[178:181], v151 offset:2048
	ds_read_b128 v[182:185], v151 offset:3072
	ds_read_b128 v[186:189], v152
	ds_read_b128 v[190:193], v152 offset:1024
	ds_read_b128 v[194:197], v152 offset:2048
	ds_read_b128 v[198:201], v152 offset:3072
	ds_read_b128 v[202:205], v152 offset:4096
	ds_read_b128 v[206:209], v152 offset:5120
	ds_read_b128 v[210:213], v152 offset:6144
	ds_read_b128 v[214:217], v152 offset:7168
	s_add_i32 s75, s54, 2
	s_cmpk_gt_u32 s75, 0x55
	s_cselect_b64 s[56:57], -1, 0
	s_and_b64 vcc, s[56:57], exec
	s_cselect_b32 s56, s24, s50
	s_cselect_b32 s28, s9, s49
	s_cselect_b32 s29, s8, s48
	s_cselect_b32 s55, s25, s51
	s_add_u32 s56, s56, s52
	s_addc_u32 s55, s55, s53
	s_add_u32 s56, s56, 0xffea0080
	s_addc_u32 s55, s55, -1
	s_add_u32 s29, s29, s52
	s_addc_u32 s28, s28, s53
	s_add_u32 s29, s29, 0xffea0080
	s_addc_u32 s28, s28, -1
	s_cmpk_eq_i32 s54, 0x54
	s_cselect_b32 s54, s46, s29
	s_cselect_b32 s57, s5, s55
	s_cselect_b32 s56, s4, s56
	s_cselect_b32 s55, s47, s28
	v_lshl_add_u64 v[146:147], v[142:143], 0, s[52:53]
	s_add_i32 m0, s23, 0xc000
	global_load_lds_dwordx4 v[146:147], off
	v_lshl_add_u64 v[146:147], v[144:145], 0, s[52:53]
	s_add_i32 m0, s23, 0xe000
	s_nop 0
	global_load_lds_dwordx4 v[146:147], off
	s_waitcnt vmcnt(8)
	s_waitcnt lgkmcnt(0)
	s_barrier
	s_setprio 1
	s_waitcnt lgkmcnt(0)
	v_mfma_f32_16x16x32_bf16 v[126:129], v[154:157], v[186:189], v[126:129]
	v_mfma_f32_16x16x32_bf16 v[122:125], v[162:165], v[186:189], v[122:125]
	v_mfma_f32_16x16x32_bf16 v[114:117], v[154:157], v[194:197], v[114:117]
	v_mfma_f32_16x16x32_bf16 v[106:109], v[162:165], v[194:197], v[106:109]
	v_mfma_f32_16x16x32_bf16 v[94:97], v[154:157], v[202:205], v[94:97]
	v_mfma_f32_16x16x32_bf16 v[90:93], v[162:165], v[202:205], v[90:93]
	v_mfma_f32_16x16x32_bf16 v[78:81], v[154:157], v[210:213], v[78:81]
	v_mfma_f32_16x16x32_bf16 v[74:77], v[162:165], v[210:213], v[74:77]
	v_mfma_f32_16x16x32_bf16 v[126:129], v[158:161], v[190:193], v[126:129]
	v_mfma_f32_16x16x32_bf16 v[122:125], v[166:169], v[190:193], v[122:125]
	v_mfma_f32_16x16x32_bf16 v[114:117], v[158:161], v[198:201], v[114:117]
	v_mfma_f32_16x16x32_bf16 v[106:109], v[166:169], v[198:201], v[106:109]
	v_mfma_f32_16x16x32_bf16 v[94:97], v[158:161], v[206:209], v[94:97]
	v_mfma_f32_16x16x32_bf16 v[90:93], v[166:169], v[206:209], v[90:93]
	v_mfma_f32_16x16x32_bf16 v[78:81], v[158:161], v[214:217], v[78:81]
	v_mfma_f32_16x16x32_bf16 v[74:77], v[166:169], v[214:217], v[74:77]
	s_setprio 0
	s_setprio 1
	v_mfma_f32_16x16x32_bf16 v[118:121], v[170:173], v[186:189], v[118:121]
	v_mfma_f32_16x16x32_bf16 v[110:113], v[178:181], v[186:189], v[110:113]
	v_mfma_f32_16x16x32_bf16 v[102:105], v[170:173], v[194:197], v[102:105]
	v_mfma_f32_16x16x32_bf16 v[98:101], v[178:181], v[194:197], v[98:101]
	v_mfma_f32_16x16x32_bf16 v[86:89], v[170:173], v[202:205], v[86:89]
	v_mfma_f32_16x16x32_bf16 v[82:85], v[178:181], v[202:205], v[82:85]
	v_mfma_f32_16x16x32_bf16 v[70:73], v[170:173], v[210:213], v[70:73]
	v_mfma_f32_16x16x32_bf16 v[66:69], v[178:181], v[210:213], v[66:69]
	v_mfma_f32_16x16x32_bf16 v[118:121], v[174:177], v[190:193], v[118:121]
	v_mfma_f32_16x16x32_bf16 v[110:113], v[182:185], v[190:193], v[110:113]
	v_mfma_f32_16x16x32_bf16 v[102:105], v[174:177], v[198:201], v[102:105]
	v_mfma_f32_16x16x32_bf16 v[98:101], v[182:185], v[198:201], v[98:101]
	v_mfma_f32_16x16x32_bf16 v[86:89], v[174:177], v[206:209], v[86:89]
	v_mfma_f32_16x16x32_bf16 v[82:85], v[182:185], v[206:209], v[82:85]
	v_mfma_f32_16x16x32_bf16 v[70:73], v[174:177], v[214:217], v[70:73]
	v_mfma_f32_16x16x32_bf16 v[66:69], v[182:185], v[214:217], v[66:69]
	s_setprio 0
	s_barrier
	s_add_i32 s28, s65, s21
	v_lshl_add_u64 v[146:147], s[54:55], 0, v[130:131]
	s_mov_b32 m0, s28
	ds_read_b128 v[186:189], v152 offset:16384
	ds_read_b128 v[190:193], v152 offset:17408
	ds_read_b128 v[194:197], v152 offset:18432
	ds_read_b128 v[198:201], v152 offset:19456
	ds_read_b128 v[202:205], v152 offset:20480
	ds_read_b128 v[206:209], v152 offset:21504
	ds_read_b128 v[210:213], v152 offset:22528
	ds_read_b128 v[214:217], v152 offset:23552
	global_load_lds_dwordx4 v[146:147], off
	s_add_i32 m0, s28, 0x2000
	s_add_u32 s76, s54, 0x160000
	v_lshl_add_u64 v[218:219], s[54:55], 0, v[132:133]
	s_addc_u32 s77, s55, 0
	s_add_i32 s28, s66, s21
	global_load_lds_dwordx4 v[218:219], off
	v_lshl_add_u64 v[220:221], s[76:77], 0, v[130:131]
	s_mov_b32 m0, s28
	v_lshl_add_u64 v[222:223], s[56:57], 0, v[132:133]
	global_load_lds_dwordx4 v[220:221], off
	v_lshl_add_u64 v[220:221], s[76:77], 0, v[132:133]
	s_add_i32 m0, s28, 0x2000
	s_nop 0
	global_load_lds_dwordx4 v[220:221], off
	v_lshl_add_u64 v[220:221], s[56:57], 0, v[130:131]
	s_mov_b32 m0, s23
	s_nop 0
	global_load_lds_dwordx4 v[220:221], off
	s_mov_b32 m0, s33
	s_nop 0
	global_load_lds_dwordx4 v[222:223], off
	s_waitcnt vmcnt(8)
	s_waitcnt lgkmcnt(0)
	s_barrier
; #define PG8_STAGEA(bufoff, gbase, voff) PG8_STAGE_X(bufoff, gbase, voff, PG8_AUX_A)
; #define PG8_LDA(dst, b, h) do { _Pragma("unroll") for (int m = 0; m < 4; ++m) _Pragma("unroll") for (int k = 0; k < 2; ++k) dst[m][k] = *(const PG8_LAS bf16x8*)(lds + PG8_SA(b, h) + aoff + m * 2048 + k * 1024); } while (0)
; #define PG8_LDB(dst, b, h) do { _Pragma("unroll") for (int n = 0; n < 2; ++n) _Pragma("unroll") for (int k = 0; k < 2; ++k) dst[n][k] = *(const PG8_LAS bf16x8*)(lds + PG8_SB(b, h) + boff + n * 2048 + k * 1024); } while (0)
; #define PG8_MMA(ai, bj, At, Bt) do { __builtin_amdgcn_s_setprio(1); _Pragma("unroll") for (int m = 0; m < 4; ++m) _Pragma("unroll") for (int n = 0; n < 2; ++n) _Pragma("unroll") for (int k = 0; k < 2; ++k) \
;         acc[ai][bj][m][n] = __builtin_amdgcn_mfma_f32_16x16x32_bf16(Bt[n][k], At[m][k], acc[ai][bj][m][n], 0, 0, 0); __builtin_amdgcn_s_setprio(0); } while (0)
; #define PG8_WAIT_V(n) asm volatile("s_waitcnt vmcnt(" #n ")" ::: "memory")
; #define PG8_WAIT_L(n) asm volatile("s_waitcnt lgkmcnt(" #n ")" ::: "memory")
; #define PG8_BAR __builtin_amdgcn_s_barrier()
; #define PG8_SCHED __builtin_amdgcn_sched_barrier(0)
; template <class Epi, class Sched, bool ALIGN_EPI = false, bool SP2 = false>
; __device__ __forceinline__ void gemm_phase(PG8_LAS unsigned char* lds, const Gemm g, const Sched& S, const Epi& E) {
;     ...
;             PG8_WAIT_V(8); PG8_WAIT_L(0); PG8_BAR; PG8_MMA(1, 0, At, B0); PG8_MMA(1, 1, At, B1); PG8_BAR; PG8_SCHED;
;             PG8_LDB(B0, 1, 0); PG8_LDB(B1, 1, 1); PG8_SCHED; PG8_LDA(At, 1, 0); PG8_STAGEA(PG8_SA(0, 1), a2 + hstep, voffA);
;             PG8_WAIT_V(8); PG8_WAIT_L(0); PG8_BAR; PG8_MMA(0, 0, At, B0); PG8_MMA(0, 1, At, B1); PG8_BAR; PG8_SCHED;
	s_setprio 1
	s_waitcnt lgkmcnt(0)
	v_mfma_f32_16x16x32_bf16 v[62:65], v[154:157], v[186:189], v[62:65]
	v_mfma_f32_16x16x32_bf16 v[58:61], v[162:165], v[186:189], v[58:61]
	v_mfma_f32_16x16x32_bf16 v[46:49], v[154:157], v[194:197], v[46:49]
	v_mfma_f32_16x16x32_bf16 v[42:45], v[162:165], v[194:197], v[42:45]
	v_mfma_f32_16x16x32_bf16 v[30:33], v[154:157], v[202:205], v[30:33]
	v_mfma_f32_16x16x32_bf16 v[26:29], v[162:165], v[202:205], v[26:29]
	v_mfma_f32_16x16x32_bf16 v[14:17], v[154:157], v[210:213], v[14:17]
	v_mfma_f32_16x16x32_bf16 v[10:13], v[162:165], v[210:213], v[10:13]
	v_mfma_f32_16x16x32_bf16 v[62:65], v[158:161], v[190:193], v[62:65]
	v_mfma_f32_16x16x32_bf16 v[58:61], v[166:169], v[190:193], v[58:61]
	v_mfma_f32_16x16x32_bf16 v[46:49], v[158:161], v[198:201], v[46:49]
	v_mfma_f32_16x16x32_bf16 v[42:45], v[166:169], v[198:201], v[42:45]
	v_mfma_f32_16x16x32_bf16 v[30:33], v[158:161], v[206:209], v[30:33]
	v_mfma_f32_16x16x32_bf16 v[26:29], v[166:169], v[206:209], v[26:29]
	v_mfma_f32_16x16x32_bf16 v[14:17], v[158:161], v[214:217], v[14:17]
	v_mfma_f32_16x16x32_bf16 v[10:13], v[166:169], v[214:217], v[10:13]
	s_setprio 0
	s_setprio 1
	v_mfma_f32_16x16x32_bf16 v[54:57], v[170:173], v[186:189], v[54:57]
	v_mfma_f32_16x16x32_bf16 v[50:53], v[178:181], v[186:189], v[50:53]
	v_mfma_f32_16x16x32_bf16 v[38:41], v[170:173], v[194:197], v[38:41]
	v_mfma_f32_16x16x32_bf16 v[34:37], v[178:181], v[194:197], v[34:37]
	v_mfma_f32_16x16x32_bf16 v[22:25], v[170:173], v[202:205], v[22:25]
	v_mfma_f32_16x16x32_bf16 v[18:21], v[178:181], v[202:205], v[18:21]
	v_mfma_f32_16x16x32_bf16 v[6:9], v[170:173], v[210:213], v[6:9]
	v_mfma_f32_16x16x32_bf16 v[2:5], v[178:181], v[210:213], v[2:5]
	v_mfma_f32_16x16x32_bf16 v[54:57], v[174:177], v[190:193], v[54:57]
	v_mfma_f32_16x16x32_bf16 v[50:53], v[182:185], v[190:193], v[50:53]
	v_mfma_f32_16x16x32_bf16 v[38:41], v[174:177], v[198:201], v[38:41]
	v_mfma_f32_16x16x32_bf16 v[34:37], v[182:185], v[198:201], v[34:37]
	v_mfma_f32_16x16x32_bf16 v[22:25], v[174:177], v[206:209], v[22:25]
	v_mfma_f32_16x16x32_bf16 v[18:21], v[182:185], v[206:209], v[18:21]
	v_mfma_f32_16x16x32_bf16 v[6:9], v[174:177], v[214:217], v[6:9]
	v_mfma_f32_16x16x32_bf16 v[2:5], v[182:185], v[214:217], v[2:5]
	s_setprio 0
	s_barrier
	s_add_i32 s28, 0, 0x18000
	v_add_u32_e32 v153, s28, v148
	s_add_i32 s29, 0, 0x1c000
	ds_read_b128 v[154:157], v153
	ds_read_b128 v[158:161], v153 offset:1024
	ds_read_b128 v[162:165], v153 offset:2048
	ds_read_b128 v[166:169], v153 offset:3072
	v_add_u32_e32 v153, s29, v148
	ds_read_b128 v[170:173], v153
	ds_read_b128 v[174:177], v153 offset:1024
	ds_read_b128 v[178:181], v153 offset:2048
	ds_read_b128 v[182:185], v153 offset:3072
	s_add_u32 s56, s56, 0x160000
	s_addc_u32 s57, s57, 0
	s_mov_b32 m0, s58
	v_lshl_add_u64 v[224:225], s[56:57], 0, v[130:131]
	ds_read_b128 v[186:189], v152 offset:32768
	ds_read_b128 v[190:193], v152 offset:33792
	ds_read_b128 v[194:197], v152 offset:34816
	ds_read_b128 v[198:201], v152 offset:35840
	ds_read_b128 v[202:205], v152 offset:36864
	ds_read_b128 v[206:209], v152 offset:37888
	ds_read_b128 v[210:213], v152 offset:38912
	ds_read_b128 v[214:217], v152 offset:39936
	global_load_lds_dwordx4 v[224:225], off
	v_lshl_add_u64 v[224:225], s[56:57], 0, v[132:133]
	s_mov_b32 m0, s59
	s_nop 0
	global_load_lds_dwordx4 v[224:225], off
	s_waitcnt vmcnt(8)
	s_waitcnt lgkmcnt(0)
	s_barrier
	s_setprio 1
	s_waitcnt lgkmcnt(0)
	v_mfma_f32_16x16x32_bf16 v[126:129], v[154:157], v[186:189], v[126:129]
	v_mfma_f32_16x16x32_bf16 v[122:125], v[162:165], v[186:189], v[122:125]
	v_mfma_f32_16x16x32_bf16 v[114:117], v[154:157], v[194:197], v[114:117]
	v_mfma_f32_16x16x32_bf16 v[106:109], v[162:165], v[194:197], v[106:109]
	v_mfma_f32_16x16x32_bf16 v[94:97], v[154:157], v[202:205], v[94:97]
	v_mfma_f32_16x16x32_bf16 v[90:93], v[162:165], v[202:205], v[90:93]
	v_mfma_f32_16x16x32_bf16 v[78:81], v[154:157], v[210:213], v[78:81]
	v_mfma_f32_16x16x32_bf16 v[74:77], v[162:165], v[210:213], v[74:77]
	v_mfma_f32_16x16x32_bf16 v[126:129], v[158:161], v[190:193], v[126:129]
	v_mfma_f32_16x16x32_bf16 v[122:125], v[166:169], v[190:193], v[122:125]
	v_mfma_f32_16x16x32_bf16 v[114:117], v[158:161], v[198:201], v[114:117]
	v_mfma_f32_16x16x32_bf16 v[106:109], v[166:169], v[198:201], v[106:109]
	v_mfma_f32_16x16x32_bf16 v[94:97], v[158:161], v[206:209], v[94:97]
	v_mfma_f32_16x16x32_bf16 v[90:93], v[166:169], v[206:209], v[90:93]
	v_mfma_f32_16x16x32_bf16 v[78:81], v[158:161], v[214:217], v[78:81]
	v_mfma_f32_16x16x32_bf16 v[74:77], v[166:169], v[214:217], v[74:77]
	s_setprio 0
	s_setprio 1
	v_mfma_f32_16x16x32_bf16 v[118:121], v[170:173], v[186:189], v[118:121]
	v_mfma_f32_16x16x32_bf16 v[110:113], v[178:181], v[186:189], v[110:113]
	v_mfma_f32_16x16x32_bf16 v[102:105], v[170:173], v[194:197], v[102:105]
	v_mfma_f32_16x16x32_bf16 v[98:101], v[178:181], v[194:197], v[98:101]
	v_mfma_f32_16x16x32_bf16 v[86:89], v[170:173], v[202:205], v[86:89]
	v_mfma_f32_16x16x32_bf16 v[82:85], v[178:181], v[202:205], v[82:85]
	v_mfma_f32_16x16x32_bf16 v[70:73], v[170:173], v[210:213], v[70:73]
	v_mfma_f32_16x16x32_bf16 v[66:69], v[178:181], v[210:213], v[66:69]
	v_mfma_f32_16x16x32_bf16 v[118:121], v[174:177], v[190:193], v[118:121]
	v_mfma_f32_16x16x32_bf16 v[110:113], v[182:185], v[190:193], v[110:113]
	v_mfma_f32_16x16x32_bf16 v[102:105], v[174:177], v[198:201], v[102:105]
	v_mfma_f32_16x16x32_bf16 v[98:101], v[182:185], v[198:201], v[98:101]
	v_mfma_f32_16x16x32_bf16 v[86:89], v[174:177], v[206:209], v[86:89]
	v_mfma_f32_16x16x32_bf16 v[82:85], v[182:185], v[206:209], v[82:85]
	v_mfma_f32_16x16x32_bf16 v[70:73], v[174:177], v[214:217], v[70:73]
	v_mfma_f32_16x16x32_bf16 v[66:69], v[182:185], v[214:217], v[66:69]
	s_setprio 0
	s_barrier
; #define PG8_STAGEA(bufoff, gbase, voff) PG8_STAGE_X(bufoff, gbase, voff, PG8_AUX_A)
; #define PG8_STAGEB(bufoff, gbase, voff) PG8_STAGE_X(bufoff, gbase, voff, PG8_AUX_B)
; #define PG8_LDA(dst, b, h) do { _Pragma("unroll") for (int m = 0; m < 4; ++m) _Pragma("unroll") for (int k = 0; k < 2; ++k) dst[m][k] = *(const PG8_LAS bf16x8*)(lds + PG8_SA(b, h) + aoff + m * 2048 + k * 1024); } while (0)
; #define PG8_MMA(ai, bj, At, Bt) do { __builtin_amdgcn_s_setprio(1); _Pragma("unroll") for (int m = 0; m < 4; ++m) _Pragma("unroll") for (int n = 0; n < 2; ++n) _Pragma("unroll") for (int k = 0; k < 2; ++k) \
;         acc[ai][bj][m][n] = __builtin_amdgcn_mfma_f32_16x16x32_bf16(Bt[n][k], At[m][k], acc[ai][bj][m][n], 0, 0, 0); __builtin_amdgcn_s_setprio(0); } while (0)
; #define PG8_WAIT_V(n) asm volatile("s_waitcnt vmcnt(" #n ")" ::: "memory")
; #define PG8_WAIT_L(n) asm volatile("s_waitcnt lgkmcnt(" #n ")" ::: "memory")
; #define PG8_BAR __builtin_amdgcn_s_barrier()
; #define PG8_SCHED __builtin_amdgcn_sched_barrier(0)
; template <class Epi, class Sched, bool ALIGN_EPI = false, bool SP2 = false>
; __device__ __forceinline__ void gemm_phase(PG8_LAS unsigned char* lds, const Gemm g, const Sched& S, const Epi& E) {
;     ...
;             PG8_LDA(At, 1, 1); PG8_STAGEB(PG8_SB(1, 0), b3, voffB); PG8_STAGEB(PG8_SB(1, 1), b3 + hstep, voffB); PG8_STAGEA(PG8_SA(1, 0), a3, voffA);
;             PG8_WAIT_V(8); PG8_WAIT_L(0); PG8_BAR; PG8_MMA(1, 0, At, B0); PG8_MMA(1, 1, At, B1); PG8_BAR; PG8_SCHED;
;     ...
;         if constexpr (ALIGN_EPI) { if (wr == 0) PG8_BAR; }
	s_add_i32 s28, s28, s21
	v_lshl_add_u64 v[146:147], v[146:147], 0, s[34:35]
	s_mov_b32 m0, s28
	ds_read_b128 v[186:189], v152 offset:49152
	ds_read_b128 v[190:193], v152 offset:50176
	ds_read_b128 v[194:197], v152 offset:51200
	ds_read_b128 v[198:201], v152 offset:52224
	ds_read_b128 v[202:205], v152 offset:53248
	ds_read_b128 v[206:209], v152 offset:54272
	ds_read_b128 v[210:213], v152 offset:55296
	ds_read_b128 v[214:217], v152 offset:56320
	global_load_lds_dwordx4 v[146:147], off
	s_add_i32 m0, s28, 0x2000
	s_add_u32 s54, s54, 0x160080
	v_lshl_add_u64 v[146:147], v[218:219], 0, s[34:35]
	s_addc_u32 s55, s55, 0
	s_add_i32 s28, s29, s21
	global_load_lds_dwordx4 v[146:147], off
	v_lshl_add_u64 v[146:147], s[54:55], 0, v[130:131]
	s_mov_b32 m0, s28
	s_nop 0
	global_load_lds_dwordx4 v[146:147], off
	v_lshl_add_u64 v[146:147], s[54:55], 0, v[132:133]
	s_add_i32 m0, s28, 0x2000
	s_nop 0
	global_load_lds_dwordx4 v[146:147], off
	v_lshl_add_u64 v[146:147], v[220:221], 0, s[34:35]
	s_mov_b32 m0, s61
	s_nop 0
	global_load_lds_dwordx4 v[146:147], off
	v_lshl_add_u64 v[146:147], v[222:223], 0, s[34:35]
	s_mov_b32 m0, s62
	s_nop 0
	global_load_lds_dwordx4 v[146:147], off
	s_waitcnt vmcnt(8)
	s_waitcnt lgkmcnt(0)
	s_barrier
	s_setprio 1
	s_waitcnt lgkmcnt(0)
	v_mfma_f32_16x16x32_bf16 v[62:65], v[154:157], v[186:189], v[62:65]
	v_mfma_f32_16x16x32_bf16 v[58:61], v[162:165], v[186:189], v[58:61]
	v_mfma_f32_16x16x32_bf16 v[46:49], v[154:157], v[194:197], v[46:49]
	v_mfma_f32_16x16x32_bf16 v[42:45], v[162:165], v[194:197], v[42:45]
	v_mfma_f32_16x16x32_bf16 v[30:33], v[154:157], v[202:205], v[30:33]
	v_mfma_f32_16x16x32_bf16 v[26:29], v[162:165], v[202:205], v[26:29]
	v_mfma_f32_16x16x32_bf16 v[14:17], v[154:157], v[210:213], v[14:17]
	v_mfma_f32_16x16x32_bf16 v[10:13], v[162:165], v[210:213], v[10:13]
	v_mfma_f32_16x16x32_bf16 v[62:65], v[158:161], v[190:193], v[62:65]
	v_mfma_f32_16x16x32_bf16 v[58:61], v[166:169], v[190:193], v[58:61]
	v_mfma_f32_16x16x32_bf16 v[46:49], v[158:161], v[198:201], v[46:49]
	v_mfma_f32_16x16x32_bf16 v[42:45], v[166:169], v[198:201], v[42:45]
	v_mfma_f32_16x16x32_bf16 v[30:33], v[158:161], v[206:209], v[30:33]
	v_mfma_f32_16x16x32_bf16 v[26:29], v[166:169], v[206:209], v[26:29]
	v_mfma_f32_16x16x32_bf16 v[14:17], v[158:161], v[214:217], v[14:17]
	v_mfma_f32_16x16x32_bf16 v[10:13], v[166:169], v[214:217], v[10:13]
	s_setprio 0
	s_setprio 1
	v_mfma_f32_16x16x32_bf16 v[54:57], v[170:173], v[186:189], v[54:57]
	v_mfma_f32_16x16x32_bf16 v[50:53], v[178:181], v[186:189], v[50:53]
	v_mfma_f32_16x16x32_bf16 v[38:41], v[170:173], v[194:197], v[38:41]
	v_mfma_f32_16x16x32_bf16 v[34:37], v[178:181], v[194:197], v[34:37]
	v_mfma_f32_16x16x32_bf16 v[22:25], v[170:173], v[202:205], v[22:25]
	v_mfma_f32_16x16x32_bf16 v[18:21], v[178:181], v[202:205], v[18:21]
	v_mfma_f32_16x16x32_bf16 v[6:9], v[170:173], v[210:213], v[6:9]
	v_mfma_f32_16x16x32_bf16 v[2:5], v[178:181], v[210:213], v[2:5]
	v_mfma_f32_16x16x32_bf16 v[54:57], v[174:177], v[190:193], v[54:57]
	v_mfma_f32_16x16x32_bf16 v[50:53], v[182:185], v[190:193], v[50:53]
	v_mfma_f32_16x16x32_bf16 v[38:41], v[174:177], v[198:201], v[38:41]
	v_mfma_f32_16x16x32_bf16 v[34:37], v[182:185], v[198:201], v[34:37]
	v_mfma_f32_16x16x32_bf16 v[22:25], v[174:177], v[206:209], v[22:25]
	v_mfma_f32_16x16x32_bf16 v[18:21], v[182:185], v[206:209], v[18:21]
	v_mfma_f32_16x16x32_bf16 v[6:9], v[174:177], v[214:217], v[6:9]
	v_mfma_f32_16x16x32_bf16 v[2:5], v[182:185], v[214:217], v[2:5]
	s_setprio 0
	s_barrier
	s_add_u32 s52, s52, 0x100
	s_addc_u32 s53, s53, 0
	s_mov_b32 s54, s75
	s_cbranch_vccz .LBB0_1090
	s_and_b64 vcc, exec, s[36:37]
	s_cbranch_vccz .LBB0_1093
	s_barrier
